# v12 + open barrier before the first MFMA of each segment (first k0,k1 chain not split by the barrier)
# speedup vs baseline: 1.0114x; 1.0034x over previous
.LBB0_642:
	ds_read_b128 v[148:151], v139
	ds_read_b128 v[152:155], v139 offset:1024
	ds_read_b128 v[156:159], v139 offset:2048
	ds_read_b128 v[160:163], v139 offset:3072
	ds_read_b128 v[164:167], v140
	ds_read_b128 v[168:171], v140 offset:1024
	ds_read_b128 v[172:175], v140 offset:2048
	ds_read_b128 v[176:179], v140 offset:3072
	s_add_i32 s18, s71, 0xffe80080
	s_cmp_eq_u32 s58, s73
	s_cselect_b32 s74, s69, s18
	s_cselect_b32 s76, s70, s72
	s_or_b32 s75, s74, 0x80
	s_add_i32 s18, s71, 0xfff80000
	s_mov_b32 m0, s59
	ds_read_b128 v[180:183], v141
	ds_read_b128 v[184:187], v141 offset:1024
	ds_read_b128 v[188:191], v141 offset:2048
	ds_read_b128 v[192:195], v141 offset:3072
	ds_read_b128 v[196:199], v141 offset:4096
	ds_read_b128 v[200:203], v141 offset:5120
	ds_read_b128 v[204:207], v141 offset:6144
	ds_read_b128 v[208:211], v141 offset:7168
	buffer_load_dwordx4 v137, s[12:15], s18 offen lds
	s_mov_b32 m0, s60
	s_nop 0
	buffer_load_dwordx4 v137, s[12:15], s71 offen lds
	s_waitcnt vmcnt(8)
	s_waitcnt lgkmcnt(0)
	s_setprio 1
	s_barrier
	v_mfma_f32_16x16x32_bf16 v[118:121], v[148:151], v[180:183], v[118:121]
	v_mfma_f32_16x16x32_bf16 v[118:121], v[152:155], v[184:187], v[118:121]
	v_mfma_f32_16x16x32_bf16 v[114:117], v[156:159], v[180:183], v[114:117]
	v_mfma_f32_16x16x32_bf16 v[114:117], v[160:163], v[184:187], v[114:117]
	v_mfma_f32_16x16x32_bf16 v[126:129], v[164:167], v[180:183], v[126:129]
	v_mfma_f32_16x16x32_bf16 v[126:129], v[168:171], v[184:187], v[126:129]
	v_mfma_f32_16x16x32_bf16 v[122:125], v[172:175], v[180:183], v[122:125]
	v_mfma_f32_16x16x32_bf16 v[122:125], v[176:179], v[184:187], v[122:125]
	v_mfma_f32_16x16x32_bf16 v[98:101], v[172:175], v[188:191], v[98:101]
	v_mfma_f32_16x16x32_bf16 v[98:101], v[176:179], v[192:195], v[98:101]
	v_mfma_f32_16x16x32_bf16 v[106:109], v[164:167], v[188:191], v[106:109]
	v_mfma_f32_16x16x32_bf16 v[106:109], v[168:171], v[192:195], v[106:109]
	v_mfma_f32_16x16x32_bf16 v[102:105], v[156:159], v[188:191], v[102:105]
	v_mfma_f32_16x16x32_bf16 v[102:105], v[160:163], v[192:195], v[102:105]
	v_mfma_f32_16x16x32_bf16 v[110:113], v[148:151], v[188:191], v[110:113]
	v_mfma_f32_16x16x32_bf16 v[110:113], v[152:155], v[192:195], v[110:113]
	v_mfma_f32_16x16x32_bf16 v[94:97], v[148:151], v[196:199], v[94:97]
	v_mfma_f32_16x16x32_bf16 v[94:97], v[152:155], v[200:203], v[94:97]
	v_mfma_f32_16x16x32_bf16 v[86:89], v[156:159], v[196:199], v[86:89]
	v_mfma_f32_16x16x32_bf16 v[86:89], v[160:163], v[200:203], v[86:89]
	v_mfma_f32_16x16x32_bf16 v[90:93], v[164:167], v[196:199], v[90:93]
	v_mfma_f32_16x16x32_bf16 v[90:93], v[168:171], v[200:203], v[90:93]
	v_mfma_f32_16x16x32_bf16 v[82:85], v[172:175], v[196:199], v[82:85]
	v_mfma_f32_16x16x32_bf16 v[82:85], v[176:179], v[200:203], v[82:85]
	v_mfma_f32_16x16x32_bf16 v[70:73], v[172:175], v[204:207], v[70:73]
	v_mfma_f32_16x16x32_bf16 v[70:73], v[176:179], v[208:211], v[70:73]
	v_mfma_f32_16x16x32_bf16 v[74:77], v[164:167], v[204:207], v[74:77]
	v_mfma_f32_16x16x32_bf16 v[74:77], v[168:171], v[208:211], v[74:77]
	v_mfma_f32_16x16x32_bf16 v[66:69], v[156:159], v[204:207], v[66:69]
	v_mfma_f32_16x16x32_bf16 v[66:69], v[160:163], v[208:211], v[66:69]
	v_mfma_f32_16x16x32_bf16 v[78:81], v[148:151], v[204:207], v[78:81]
	v_mfma_f32_16x16x32_bf16 v[78:81], v[152:155], v[208:211], v[78:81]
	s_setprio 0
	s_barrier
	s_mov_b32 m0, s30
	s_mov_b32 s18, s14
	s_mov_b32 s19, s15
	ds_read_b128 v[180:183], v141 offset:16384
	ds_read_b128 v[184:187], v141 offset:17408
	ds_read_b128 v[188:191], v141 offset:18432
	ds_read_b128 v[192:195], v141 offset:19456
	ds_read_b128 v[196:199], v141 offset:20480
	ds_read_b128 v[200:203], v141 offset:21504
	ds_read_b128 v[204:207], v141 offset:22528
	ds_read_b128 v[208:211], v141 offset:23552
	buffer_load_dwordx4 v138, s[16:19], s76 offen lds
	s_add_i32 s77, s76, 0x80000
	s_mov_b32 m0, s31
	s_nop 0
	buffer_load_dwordx4 v138, s[16:19], s77 offen lds
	s_add_i32 s77, s76, 0x100000
	s_mov_b32 m0, s44
	s_nop 0
	buffer_load_dwordx4 v138, s[16:19], s77 offen lds
	s_add_i32 s77, s76, 0x180000
	s_mov_b32 m0, s45
	s_nop 0
	buffer_load_dwordx4 v138, s[16:19], s77 offen lds
	s_mov_b32 m0, s27
	s_add_i32 s77, s74, 0x80000
	buffer_load_dwordx4 v137, s[12:15], s74 offen lds
	s_mov_b32 m0, s46
	s_nop 0
	buffer_load_dwordx4 v137, s[12:15], s77 offen lds
	s_waitcnt vmcnt(8)
	s_waitcnt lgkmcnt(0)
	s_setprio 1
	s_barrier
	v_mfma_f32_16x16x32_bf16 v[62:65], v[148:151], v[180:183], v[62:65]
	v_mfma_f32_16x16x32_bf16 v[62:65], v[152:155], v[184:187], v[62:65]
	v_mfma_f32_16x16x32_bf16 v[54:57], v[156:159], v[180:183], v[54:57]
	v_mfma_f32_16x16x32_bf16 v[54:57], v[160:163], v[184:187], v[54:57]
	v_mfma_f32_16x16x32_bf16 v[58:61], v[164:167], v[180:183], v[58:61]
	v_mfma_f32_16x16x32_bf16 v[58:61], v[168:171], v[184:187], v[58:61]
	v_mfma_f32_16x16x32_bf16 v[50:53], v[172:175], v[180:183], v[50:53]
	v_mfma_f32_16x16x32_bf16 v[50:53], v[176:179], v[184:187], v[50:53]
	v_mfma_f32_16x16x32_bf16 v[34:37], v[172:175], v[188:191], v[34:37]
	v_mfma_f32_16x16x32_bf16 v[34:37], v[176:179], v[192:195], v[34:37]
	v_mfma_f32_16x16x32_bf16 v[42:45], v[164:167], v[188:191], v[42:45]
	v_mfma_f32_16x16x32_bf16 v[42:45], v[168:171], v[192:195], v[42:45]
	v_mfma_f32_16x16x32_bf16 v[38:41], v[156:159], v[188:191], v[38:41]
	v_mfma_f32_16x16x32_bf16 v[38:41], v[160:163], v[192:195], v[38:41]
	v_mfma_f32_16x16x32_bf16 v[46:49], v[148:151], v[188:191], v[46:49]
	v_mfma_f32_16x16x32_bf16 v[46:49], v[152:155], v[192:195], v[46:49]
	v_mfma_f32_16x16x32_bf16 v[30:33], v[148:151], v[196:199], v[30:33]
	v_mfma_f32_16x16x32_bf16 v[30:33], v[152:155], v[200:203], v[30:33]
	v_mfma_f32_16x16x32_bf16 v[22:25], v[156:159], v[196:199], v[22:25]
	v_mfma_f32_16x16x32_bf16 v[22:25], v[160:163], v[200:203], v[22:25]
	v_mfma_f32_16x16x32_bf16 v[26:29], v[164:167], v[196:199], v[26:29]
	v_mfma_f32_16x16x32_bf16 v[26:29], v[168:171], v[200:203], v[26:29]
	v_mfma_f32_16x16x32_bf16 v[18:21], v[172:175], v[196:199], v[18:21]
	v_mfma_f32_16x16x32_bf16 v[18:21], v[176:179], v[200:203], v[18:21]
	v_mfma_f32_16x16x32_bf16 v[2:5], v[172:175], v[204:207], v[2:5]
	v_mfma_f32_16x16x32_bf16 v[2:5], v[176:179], v[208:211], v[2:5]
	v_mfma_f32_16x16x32_bf16 v[10:13], v[164:167], v[204:207], v[10:13]
	v_mfma_f32_16x16x32_bf16 v[10:13], v[168:171], v[208:211], v[10:13]
	v_mfma_f32_16x16x32_bf16 v[6:9], v[156:159], v[204:207], v[6:9]
	v_mfma_f32_16x16x32_bf16 v[6:9], v[160:163], v[208:211], v[6:9]
	v_mfma_f32_16x16x32_bf16 v[14:17], v[148:151], v[204:207], v[14:17]
	v_mfma_f32_16x16x32_bf16 v[14:17], v[152:155], v[208:211], v[14:17]
	s_setprio 0
	s_barrier
	ds_read_b128 v[148:151], v142
	ds_read_b128 v[152:155], v142 offset:1024
	ds_read_b128 v[156:159], v142 offset:2048
	ds_read_b128 v[160:163], v142 offset:3072
	ds_read_b128 v[164:167], v143
	ds_read_b128 v[168:171], v143 offset:1024
	ds_read_b128 v[172:175], v143 offset:2048
	ds_read_b128 v[176:179], v143 offset:3072
	s_mov_b32 m0, s47
	s_add_i32 s77, s74, 0x100000
	ds_read_b128 v[180:183], v141 offset:32768
	ds_read_b128 v[184:187], v141 offset:33792
	ds_read_b128 v[188:191], v141 offset:34816
	ds_read_b128 v[192:195], v141 offset:35840
	ds_read_b128 v[196:199], v141 offset:36864
	ds_read_b128 v[200:203], v141 offset:37888
	ds_read_b128 v[204:207], v141 offset:38912
	ds_read_b128 v[208:211], v141 offset:39936
	buffer_load_dwordx4 v137, s[12:15], s77 offen lds
	s_add_i32 s77, s74, 0x180000
	s_mov_b32 m0, s48
	s_nop 0
	buffer_load_dwordx4 v137, s[12:15], s77 offen lds
	s_waitcnt vmcnt(8)
	s_waitcnt lgkmcnt(0)
	s_setprio 1
	s_barrier
	v_mfma_f32_16x16x32_bf16 v[118:121], v[148:151], v[180:183], v[118:121]
	v_mfma_f32_16x16x32_bf16 v[118:121], v[152:155], v[184:187], v[118:121]
	v_mfma_f32_16x16x32_bf16 v[114:117], v[156:159], v[180:183], v[114:117]
	v_mfma_f32_16x16x32_bf16 v[114:117], v[160:163], v[184:187], v[114:117]
	v_mfma_f32_16x16x32_bf16 v[126:129], v[164:167], v[180:183], v[126:129]
	v_mfma_f32_16x16x32_bf16 v[126:129], v[168:171], v[184:187], v[126:129]
	v_mfma_f32_16x16x32_bf16 v[122:125], v[172:175], v[180:183], v[122:125]
	v_mfma_f32_16x16x32_bf16 v[122:125], v[176:179], v[184:187], v[122:125]
	v_mfma_f32_16x16x32_bf16 v[98:101], v[172:175], v[188:191], v[98:101]
	v_mfma_f32_16x16x32_bf16 v[98:101], v[176:179], v[192:195], v[98:101]
	v_mfma_f32_16x16x32_bf16 v[106:109], v[164:167], v[188:191], v[106:109]
	v_mfma_f32_16x16x32_bf16 v[106:109], v[168:171], v[192:195], v[106:109]
	v_mfma_f32_16x16x32_bf16 v[102:105], v[156:159], v[188:191], v[102:105]
	v_mfma_f32_16x16x32_bf16 v[102:105], v[160:163], v[192:195], v[102:105]
	v_mfma_f32_16x16x32_bf16 v[110:113], v[148:151], v[188:191], v[110:113]
	v_mfma_f32_16x16x32_bf16 v[110:113], v[152:155], v[192:195], v[110:113]
	v_mfma_f32_16x16x32_bf16 v[94:97], v[148:151], v[196:199], v[94:97]
	v_mfma_f32_16x16x32_bf16 v[94:97], v[152:155], v[200:203], v[94:97]
	v_mfma_f32_16x16x32_bf16 v[86:89], v[156:159], v[196:199], v[86:89]
	v_mfma_f32_16x16x32_bf16 v[86:89], v[160:163], v[200:203], v[86:89]
	v_mfma_f32_16x16x32_bf16 v[90:93], v[164:167], v[196:199], v[90:93]
	v_mfma_f32_16x16x32_bf16 v[90:93], v[168:171], v[200:203], v[90:93]
	v_mfma_f32_16x16x32_bf16 v[82:85], v[172:175], v[196:199], v[82:85]
	v_mfma_f32_16x16x32_bf16 v[82:85], v[176:179], v[200:203], v[82:85]
	v_mfma_f32_16x16x32_bf16 v[70:73], v[172:175], v[204:207], v[70:73]
	v_mfma_f32_16x16x32_bf16 v[70:73], v[176:179], v[208:211], v[70:73]
	v_mfma_f32_16x16x32_bf16 v[74:77], v[164:167], v[204:207], v[74:77]
	v_mfma_f32_16x16x32_bf16 v[74:77], v[168:171], v[208:211], v[74:77]
	v_mfma_f32_16x16x32_bf16 v[66:69], v[156:159], v[204:207], v[66:69]
	v_mfma_f32_16x16x32_bf16 v[66:69], v[160:163], v[208:211], v[66:69]
	v_mfma_f32_16x16x32_bf16 v[78:81], v[148:151], v[204:207], v[78:81]
	v_mfma_f32_16x16x32_bf16 v[78:81], v[152:155], v[208:211], v[78:81]
	s_setprio 0
	s_barrier
	s_mov_b32 m0, s50
	s_or_b32 s77, s76, 0x80
	ds_read_b128 v[180:183], v141 offset:49152
	ds_read_b128 v[184:187], v141 offset:50176
	ds_read_b128 v[188:191], v141 offset:51200
	ds_read_b128 v[192:195], v141 offset:52224
	ds_read_b128 v[196:199], v141 offset:53248
	ds_read_b128 v[200:203], v141 offset:54272
	ds_read_b128 v[204:207], v141 offset:55296
	ds_read_b128 v[208:211], v141 offset:56320
	buffer_load_dwordx4 v138, s[16:19], s77 offen lds
	s_add_i32 s77, s76, 0x80080
	s_mov_b32 m0, s51
	s_add_i32 s74, s74, 0x80080
	buffer_load_dwordx4 v138, s[16:19], s77 offen lds
	s_add_i32 s77, s76, 0x100080
	s_mov_b32 m0, s54
	s_add_i32 s76, s76, 0x180080
	buffer_load_dwordx4 v138, s[16:19], s77 offen lds
	s_mov_b32 m0, s55
	s_nop 0
	buffer_load_dwordx4 v138, s[16:19], s76 offen lds
	s_mov_b32 m0, s52
	s_nop 0
	buffer_load_dwordx4 v137, s[12:15], s75 offen lds
	s_mov_b32 m0, s53
	s_nop 0
	buffer_load_dwordx4 v137, s[12:15], s74 offen lds
	s_waitcnt vmcnt(8)
	s_waitcnt lgkmcnt(0)
	s_setprio 1
	s_barrier
	v_mfma_f32_16x16x32_bf16 v[62:65], v[148:151], v[180:183], v[62:65]
	v_mfma_f32_16x16x32_bf16 v[62:65], v[152:155], v[184:187], v[62:65]
	v_mfma_f32_16x16x32_bf16 v[54:57], v[156:159], v[180:183], v[54:57]
	v_mfma_f32_16x16x32_bf16 v[54:57], v[160:163], v[184:187], v[54:57]
	v_mfma_f32_16x16x32_bf16 v[58:61], v[164:167], v[180:183], v[58:61]
	v_mfma_f32_16x16x32_bf16 v[58:61], v[168:171], v[184:187], v[58:61]
	v_mfma_f32_16x16x32_bf16 v[50:53], v[172:175], v[180:183], v[50:53]
	v_mfma_f32_16x16x32_bf16 v[50:53], v[176:179], v[184:187], v[50:53]
	v_mfma_f32_16x16x32_bf16 v[34:37], v[172:175], v[188:191], v[34:37]
	v_mfma_f32_16x16x32_bf16 v[34:37], v[176:179], v[192:195], v[34:37]
	v_mfma_f32_16x16x32_bf16 v[42:45], v[164:167], v[188:191], v[42:45]
	v_mfma_f32_16x16x32_bf16 v[42:45], v[168:171], v[192:195], v[42:45]
	v_mfma_f32_16x16x32_bf16 v[38:41], v[156:159], v[188:191], v[38:41]
	v_mfma_f32_16x16x32_bf16 v[38:41], v[160:163], v[192:195], v[38:41]
	v_mfma_f32_16x16x32_bf16 v[46:49], v[148:151], v[188:191], v[46:49]
	v_mfma_f32_16x16x32_bf16 v[46:49], v[152:155], v[192:195], v[46:49]
	v_mfma_f32_16x16x32_bf16 v[30:33], v[148:151], v[196:199], v[30:33]
	v_mfma_f32_16x16x32_bf16 v[30:33], v[152:155], v[200:203], v[30:33]
	v_mfma_f32_16x16x32_bf16 v[22:25], v[156:159], v[196:199], v[22:25]
	v_mfma_f32_16x16x32_bf16 v[22:25], v[160:163], v[200:203], v[22:25]
	v_mfma_f32_16x16x32_bf16 v[26:29], v[164:167], v[196:199], v[26:29]
	v_mfma_f32_16x16x32_bf16 v[26:29], v[168:171], v[200:203], v[26:29]
	v_mfma_f32_16x16x32_bf16 v[18:21], v[172:175], v[196:199], v[18:21]
	v_mfma_f32_16x16x32_bf16 v[18:21], v[176:179], v[200:203], v[18:21]
	v_mfma_f32_16x16x32_bf16 v[2:5], v[172:175], v[204:207], v[2:5]
	v_mfma_f32_16x16x32_bf16 v[2:5], v[176:179], v[208:211], v[2:5]
	v_mfma_f32_16x16x32_bf16 v[10:13], v[164:167], v[204:207], v[10:13]
	v_mfma_f32_16x16x32_bf16 v[10:13], v[168:171], v[208:211], v[10:13]
	v_mfma_f32_16x16x32_bf16 v[6:9], v[156:159], v[204:207], v[6:9]
	v_mfma_f32_16x16x32_bf16 v[6:9], v[160:163], v[208:211], v[6:9]
	v_mfma_f32_16x16x32_bf16 v[14:17], v[148:151], v[204:207], v[14:17]
	v_mfma_f32_16x16x32_bf16 v[14:17], v[152:155], v[208:211], v[14:17]
	s_setprio 0
	s_barrier
	s_add_i32 s73, s73, 2
	s_addk_i32 s71, 0x100
	s_addk_i32 s72, 0x100
	s_cmp_ge_i32 s73, s3
	s_cbranch_scc0 .LBB0_642
	s_and_b64 vcc, exec, s[42:43]
	s_cbranch_vccz .LBB0_645

.LBB0_799:
	ds_read_b128 v[134:137], v210
	ds_read_b128 v[138:141], v210 offset:1024
	ds_read_b128 v[142:145], v210 offset:2048
	ds_read_b128 v[148:151], v210 offset:3072
	ds_read_b128 v[152:155], v211
	ds_read_b128 v[156:159], v211 offset:1024
	ds_read_b128 v[160:163], v211 offset:2048
	ds_read_b128 v[164:167], v211 offset:3072
	s_add_i32 s18, s77, 0xffbf8080
	s_cmp_eq_u32 s62, s79
	s_cselect_b32 s80, s6, s18
	s_cselect_b32 s82, s7, s78
	s_or_b32 s81, s80, 0x80
	s_add_i32 s18, s77, 0xffea8000
	s_mov_b32 m0, s63
	ds_read_b128 v[168:171], v212
	ds_read_b128 v[172:175], v212 offset:1024
	ds_read_b128 v[176:179], v212 offset:2048
	ds_read_b128 v[180:183], v212 offset:3072
	ds_read_b128 v[184:187], v212 offset:4096
	ds_read_b128 v[188:191], v212 offset:5120
	ds_read_b128 v[192:195], v212 offset:6144
	ds_read_b128 v[196:199], v212 offset:7168
	buffer_load_dwordx4 v208, s[12:15], s18 offen lds
	s_mov_b32 m0, s66
	s_nop 0
	buffer_load_dwordx4 v208, s[12:15], s77 offen lds
	s_waitcnt vmcnt(8)
	s_waitcnt lgkmcnt(0)
	s_setprio 1
	s_barrier
	v_mfma_f32_16x16x32_bf16 v[126:129], v[134:137], v[168:171], v[126:129]
	v_mfma_f32_16x16x32_bf16 v[126:129], v[138:141], v[172:175], v[126:129]
	v_mfma_f32_16x16x32_bf16 v[122:125], v[142:145], v[168:171], v[122:125]
	v_mfma_f32_16x16x32_bf16 v[122:125], v[148:151], v[172:175], v[122:125]
	v_mfma_f32_16x16x32_bf16 v[110:113], v[152:155], v[168:171], v[110:113]
	v_mfma_f32_16x16x32_bf16 v[110:113], v[156:159], v[172:175], v[110:113]
	v_mfma_f32_16x16x32_bf16 v[102:105], v[160:163], v[168:171], v[102:105]
	v_mfma_f32_16x16x32_bf16 v[102:105], v[164:167], v[172:175], v[102:105]
	v_mfma_f32_16x16x32_bf16 v[86:89], v[160:163], v[176:179], v[86:89]
	v_mfma_f32_16x16x32_bf16 v[86:89], v[164:167], v[180:183], v[86:89]
	v_mfma_f32_16x16x32_bf16 v[94:97], v[152:155], v[176:179], v[94:97]
	v_mfma_f32_16x16x32_bf16 v[94:97], v[156:159], v[180:183], v[94:97]
	v_mfma_f32_16x16x32_bf16 v[114:117], v[142:145], v[176:179], v[114:117]
	v_mfma_f32_16x16x32_bf16 v[114:117], v[148:151], v[180:183], v[114:117]
	v_mfma_f32_16x16x32_bf16 v[118:121], v[134:137], v[176:179], v[118:121]
	v_mfma_f32_16x16x32_bf16 v[118:121], v[138:141], v[180:183], v[118:121]
	v_mfma_f32_16x16x32_bf16 v[106:109], v[134:137], v[184:187], v[106:109]
	v_mfma_f32_16x16x32_bf16 v[106:109], v[138:141], v[188:191], v[106:109]
	v_mfma_f32_16x16x32_bf16 v[98:101], v[142:145], v[184:187], v[98:101]
	v_mfma_f32_16x16x32_bf16 v[98:101], v[148:151], v[188:191], v[98:101]
	v_mfma_f32_16x16x32_bf16 v[78:81], v[152:155], v[184:187], v[78:81]
	v_mfma_f32_16x16x32_bf16 v[78:81], v[156:159], v[188:191], v[78:81]
	v_mfma_f32_16x16x32_bf16 v[74:77], v[160:163], v[184:187], v[74:77]
	v_mfma_f32_16x16x32_bf16 v[74:77], v[164:167], v[188:191], v[74:77]
	v_mfma_f32_16x16x32_bf16 v[66:69], v[160:163], v[192:195], v[66:69]
	v_mfma_f32_16x16x32_bf16 v[66:69], v[164:167], v[196:199], v[66:69]
	v_mfma_f32_16x16x32_bf16 v[70:73], v[152:155], v[192:195], v[70:73]
	v_mfma_f32_16x16x32_bf16 v[70:73], v[156:159], v[196:199], v[70:73]
	v_mfma_f32_16x16x32_bf16 v[82:85], v[142:145], v[192:195], v[82:85]
	v_mfma_f32_16x16x32_bf16 v[82:85], v[148:151], v[196:199], v[82:85]
	v_mfma_f32_16x16x32_bf16 v[90:93], v[134:137], v[192:195], v[90:93]
	v_mfma_f32_16x16x32_bf16 v[90:93], v[138:141], v[196:199], v[90:93]
	s_setprio 0
	s_barrier
	s_mov_b32 m0, s25
	s_mov_b32 s18, s14
	s_mov_b32 s19, s15
	ds_read_b128 v[168:171], v212 offset:16384
	ds_read_b128 v[172:175], v212 offset:17408
	ds_read_b128 v[176:179], v212 offset:18432
	ds_read_b128 v[180:183], v212 offset:19456
	ds_read_b128 v[184:187], v212 offset:20480
	ds_read_b128 v[188:191], v212 offset:21504
	ds_read_b128 v[192:195], v212 offset:22528
	ds_read_b128 v[196:199], v212 offset:23552
	buffer_load_dwordx4 v209, s[16:19], s82 offen lds
	s_add_i32 s83, s82, 0x158000
	s_mov_b32 m0, s27
	s_nop 0
	buffer_load_dwordx4 v209, s[16:19], s83 offen lds
	s_add_i32 s83, s82, 0x2b0000
	s_mov_b32 m0, s30
	s_nop 0
	buffer_load_dwordx4 v209, s[16:19], s83 offen lds
	s_add_i32 s83, s82, 0x408000
	s_mov_b32 m0, s31
	s_nop 0
	buffer_load_dwordx4 v209, s[16:19], s83 offen lds
	s_mov_b32 m0, s21
	s_add_i32 s83, s80, 0x158000
	buffer_load_dwordx4 v208, s[12:15], s80 offen lds
	s_mov_b32 m0, s48
	s_nop 0
	buffer_load_dwordx4 v208, s[12:15], s83 offen lds
	s_waitcnt vmcnt(8)
	s_waitcnt lgkmcnt(0)
	s_setprio 1
	s_barrier
	v_mfma_f32_16x16x32_bf16 v[62:65], v[134:137], v[168:171], v[62:65]
	v_mfma_f32_16x16x32_bf16 v[62:65], v[138:141], v[172:175], v[62:65]
	v_mfma_f32_16x16x32_bf16 v[58:61], v[142:145], v[168:171], v[58:61]
	v_mfma_f32_16x16x32_bf16 v[58:61], v[148:151], v[172:175], v[58:61]
	v_mfma_f32_16x16x32_bf16 v[46:49], v[152:155], v[168:171], v[46:49]
	v_mfma_f32_16x16x32_bf16 v[46:49], v[156:159], v[172:175], v[46:49]
	v_mfma_f32_16x16x32_bf16 v[38:41], v[160:163], v[168:171], v[38:41]
	v_mfma_f32_16x16x32_bf16 v[38:41], v[164:167], v[172:175], v[38:41]
	v_mfma_f32_16x16x32_bf16 v[22:25], v[160:163], v[176:179], v[22:25]
	v_mfma_f32_16x16x32_bf16 v[22:25], v[164:167], v[180:183], v[22:25]
	v_mfma_f32_16x16x32_bf16 v[30:33], v[152:155], v[176:179], v[30:33]
	v_mfma_f32_16x16x32_bf16 v[30:33], v[156:159], v[180:183], v[30:33]
	v_mfma_f32_16x16x32_bf16 v[50:53], v[142:145], v[176:179], v[50:53]
	v_mfma_f32_16x16x32_bf16 v[50:53], v[148:151], v[180:183], v[50:53]
	v_mfma_f32_16x16x32_bf16 v[54:57], v[134:137], v[176:179], v[54:57]
	v_mfma_f32_16x16x32_bf16 v[54:57], v[138:141], v[180:183], v[54:57]
	v_mfma_f32_16x16x32_bf16 v[42:45], v[134:137], v[184:187], v[42:45]
	v_mfma_f32_16x16x32_bf16 v[42:45], v[138:141], v[188:191], v[42:45]
	v_mfma_f32_16x16x32_bf16 v[34:37], v[142:145], v[184:187], v[34:37]
	v_mfma_f32_16x16x32_bf16 v[34:37], v[148:151], v[188:191], v[34:37]
	v_mfma_f32_16x16x32_bf16 v[14:17], v[152:155], v[184:187], v[14:17]
	v_mfma_f32_16x16x32_bf16 v[14:17], v[156:159], v[188:191], v[14:17]
	v_mfma_f32_16x16x32_bf16 v[10:13], v[160:163], v[184:187], v[10:13]
	v_mfma_f32_16x16x32_bf16 v[10:13], v[164:167], v[188:191], v[10:13]
	v_mfma_f32_16x16x32_bf16 v[2:5], v[160:163], v[192:195], v[2:5]
	v_mfma_f32_16x16x32_bf16 v[2:5], v[164:167], v[196:199], v[2:5]
	v_mfma_f32_16x16x32_bf16 v[6:9], v[152:155], v[192:195], v[6:9]
	v_mfma_f32_16x16x32_bf16 v[6:9], v[156:159], v[196:199], v[6:9]
	v_mfma_f32_16x16x32_bf16 v[18:21], v[142:145], v[192:195], v[18:21]
	v_mfma_f32_16x16x32_bf16 v[18:21], v[148:151], v[196:199], v[18:21]
	v_mfma_f32_16x16x32_bf16 v[26:29], v[134:137], v[192:195], v[26:29]
	v_mfma_f32_16x16x32_bf16 v[26:29], v[138:141], v[196:199], v[26:29]
	s_setprio 0
	s_barrier
	ds_read_b128 v[134:137], v213
	ds_read_b128 v[138:141], v213 offset:1024
	ds_read_b128 v[142:145], v213 offset:2048
	ds_read_b128 v[148:151], v213 offset:3072
	ds_read_b128 v[152:155], v214
	ds_read_b128 v[156:159], v214 offset:1024
	ds_read_b128 v[160:163], v214 offset:2048
	ds_read_b128 v[164:167], v214 offset:3072
	s_mov_b32 m0, s49
	s_add_i32 s83, s80, 0x2b0000
	ds_read_b128 v[168:171], v212 offset:32768
	ds_read_b128 v[172:175], v212 offset:33792
	ds_read_b128 v[176:179], v212 offset:34816
	ds_read_b128 v[180:183], v212 offset:35840
	ds_read_b128 v[184:187], v212 offset:36864
	ds_read_b128 v[188:191], v212 offset:37888
	ds_read_b128 v[192:195], v212 offset:38912
	ds_read_b128 v[196:199], v212 offset:39936
	buffer_load_dwordx4 v208, s[12:15], s83 offen lds
	s_add_i32 s83, s80, 0x408000
	s_mov_b32 m0, s50
	s_nop 0
	buffer_load_dwordx4 v208, s[12:15], s83 offen lds
	s_waitcnt vmcnt(8)
	s_waitcnt lgkmcnt(0)
	s_setprio 1
	s_barrier
	v_mfma_f32_16x16x32_bf16 v[126:129], v[134:137], v[168:171], v[126:129]
	v_mfma_f32_16x16x32_bf16 v[126:129], v[138:141], v[172:175], v[126:129]
	v_mfma_f32_16x16x32_bf16 v[122:125], v[142:145], v[168:171], v[122:125]
	v_mfma_f32_16x16x32_bf16 v[122:125], v[148:151], v[172:175], v[122:125]
	v_mfma_f32_16x16x32_bf16 v[110:113], v[152:155], v[168:171], v[110:113]
	v_mfma_f32_16x16x32_bf16 v[110:113], v[156:159], v[172:175], v[110:113]
	v_mfma_f32_16x16x32_bf16 v[102:105], v[160:163], v[168:171], v[102:105]
	v_mfma_f32_16x16x32_bf16 v[102:105], v[164:167], v[172:175], v[102:105]
	v_mfma_f32_16x16x32_bf16 v[86:89], v[160:163], v[176:179], v[86:89]
	v_mfma_f32_16x16x32_bf16 v[86:89], v[164:167], v[180:183], v[86:89]
	v_mfma_f32_16x16x32_bf16 v[94:97], v[152:155], v[176:179], v[94:97]
	v_mfma_f32_16x16x32_bf16 v[94:97], v[156:159], v[180:183], v[94:97]
	v_mfma_f32_16x16x32_bf16 v[114:117], v[142:145], v[176:179], v[114:117]
	v_mfma_f32_16x16x32_bf16 v[114:117], v[148:151], v[180:183], v[114:117]
	v_mfma_f32_16x16x32_bf16 v[118:121], v[134:137], v[176:179], v[118:121]
	v_mfma_f32_16x16x32_bf16 v[118:121], v[138:141], v[180:183], v[118:121]
	v_mfma_f32_16x16x32_bf16 v[106:109], v[134:137], v[184:187], v[106:109]
	v_mfma_f32_16x16x32_bf16 v[106:109], v[138:141], v[188:191], v[106:109]
	v_mfma_f32_16x16x32_bf16 v[98:101], v[142:145], v[184:187], v[98:101]
	v_mfma_f32_16x16x32_bf16 v[98:101], v[148:151], v[188:191], v[98:101]
	v_mfma_f32_16x16x32_bf16 v[78:81], v[152:155], v[184:187], v[78:81]
	v_mfma_f32_16x16x32_bf16 v[78:81], v[156:159], v[188:191], v[78:81]
	v_mfma_f32_16x16x32_bf16 v[74:77], v[160:163], v[184:187], v[74:77]
	v_mfma_f32_16x16x32_bf16 v[74:77], v[164:167], v[188:191], v[74:77]
	v_mfma_f32_16x16x32_bf16 v[66:69], v[160:163], v[192:195], v[66:69]
	v_mfma_f32_16x16x32_bf16 v[66:69], v[164:167], v[196:199], v[66:69]
	v_mfma_f32_16x16x32_bf16 v[70:73], v[152:155], v[192:195], v[70:73]
	v_mfma_f32_16x16x32_bf16 v[70:73], v[156:159], v[196:199], v[70:73]
	v_mfma_f32_16x16x32_bf16 v[82:85], v[142:145], v[192:195], v[82:85]
	v_mfma_f32_16x16x32_bf16 v[82:85], v[148:151], v[196:199], v[82:85]
	v_mfma_f32_16x16x32_bf16 v[90:93], v[134:137], v[192:195], v[90:93]
	v_mfma_f32_16x16x32_bf16 v[90:93], v[138:141], v[196:199], v[90:93]
	s_setprio 0
	s_barrier
	s_mov_b32 m0, s54
	s_or_b32 s83, s82, 0x80
	ds_read_b128 v[168:171], v212 offset:49152
	ds_read_b128 v[172:175], v212 offset:50176
	ds_read_b128 v[176:179], v212 offset:51200
	ds_read_b128 v[180:183], v212 offset:52224
	ds_read_b128 v[184:187], v212 offset:53248
	ds_read_b128 v[188:191], v212 offset:54272
	ds_read_b128 v[192:195], v212 offset:55296
	ds_read_b128 v[196:199], v212 offset:56320
	buffer_load_dwordx4 v209, s[16:19], s83 offen lds
	s_add_i32 s83, s82, 0x158080
	s_mov_b32 m0, s55
	s_add_i32 s80, s80, 0x158080
	buffer_load_dwordx4 v209, s[16:19], s83 offen lds
	s_add_i32 s83, s82, 0x2b0080
	s_mov_b32 m0, s58
	s_add_i32 s82, s82, 0x408080
	buffer_load_dwordx4 v209, s[16:19], s83 offen lds
	s_mov_b32 m0, s59
	s_nop 0
	buffer_load_dwordx4 v209, s[16:19], s82 offen lds
	s_mov_b32 m0, s56
	s_nop 0
	buffer_load_dwordx4 v208, s[12:15], s81 offen lds
	s_mov_b32 m0, s57
	s_nop 0
	buffer_load_dwordx4 v208, s[12:15], s80 offen lds
	s_waitcnt vmcnt(8)
	s_waitcnt lgkmcnt(0)
	s_setprio 1
	s_barrier
	v_mfma_f32_16x16x32_bf16 v[62:65], v[134:137], v[168:171], v[62:65]
	v_mfma_f32_16x16x32_bf16 v[62:65], v[138:141], v[172:175], v[62:65]
	v_mfma_f32_16x16x32_bf16 v[58:61], v[142:145], v[168:171], v[58:61]
	v_mfma_f32_16x16x32_bf16 v[58:61], v[148:151], v[172:175], v[58:61]
	v_mfma_f32_16x16x32_bf16 v[46:49], v[152:155], v[168:171], v[46:49]
	v_mfma_f32_16x16x32_bf16 v[46:49], v[156:159], v[172:175], v[46:49]
	v_mfma_f32_16x16x32_bf16 v[38:41], v[160:163], v[168:171], v[38:41]
	v_mfma_f32_16x16x32_bf16 v[38:41], v[164:167], v[172:175], v[38:41]
	v_mfma_f32_16x16x32_bf16 v[22:25], v[160:163], v[176:179], v[22:25]
	v_mfma_f32_16x16x32_bf16 v[22:25], v[164:167], v[180:183], v[22:25]
	v_mfma_f32_16x16x32_bf16 v[30:33], v[152:155], v[176:179], v[30:33]
	v_mfma_f32_16x16x32_bf16 v[30:33], v[156:159], v[180:183], v[30:33]
	v_mfma_f32_16x16x32_bf16 v[50:53], v[142:145], v[176:179], v[50:53]
	v_mfma_f32_16x16x32_bf16 v[50:53], v[148:151], v[180:183], v[50:53]
	v_mfma_f32_16x16x32_bf16 v[54:57], v[134:137], v[176:179], v[54:57]
	v_mfma_f32_16x16x32_bf16 v[54:57], v[138:141], v[180:183], v[54:57]
	v_mfma_f32_16x16x32_bf16 v[42:45], v[134:137], v[184:187], v[42:45]
	v_mfma_f32_16x16x32_bf16 v[42:45], v[138:141], v[188:191], v[42:45]
	v_mfma_f32_16x16x32_bf16 v[34:37], v[142:145], v[184:187], v[34:37]
	v_mfma_f32_16x16x32_bf16 v[34:37], v[148:151], v[188:191], v[34:37]
	v_mfma_f32_16x16x32_bf16 v[14:17], v[152:155], v[184:187], v[14:17]
	v_mfma_f32_16x16x32_bf16 v[14:17], v[156:159], v[188:191], v[14:17]
	v_mfma_f32_16x16x32_bf16 v[10:13], v[160:163], v[184:187], v[10:13]
	v_mfma_f32_16x16x32_bf16 v[10:13], v[164:167], v[188:191], v[10:13]
	v_mfma_f32_16x16x32_bf16 v[2:5], v[160:163], v[192:195], v[2:5]
	v_mfma_f32_16x16x32_bf16 v[2:5], v[164:167], v[196:199], v[2:5]
	v_mfma_f32_16x16x32_bf16 v[6:9], v[152:155], v[192:195], v[6:9]
	v_mfma_f32_16x16x32_bf16 v[6:9], v[156:159], v[196:199], v[6:9]
	v_mfma_f32_16x16x32_bf16 v[18:21], v[142:145], v[192:195], v[18:21]
	v_mfma_f32_16x16x32_bf16 v[18:21], v[148:151], v[196:199], v[18:21]
	v_mfma_f32_16x16x32_bf16 v[26:29], v[134:137], v[192:195], v[26:29]
	v_mfma_f32_16x16x32_bf16 v[26:29], v[138:141], v[196:199], v[26:29]
	s_setprio 0
	s_barrier
	s_add_i32 s79, s79, 2
	s_addk_i32 s77, 0x100
	s_addk_i32 s78, 0x100
	s_cmp_ge_i32 s79, s3
	s_cbranch_scc0 .LBB0_799
	v_pk_mul_f32 v[184:185], v[128:129], 0.5 op_sel_hi:[1,0]
	v_pk_mul_f32 v[186:187], v[126:127], 0.5 op_sel_hi:[1,0]
	v_pk_mul_f32 v[188:189], v[124:125], 0.5 op_sel_hi:[1,0]
	v_pk_mul_f32 v[190:191], v[122:123], 0.5 op_sel_hi:[1,0]
	v_pk_mul_f32 v[198:199], v[112:113], 0.5 op_sel_hi:[1,0]
	v_pk_mul_f32 v[196:197], v[110:111], 0.5 op_sel_hi:[1,0]
	v_pk_mul_f32 v[194:195], v[104:105], 0.5 op_sel_hi:[1,0]
	v_pk_mul_f32 v[192:193], v[102:103], 0.5 op_sel_hi:[1,0]
	v_pk_mul_f32 v[182:183], v[120:121], 0.5 op_sel_hi:[1,0]
	v_pk_mul_f32 v[180:181], v[118:119], 0.5 op_sel_hi:[1,0]
	v_pk_mul_f32 v[178:179], v[116:117], 0.5 op_sel_hi:[1,0]
	v_pk_mul_f32 v[176:177], v[114:115], 0.5 op_sel_hi:[1,0]
	v_pk_mul_f32 v[172:173], v[96:97], 0.5 op_sel_hi:[1,0]
	v_pk_mul_f32 v[170:171], v[94:95], 0.5 op_sel_hi:[1,0]
	v_pk_mul_f32 v[168:169], v[88:89], 0.5 op_sel_hi:[1,0]
	v_pk_mul_f32 v[166:167], v[86:87], 0.5 op_sel_hi:[1,0]
	v_pk_mul_f32 v[164:165], v[108:109], 0.5 op_sel_hi:[1,0]
	v_pk_mul_f32 v[162:163], v[106:107], 0.5 op_sel_hi:[1,0]
	v_pk_mul_f32 v[160:161], v[100:101], 0.5 op_sel_hi:[1,0]
	v_pk_mul_f32 v[158:159], v[98:99], 0.5 op_sel_hi:[1,0]
	v_pk_mul_f32 v[156:157], v[80:81], 0.5 op_sel_hi:[1,0]
	v_pk_mul_f32 v[154:155], v[78:79], 0.5 op_sel_hi:[1,0]
	v_pk_mul_f32 v[152:153], v[76:77], 0.5 op_sel_hi:[1,0]
	v_pk_mul_f32 v[150:151], v[74:75], 0.5 op_sel_hi:[1,0]
	v_pk_mul_f32 v[144:145], v[92:93], 0.5 op_sel_hi:[1,0]
	v_pk_mul_f32 v[142:143], v[90:91], 0.5 op_sel_hi:[1,0]
	v_pk_mul_f32 v[140:141], v[84:85], 0.5 op_sel_hi:[1,0]
	v_pk_mul_f32 v[138:139], v[82:83], 0.5 op_sel_hi:[1,0]
	v_pk_mul_f32 v[136:137], v[72:73], 0.5 op_sel_hi:[1,0]
	v_pk_mul_f32 v[134:135], v[70:71], 0.5 op_sel_hi:[1,0]
	v_pk_mul_f32 v[128:129], v[68:69], 0.5 op_sel_hi:[1,0]
	v_pk_mul_f32 v[126:127], v[66:67], 0.5 op_sel_hi:[1,0]
	v_pk_mul_f32 v[122:123], v[64:65], 0.5 op_sel_hi:[1,0]
	v_pk_mul_f32 v[120:121], v[62:63], 0.5 op_sel_hi:[1,0]
	v_pk_mul_f32 v[118:119], v[60:61], 0.5 op_sel_hi:[1,0]
	v_pk_mul_f32 v[116:117], v[58:59], 0.5 op_sel_hi:[1,0]
	v_pk_mul_f32 v[112:113], v[48:49], 0.5 op_sel_hi:[1,0]
	v_pk_mul_f32 v[110:111], v[46:47], 0.5 op_sel_hi:[1,0]
	v_pk_mul_f32 v[108:109], v[40:41], 0.5 op_sel_hi:[1,0]
	v_pk_mul_f32 v[106:107], v[38:39], 0.5 op_sel_hi:[1,0]
	v_pk_mul_f32 v[104:105], v[56:57], 0.5 op_sel_hi:[1,0]
	v_pk_mul_f32 v[102:103], v[54:55], 0.5 op_sel_hi:[1,0]
	v_pk_mul_f32 v[100:101], v[52:53], 0.5 op_sel_hi:[1,0]
	v_pk_mul_f32 v[98:99], v[50:51], 0.5 op_sel_hi:[1,0]
	v_pk_mul_f32 v[96:97], v[32:33], 0.5 op_sel_hi:[1,0]
	v_pk_mul_f32 v[94:95], v[30:31], 0.5 op_sel_hi:[1,0]
	v_pk_mul_f32 v[92:93], v[24:25], 0.5 op_sel_hi:[1,0]
	v_pk_mul_f32 v[90:91], v[22:23], 0.5 op_sel_hi:[1,0]
	v_pk_mul_f32 v[88:89], v[44:45], 0.5 op_sel_hi:[1,0]
	v_pk_mul_f32 v[86:87], v[42:43], 0.5 op_sel_hi:[1,0]
	v_pk_mul_f32 v[84:85], v[36:37], 0.5 op_sel_hi:[1,0]
	v_pk_mul_f32 v[82:83], v[34:35], 0.5 op_sel_hi:[1,0]
	v_pk_mul_f32 v[80:81], v[16:17], 0.5 op_sel_hi:[1,0]
	v_pk_mul_f32 v[78:79], v[14:15], 0.5 op_sel_hi:[1,0]
	v_pk_mul_f32 v[76:77], v[12:13], 0.5 op_sel_hi:[1,0]
	v_pk_mul_f32 v[74:75], v[10:11], 0.5 op_sel_hi:[1,0]
	v_pk_mul_f32 v[72:73], v[28:29], 0.5 op_sel_hi:[1,0]
	v_pk_mul_f32 v[70:71], v[26:27], 0.5 op_sel_hi:[1,0]
	v_pk_mul_f32 v[68:69], v[20:21], 0.5 op_sel_hi:[1,0]
	v_pk_mul_f32 v[66:67], v[18:19], 0.5 op_sel_hi:[1,0]
	v_pk_mul_f32 v[64:65], v[8:9], 0.5 op_sel_hi:[1,0]
	v_pk_mul_f32 v[62:63], v[6:7], 0.5 op_sel_hi:[1,0]
	v_pk_mul_f32 v[60:61], v[4:5], 0.5 op_sel_hi:[1,0]
	v_pk_mul_f32 v[58:59], v[2:3], 0.5 op_sel_hi:[1,0]
	s_and_b64 vcc, exec, s[38:39]
	s_cbranch_vccz .LBB0_802

.LBB0_892:
	ds_read_b128 v[130:133], v172
	ds_read_b128 v[134:137], v172 offset:1024
	ds_read_b128 v[148:151], v172 offset:2048
	ds_read_b128 v[152:155], v172 offset:3072
	ds_read_b128 v[156:159], v173
	ds_read_b128 v[160:163], v173 offset:1024
	ds_read_b128 v[164:167], v173 offset:2048
	ds_read_b128 v[180:183], v173 offset:3072
	s_add_i32 s18, s8, 0xffe80080
	s_cmp_eq_u32 s77, s52
	s_cselect_b32 s53, s6, s18
	s_cselect_b32 s58, s7, s9
	s_or_b32 s57, s53, 0x80
	s_add_i32 s18, s8, 0xfff80000
	s_mov_b32 m0, s78
	ds_read_b128 v[184:187], v174
	ds_read_b128 v[188:191], v174 offset:1024
	ds_read_b128 v[192:195], v174 offset:2048
	ds_read_b128 v[196:199], v174 offset:3072
	ds_read_b128 v[200:203], v174 offset:4096
	ds_read_b128 v[204:207], v174 offset:5120
	ds_read_b128 v[208:211], v174 offset:6144
	ds_read_b128 v[212:215], v174 offset:7168
	buffer_load_dwordx4 v170, s[12:15], s18 offen lds
	s_mov_b32 m0, s79
	s_nop 0
	buffer_load_dwordx4 v170, s[12:15], s8 offen lds
	s_waitcnt vmcnt(8)
	s_waitcnt lgkmcnt(0)
	s_setprio 1
	s_barrier
	v_mfma_f32_16x16x32_bf16 v[126:129], v[130:133], v[184:187], v[126:129]
	v_mfma_f32_16x16x32_bf16 v[126:129], v[134:137], v[188:191], v[126:129]
	v_mfma_f32_16x16x32_bf16 v[118:121], v[148:151], v[184:187], v[118:121]
	v_mfma_f32_16x16x32_bf16 v[118:121], v[152:155], v[188:191], v[118:121]
	v_mfma_f32_16x16x32_bf16 v[122:125], v[156:159], v[184:187], v[122:125]
	v_mfma_f32_16x16x32_bf16 v[122:125], v[160:163], v[188:191], v[122:125]
	v_mfma_f32_16x16x32_bf16 v[114:117], v[164:167], v[184:187], v[114:117]
	v_mfma_f32_16x16x32_bf16 v[114:117], v[180:183], v[188:191], v[114:117]
	v_mfma_f32_16x16x32_bf16 v[98:101], v[164:167], v[192:195], v[98:101]
	v_mfma_f32_16x16x32_bf16 v[98:101], v[180:183], v[196:199], v[98:101]
	v_mfma_f32_16x16x32_bf16 v[106:109], v[156:159], v[192:195], v[106:109]
	v_mfma_f32_16x16x32_bf16 v[106:109], v[160:163], v[196:199], v[106:109]
	v_mfma_f32_16x16x32_bf16 v[102:105], v[148:151], v[192:195], v[102:105]
	v_mfma_f32_16x16x32_bf16 v[102:105], v[152:155], v[196:199], v[102:105]
	v_mfma_f32_16x16x32_bf16 v[110:113], v[130:133], v[192:195], v[110:113]
	v_mfma_f32_16x16x32_bf16 v[110:113], v[134:137], v[196:199], v[110:113]
	v_mfma_f32_16x16x32_bf16 v[94:97], v[130:133], v[200:203], v[94:97]
	v_mfma_f32_16x16x32_bf16 v[94:97], v[134:137], v[204:207], v[94:97]
	v_mfma_f32_16x16x32_bf16 v[90:93], v[148:151], v[200:203], v[90:93]
	v_mfma_f32_16x16x32_bf16 v[90:93], v[152:155], v[204:207], v[90:93]
	v_mfma_f32_16x16x32_bf16 v[86:89], v[156:159], v[200:203], v[86:89]
	v_mfma_f32_16x16x32_bf16 v[86:89], v[160:163], v[204:207], v[86:89]
	v_mfma_f32_16x16x32_bf16 v[82:85], v[164:167], v[200:203], v[82:85]
	v_mfma_f32_16x16x32_bf16 v[82:85], v[180:183], v[204:207], v[82:85]
	v_mfma_f32_16x16x32_bf16 v[66:69], v[164:167], v[208:211], v[66:69]
	v_mfma_f32_16x16x32_bf16 v[66:69], v[180:183], v[212:215], v[66:69]
	v_mfma_f32_16x16x32_bf16 v[74:77], v[156:159], v[208:211], v[74:77]
	v_mfma_f32_16x16x32_bf16 v[74:77], v[160:163], v[212:215], v[74:77]
	v_mfma_f32_16x16x32_bf16 v[70:73], v[148:151], v[208:211], v[70:73]
	v_mfma_f32_16x16x32_bf16 v[70:73], v[152:155], v[212:215], v[70:73]
	v_mfma_f32_16x16x32_bf16 v[78:81], v[130:133], v[208:211], v[78:81]
	v_mfma_f32_16x16x32_bf16 v[78:81], v[134:137], v[212:215], v[78:81]
	s_setprio 0
	s_barrier
	s_mov_b32 m0, s27
	s_mov_b32 s18, s14
	s_mov_b32 s19, s15
	ds_read_b128 v[184:187], v174 offset:16384
	ds_read_b128 v[188:191], v174 offset:17408
	ds_read_b128 v[192:195], v174 offset:18432
	ds_read_b128 v[196:199], v174 offset:19456
	ds_read_b128 v[200:203], v174 offset:20480
	ds_read_b128 v[204:207], v174 offset:21504
	ds_read_b128 v[208:211], v174 offset:22528
	ds_read_b128 v[212:215], v174 offset:23552
	buffer_load_dwordx4 v171, s[16:19], s58 offen lds
	s_add_i32 s59, s58, 0x80000
	s_mov_b32 m0, s60
	s_nop 0
	buffer_load_dwordx4 v171, s[16:19], s59 offen lds
	s_add_i32 s59, s58, 0x100000
	s_mov_b32 m0, s61
	s_nop 0
	buffer_load_dwordx4 v171, s[16:19], s59 offen lds
	s_add_i32 s59, s58, 0x180000
	s_mov_b32 m0, s62
	s_nop 0
	buffer_load_dwordx4 v171, s[16:19], s59 offen lds
	s_mov_b32 m0, s25
	s_add_i32 s59, s53, 0x80000
	buffer_load_dwordx4 v170, s[12:15], s53 offen lds
	s_mov_b32 m0, s63
	s_nop 0
	buffer_load_dwordx4 v170, s[12:15], s59 offen lds
	s_waitcnt vmcnt(8)
	s_waitcnt lgkmcnt(0)
	s_setprio 1
	s_barrier
	v_mfma_f32_16x16x32_bf16 v[62:65], v[130:133], v[184:187], v[62:65]
	v_mfma_f32_16x16x32_bf16 v[62:65], v[134:137], v[188:191], v[62:65]
	v_mfma_f32_16x16x32_bf16 v[54:57], v[148:151], v[184:187], v[54:57]
	v_mfma_f32_16x16x32_bf16 v[54:57], v[152:155], v[188:191], v[54:57]
	v_mfma_f32_16x16x32_bf16 v[58:61], v[156:159], v[184:187], v[58:61]
	v_mfma_f32_16x16x32_bf16 v[58:61], v[160:163], v[188:191], v[58:61]
	v_mfma_f32_16x16x32_bf16 v[50:53], v[164:167], v[184:187], v[50:53]
	v_mfma_f32_16x16x32_bf16 v[50:53], v[180:183], v[188:191], v[50:53]
	v_mfma_f32_16x16x32_bf16 v[34:37], v[164:167], v[192:195], v[34:37]
	v_mfma_f32_16x16x32_bf16 v[34:37], v[180:183], v[196:199], v[34:37]
	v_mfma_f32_16x16x32_bf16 v[42:45], v[156:159], v[192:195], v[42:45]
	v_mfma_f32_16x16x32_bf16 v[42:45], v[160:163], v[196:199], v[42:45]
	v_mfma_f32_16x16x32_bf16 v[38:41], v[148:151], v[192:195], v[38:41]
	v_mfma_f32_16x16x32_bf16 v[38:41], v[152:155], v[196:199], v[38:41]
	v_mfma_f32_16x16x32_bf16 v[46:49], v[130:133], v[192:195], v[46:49]
	v_mfma_f32_16x16x32_bf16 v[46:49], v[134:137], v[196:199], v[46:49]
	v_mfma_f32_16x16x32_bf16 v[30:33], v[130:133], v[200:203], v[30:33]
	v_mfma_f32_16x16x32_bf16 v[30:33], v[134:137], v[204:207], v[30:33]
	v_mfma_f32_16x16x32_bf16 v[22:25], v[148:151], v[200:203], v[22:25]
	v_mfma_f32_16x16x32_bf16 v[22:25], v[152:155], v[204:207], v[22:25]
	v_mfma_f32_16x16x32_bf16 v[26:29], v[156:159], v[200:203], v[26:29]
	v_mfma_f32_16x16x32_bf16 v[26:29], v[160:163], v[204:207], v[26:29]
	v_mfma_f32_16x16x32_bf16 v[18:21], v[164:167], v[200:203], v[18:21]
	v_mfma_f32_16x16x32_bf16 v[18:21], v[180:183], v[204:207], v[18:21]
	v_mfma_f32_16x16x32_bf16 v[2:5], v[164:167], v[208:211], v[2:5]
	v_mfma_f32_16x16x32_bf16 v[2:5], v[180:183], v[212:215], v[2:5]
	v_mfma_f32_16x16x32_bf16 v[10:13], v[156:159], v[208:211], v[10:13]
	v_mfma_f32_16x16x32_bf16 v[10:13], v[160:163], v[212:215], v[10:13]
	v_mfma_f32_16x16x32_bf16 v[6:9], v[148:151], v[208:211], v[6:9]
	v_mfma_f32_16x16x32_bf16 v[6:9], v[152:155], v[212:215], v[6:9]
	v_mfma_f32_16x16x32_bf16 v[14:17], v[130:133], v[208:211], v[14:17]
	v_mfma_f32_16x16x32_bf16 v[14:17], v[134:137], v[212:215], v[14:17]
	s_setprio 0
	s_barrier
	ds_read_b128 v[130:133], v175
	ds_read_b128 v[134:137], v175 offset:1024
	ds_read_b128 v[148:151], v175 offset:2048
	ds_read_b128 v[152:155], v175 offset:3072
	ds_read_b128 v[156:159], v176
	ds_read_b128 v[160:163], v176 offset:1024
	ds_read_b128 v[164:167], v176 offset:2048
	ds_read_b128 v[180:183], v176 offset:3072
	s_mov_b32 m0, s64
	s_add_i32 s59, s53, 0x100000
	ds_read_b128 v[184:187], v174 offset:32768
	ds_read_b128 v[188:191], v174 offset:33792
	ds_read_b128 v[192:195], v174 offset:34816
	ds_read_b128 v[196:199], v174 offset:35840
	ds_read_b128 v[200:203], v174 offset:36864
	ds_read_b128 v[204:207], v174 offset:37888
	ds_read_b128 v[208:211], v174 offset:38912
	ds_read_b128 v[212:215], v174 offset:39936
	buffer_load_dwordx4 v170, s[12:15], s59 offen lds
	s_add_i32 s59, s53, 0x180000
	s_mov_b32 m0, s65
	s_nop 0
	buffer_load_dwordx4 v170, s[12:15], s59 offen lds
	s_waitcnt vmcnt(8)
	s_waitcnt lgkmcnt(0)
	s_setprio 1
	s_barrier
	v_mfma_f32_16x16x32_bf16 v[126:129], v[130:133], v[184:187], v[126:129]
	v_mfma_f32_16x16x32_bf16 v[126:129], v[134:137], v[188:191], v[126:129]
	v_mfma_f32_16x16x32_bf16 v[118:121], v[148:151], v[184:187], v[118:121]
	v_mfma_f32_16x16x32_bf16 v[118:121], v[152:155], v[188:191], v[118:121]
	v_mfma_f32_16x16x32_bf16 v[122:125], v[156:159], v[184:187], v[122:125]
	v_mfma_f32_16x16x32_bf16 v[122:125], v[160:163], v[188:191], v[122:125]
	v_mfma_f32_16x16x32_bf16 v[114:117], v[164:167], v[184:187], v[114:117]
	v_mfma_f32_16x16x32_bf16 v[114:117], v[180:183], v[188:191], v[114:117]
	v_mfma_f32_16x16x32_bf16 v[98:101], v[164:167], v[192:195], v[98:101]
	v_mfma_f32_16x16x32_bf16 v[98:101], v[180:183], v[196:199], v[98:101]
	v_mfma_f32_16x16x32_bf16 v[106:109], v[156:159], v[192:195], v[106:109]
	v_mfma_f32_16x16x32_bf16 v[106:109], v[160:163], v[196:199], v[106:109]
	v_mfma_f32_16x16x32_bf16 v[102:105], v[148:151], v[192:195], v[102:105]
	v_mfma_f32_16x16x32_bf16 v[102:105], v[152:155], v[196:199], v[102:105]
	v_mfma_f32_16x16x32_bf16 v[110:113], v[130:133], v[192:195], v[110:113]
	v_mfma_f32_16x16x32_bf16 v[110:113], v[134:137], v[196:199], v[110:113]
	v_mfma_f32_16x16x32_bf16 v[94:97], v[130:133], v[200:203], v[94:97]
	v_mfma_f32_16x16x32_bf16 v[94:97], v[134:137], v[204:207], v[94:97]
	v_mfma_f32_16x16x32_bf16 v[90:93], v[148:151], v[200:203], v[90:93]
	v_mfma_f32_16x16x32_bf16 v[90:93], v[152:155], v[204:207], v[90:93]
	v_mfma_f32_16x16x32_bf16 v[86:89], v[156:159], v[200:203], v[86:89]
	v_mfma_f32_16x16x32_bf16 v[86:89], v[160:163], v[204:207], v[86:89]
	v_mfma_f32_16x16x32_bf16 v[82:85], v[164:167], v[200:203], v[82:85]
	v_mfma_f32_16x16x32_bf16 v[82:85], v[180:183], v[204:207], v[82:85]
	v_mfma_f32_16x16x32_bf16 v[66:69], v[164:167], v[208:211], v[66:69]
	v_mfma_f32_16x16x32_bf16 v[66:69], v[180:183], v[212:215], v[66:69]
	v_mfma_f32_16x16x32_bf16 v[74:77], v[156:159], v[208:211], v[74:77]
	v_mfma_f32_16x16x32_bf16 v[74:77], v[160:163], v[212:215], v[74:77]
	v_mfma_f32_16x16x32_bf16 v[70:73], v[148:151], v[208:211], v[70:73]
	v_mfma_f32_16x16x32_bf16 v[70:73], v[152:155], v[212:215], v[70:73]
	v_mfma_f32_16x16x32_bf16 v[78:81], v[130:133], v[208:211], v[78:81]
	v_mfma_f32_16x16x32_bf16 v[78:81], v[134:137], v[212:215], v[78:81]
	s_setprio 0
	s_barrier
	s_mov_b32 m0, s70
	s_or_b32 s59, s58, 0x80
	ds_read_b128 v[184:187], v174 offset:49152
	ds_read_b128 v[188:191], v174 offset:50176
	ds_read_b128 v[192:195], v174 offset:51200
	ds_read_b128 v[196:199], v174 offset:52224
	ds_read_b128 v[200:203], v174 offset:53248
	ds_read_b128 v[204:207], v174 offset:54272
	ds_read_b128 v[208:211], v174 offset:55296
	ds_read_b128 v[212:215], v174 offset:56320
	buffer_load_dwordx4 v171, s[16:19], s59 offen lds
	s_add_i32 s59, s58, 0x80080
	s_mov_b32 m0, s71
	s_add_i32 s53, s53, 0x80080
	buffer_load_dwordx4 v171, s[16:19], s59 offen lds
	s_add_i32 s59, s58, 0x100080
	s_mov_b32 m0, s74
	s_add_i32 s58, s58, 0x180080
	buffer_load_dwordx4 v171, s[16:19], s59 offen lds
	s_mov_b32 m0, s75
	s_nop 0
	buffer_load_dwordx4 v171, s[16:19], s58 offen lds
	s_mov_b32 m0, s72
	s_nop 0
	buffer_load_dwordx4 v170, s[12:15], s57 offen lds
	s_mov_b32 m0, s73
	s_nop 0
	buffer_load_dwordx4 v170, s[12:15], s53 offen lds
	s_waitcnt vmcnt(8)
	s_waitcnt lgkmcnt(0)
	s_setprio 1
	s_barrier
	v_mfma_f32_16x16x32_bf16 v[62:65], v[130:133], v[184:187], v[62:65]
	v_mfma_f32_16x16x32_bf16 v[62:65], v[134:137], v[188:191], v[62:65]
	v_mfma_f32_16x16x32_bf16 v[54:57], v[148:151], v[184:187], v[54:57]
	v_mfma_f32_16x16x32_bf16 v[54:57], v[152:155], v[188:191], v[54:57]
	v_mfma_f32_16x16x32_bf16 v[58:61], v[156:159], v[184:187], v[58:61]
	v_mfma_f32_16x16x32_bf16 v[58:61], v[160:163], v[188:191], v[58:61]
	v_mfma_f32_16x16x32_bf16 v[50:53], v[164:167], v[184:187], v[50:53]
	v_mfma_f32_16x16x32_bf16 v[50:53], v[180:183], v[188:191], v[50:53]
	v_mfma_f32_16x16x32_bf16 v[34:37], v[164:167], v[192:195], v[34:37]
	v_mfma_f32_16x16x32_bf16 v[34:37], v[180:183], v[196:199], v[34:37]
	v_mfma_f32_16x16x32_bf16 v[42:45], v[156:159], v[192:195], v[42:45]
	v_mfma_f32_16x16x32_bf16 v[42:45], v[160:163], v[196:199], v[42:45]
	v_mfma_f32_16x16x32_bf16 v[38:41], v[148:151], v[192:195], v[38:41]
	v_mfma_f32_16x16x32_bf16 v[38:41], v[152:155], v[196:199], v[38:41]
	v_mfma_f32_16x16x32_bf16 v[46:49], v[130:133], v[192:195], v[46:49]
	v_mfma_f32_16x16x32_bf16 v[46:49], v[134:137], v[196:199], v[46:49]
	v_mfma_f32_16x16x32_bf16 v[30:33], v[130:133], v[200:203], v[30:33]
	v_mfma_f32_16x16x32_bf16 v[30:33], v[134:137], v[204:207], v[30:33]
	v_mfma_f32_16x16x32_bf16 v[22:25], v[148:151], v[200:203], v[22:25]
	v_mfma_f32_16x16x32_bf16 v[22:25], v[152:155], v[204:207], v[22:25]
	v_mfma_f32_16x16x32_bf16 v[26:29], v[156:159], v[200:203], v[26:29]
	v_mfma_f32_16x16x32_bf16 v[26:29], v[160:163], v[204:207], v[26:29]
	v_mfma_f32_16x16x32_bf16 v[18:21], v[164:167], v[200:203], v[18:21]
	v_mfma_f32_16x16x32_bf16 v[18:21], v[180:183], v[204:207], v[18:21]
	v_mfma_f32_16x16x32_bf16 v[2:5], v[164:167], v[208:211], v[2:5]
	v_mfma_f32_16x16x32_bf16 v[2:5], v[180:183], v[212:215], v[2:5]
	v_mfma_f32_16x16x32_bf16 v[10:13], v[156:159], v[208:211], v[10:13]
	v_mfma_f32_16x16x32_bf16 v[10:13], v[160:163], v[212:215], v[10:13]
	v_mfma_f32_16x16x32_bf16 v[6:9], v[148:151], v[208:211], v[6:9]
	v_mfma_f32_16x16x32_bf16 v[6:9], v[152:155], v[212:215], v[6:9]
	v_mfma_f32_16x16x32_bf16 v[14:17], v[130:133], v[208:211], v[14:17]
	v_mfma_f32_16x16x32_bf16 v[14:17], v[134:137], v[212:215], v[14:17]
	s_setprio 0
	s_barrier
	s_add_i32 s52, s52, 2
	s_addk_i32 s8, 0x100
	s_addk_i32 s9, 0x100
	s_cmp_ge_i32 s52, s21
	s_cbranch_scc0 .LBB0_892
	s_and_b64 vcc, exec, s[48:49]
	s_cbranch_vccz .LBB0_895

.LBB0_1020:
	v_add_u32_e32 v142, 0x10000, v162
	v_add_u32_e32 v150, 0x14000, v162
	ds_read_b128 v[130:133], v142
	ds_read_b128 v[134:137], v142 offset:1024
	ds_read_b128 v[138:141], v142 offset:2048
	ds_read_b128 v[142:145], v142 offset:3072
	ds_read_b128 v[154:157], v150
	ds_read_b128 v[164:167], v150 offset:1024
	ds_read_b128 v[168:171], v150 offset:2048
	ds_read_b128 v[172:175], v150 offset:3072
	s_add_i32 s90, s6, 0x100
	s_add_i32 s7, s88, s6
	s_cmp_eq_u32 s81, s89
	s_cselect_b32 s91, 0, s90
	s_cselect_b32 s93, s87, s7
	s_add_i32 s91, s91, s70
	s_or_b32 s92, s91, 0x80
	s_add_i32 s6, s3, s6
	s_mov_b32 m0, s82
	s_add_i32 s7, s6, 0x20080
	ds_read_b128 v[176:179], v163
	ds_read_b128 v[180:183], v163 offset:1024
	ds_read_b128 v[184:187], v163 offset:2048
	ds_read_b128 v[188:191], v163 offset:3072
	ds_read_b128 v[192:195], v163 offset:4096
	ds_read_b128 v[196:199], v163 offset:5120
	ds_read_b128 v[200:203], v163 offset:6144
	ds_read_b128 v[204:207], v163 offset:7168
	buffer_load_dwordx4 v161, s[12:15], s7 offen lds
	s_add_i32 s6, s6, 0x30080
	s_mov_b32 m0, s83
	s_nop 0
	buffer_load_dwordx4 v161, s[12:15], s6 offen lds
	s_waitcnt vmcnt(8)
	s_waitcnt lgkmcnt(0)
	s_setprio 1
	s_barrier
	v_mfma_f32_16x16x32_bf16 v[126:129], v[130:133], v[176:179], v[126:129]
	v_mfma_f32_16x16x32_bf16 v[126:129], v[134:137], v[180:183], v[126:129]
	v_mfma_f32_16x16x32_bf16 v[122:125], v[138:141], v[176:179], v[122:125]
	v_mfma_f32_16x16x32_bf16 v[122:125], v[142:145], v[180:183], v[122:125]
	v_mfma_f32_16x16x32_bf16 v[118:121], v[154:157], v[176:179], v[118:121]
	v_mfma_f32_16x16x32_bf16 v[118:121], v[164:167], v[180:183], v[118:121]
	v_mfma_f32_16x16x32_bf16 v[114:117], v[168:171], v[176:179], v[114:117]
	v_mfma_f32_16x16x32_bf16 v[114:117], v[172:175], v[180:183], v[114:117]
	v_mfma_f32_16x16x32_bf16 v[98:101], v[168:171], v[184:187], v[98:101]
	v_mfma_f32_16x16x32_bf16 v[98:101], v[172:175], v[188:191], v[98:101]
	v_mfma_f32_16x16x32_bf16 v[102:105], v[154:157], v[184:187], v[102:105]
	v_mfma_f32_16x16x32_bf16 v[102:105], v[164:167], v[188:191], v[102:105]
	v_mfma_f32_16x16x32_bf16 v[106:109], v[138:141], v[184:187], v[106:109]
	v_mfma_f32_16x16x32_bf16 v[106:109], v[142:145], v[188:191], v[106:109]
	v_mfma_f32_16x16x32_bf16 v[110:113], v[130:133], v[184:187], v[110:113]
	v_mfma_f32_16x16x32_bf16 v[110:113], v[134:137], v[188:191], v[110:113]
	v_mfma_f32_16x16x32_bf16 v[94:97], v[130:133], v[192:195], v[94:97]
	v_mfma_f32_16x16x32_bf16 v[94:97], v[134:137], v[196:199], v[94:97]
	v_mfma_f32_16x16x32_bf16 v[90:93], v[138:141], v[192:195], v[90:93]
	v_mfma_f32_16x16x32_bf16 v[90:93], v[142:145], v[196:199], v[90:93]
	v_mfma_f32_16x16x32_bf16 v[86:89], v[154:157], v[192:195], v[86:89]
	v_mfma_f32_16x16x32_bf16 v[86:89], v[164:167], v[196:199], v[86:89]
	v_mfma_f32_16x16x32_bf16 v[82:85], v[168:171], v[192:195], v[82:85]
	v_mfma_f32_16x16x32_bf16 v[82:85], v[172:175], v[196:199], v[82:85]
	v_mfma_f32_16x16x32_bf16 v[66:69], v[168:171], v[200:203], v[66:69]
	v_mfma_f32_16x16x32_bf16 v[66:69], v[172:175], v[204:207], v[66:69]
	v_mfma_f32_16x16x32_bf16 v[70:73], v[154:157], v[200:203], v[70:73]
	v_mfma_f32_16x16x32_bf16 v[70:73], v[164:167], v[204:207], v[70:73]
	v_mfma_f32_16x16x32_bf16 v[74:77], v[138:141], v[200:203], v[74:77]
	v_mfma_f32_16x16x32_bf16 v[74:77], v[142:145], v[204:207], v[74:77]
	v_mfma_f32_16x16x32_bf16 v[78:81], v[130:133], v[200:203], v[78:81]
	v_mfma_f32_16x16x32_bf16 v[78:81], v[134:137], v[204:207], v[78:81]
	s_setprio 0
	s_barrier
	s_mov_b32 m0, s66
	s_mov_b32 s6, s14
	s_mov_b32 s7, s15
	ds_read_b128 v[176:179], v163 offset:16384
	ds_read_b128 v[180:183], v163 offset:17408
	ds_read_b128 v[184:187], v163 offset:18432
	ds_read_b128 v[188:191], v163 offset:19456
	ds_read_b128 v[192:195], v163 offset:20480
	ds_read_b128 v[196:199], v163 offset:21504
	ds_read_b128 v[200:203], v163 offset:22528
	ds_read_b128 v[204:207], v163 offset:23552
	buffer_load_dwordx4 v160, s[4:7], s93 offen lds
	s_add_i32 s94, s93, 0x10000
	s_mov_b32 m0, s67
	s_nop 0
	buffer_load_dwordx4 v160, s[4:7], s94 offen lds
	s_add_i32 s94, s93, 0x20000
	s_mov_b32 m0, s68
	s_nop 0
	buffer_load_dwordx4 v160, s[4:7], s94 offen lds
	s_add_i32 s94, s93, 0x30000
	s_mov_b32 m0, s69
	s_nop 0
	buffer_load_dwordx4 v160, s[4:7], s94 offen lds
	s_mov_b32 m0, s65
	s_add_i32 s94, s91, 0x10000
	buffer_load_dwordx4 v161, s[12:15], s91 offen lds
	s_mov_b32 m0, s71
	s_nop 0
	buffer_load_dwordx4 v161, s[12:15], s94 offen lds
	s_waitcnt vmcnt(8)
	s_waitcnt lgkmcnt(0)
	s_setprio 1
	s_barrier
	v_mfma_f32_16x16x32_bf16 v[62:65], v[130:133], v[176:179], v[62:65]
	v_mfma_f32_16x16x32_bf16 v[62:65], v[134:137], v[180:183], v[62:65]
	v_mfma_f32_16x16x32_bf16 v[58:61], v[138:141], v[176:179], v[58:61]
	v_mfma_f32_16x16x32_bf16 v[58:61], v[142:145], v[180:183], v[58:61]
	v_mfma_f32_16x16x32_bf16 v[54:57], v[154:157], v[176:179], v[54:57]
	v_mfma_f32_16x16x32_bf16 v[54:57], v[164:167], v[180:183], v[54:57]
	v_mfma_f32_16x16x32_bf16 v[50:53], v[168:171], v[176:179], v[50:53]
	v_mfma_f32_16x16x32_bf16 v[50:53], v[172:175], v[180:183], v[50:53]
	v_mfma_f32_16x16x32_bf16 v[34:37], v[168:171], v[184:187], v[34:37]
	v_mfma_f32_16x16x32_bf16 v[34:37], v[172:175], v[188:191], v[34:37]
	v_mfma_f32_16x16x32_bf16 v[38:41], v[154:157], v[184:187], v[38:41]
	v_mfma_f32_16x16x32_bf16 v[38:41], v[164:167], v[188:191], v[38:41]
	v_mfma_f32_16x16x32_bf16 v[42:45], v[138:141], v[184:187], v[42:45]
	v_mfma_f32_16x16x32_bf16 v[42:45], v[142:145], v[188:191], v[42:45]
	v_mfma_f32_16x16x32_bf16 v[46:49], v[130:133], v[184:187], v[46:49]
	v_mfma_f32_16x16x32_bf16 v[46:49], v[134:137], v[188:191], v[46:49]
	v_mfma_f32_16x16x32_bf16 v[30:33], v[130:133], v[192:195], v[30:33]
	v_mfma_f32_16x16x32_bf16 v[30:33], v[134:137], v[196:199], v[30:33]
	v_mfma_f32_16x16x32_bf16 v[26:29], v[138:141], v[192:195], v[26:29]
	v_mfma_f32_16x16x32_bf16 v[26:29], v[142:145], v[196:199], v[26:29]
	v_mfma_f32_16x16x32_bf16 v[22:25], v[154:157], v[192:195], v[22:25]
	v_mfma_f32_16x16x32_bf16 v[22:25], v[164:167], v[196:199], v[22:25]
	v_mfma_f32_16x16x32_bf16 v[18:21], v[168:171], v[192:195], v[18:21]
	v_mfma_f32_16x16x32_bf16 v[18:21], v[172:175], v[196:199], v[18:21]
	v_mfma_f32_16x16x32_bf16 v[2:5], v[168:171], v[200:203], v[2:5]
	v_mfma_f32_16x16x32_bf16 v[2:5], v[172:175], v[204:207], v[2:5]
	v_mfma_f32_16x16x32_bf16 v[6:9], v[154:157], v[200:203], v[6:9]
	v_mfma_f32_16x16x32_bf16 v[6:9], v[164:167], v[204:207], v[6:9]
	v_mfma_f32_16x16x32_bf16 v[10:13], v[138:141], v[200:203], v[10:13]
	v_mfma_f32_16x16x32_bf16 v[10:13], v[142:145], v[204:207], v[10:13]
	v_mfma_f32_16x16x32_bf16 v[14:17], v[130:133], v[200:203], v[14:17]
	v_mfma_f32_16x16x32_bf16 v[14:17], v[134:137], v[204:207], v[14:17]
	s_setprio 0
	s_barrier
	v_add_u32_e32 v142, 0x18000, v162
	v_add_u32_e32 v150, 0x1c000, v162
	ds_read_b128 v[130:133], v142
	ds_read_b128 v[134:137], v142 offset:1024
	ds_read_b128 v[138:141], v142 offset:2048
	ds_read_b128 v[142:145], v142 offset:3072
	ds_read_b128 v[154:157], v150
	ds_read_b128 v[164:167], v150 offset:1024
	ds_read_b128 v[168:171], v150 offset:2048
	ds_read_b128 v[172:175], v150 offset:3072
	s_mov_b32 m0, s72
	s_add_i32 s94, s91, 0x20000
	ds_read_b128 v[176:179], v163 offset:32768
	ds_read_b128 v[180:183], v163 offset:33792
	ds_read_b128 v[184:187], v163 offset:34816
	ds_read_b128 v[188:191], v163 offset:35840
	ds_read_b128 v[192:195], v163 offset:36864
	ds_read_b128 v[196:199], v163 offset:37888
	ds_read_b128 v[200:203], v163 offset:38912
	ds_read_b128 v[204:207], v163 offset:39936
	buffer_load_dwordx4 v161, s[12:15], s94 offen lds
	s_add_i32 s94, s91, 0x30000
	s_mov_b32 m0, s73
	s_nop 0
	buffer_load_dwordx4 v161, s[12:15], s94 offen lds
	s_waitcnt vmcnt(8)
	s_waitcnt lgkmcnt(0)
	s_setprio 1
	s_barrier
	v_mfma_f32_16x16x32_bf16 v[126:129], v[130:133], v[176:179], v[126:129]
	v_mfma_f32_16x16x32_bf16 v[126:129], v[134:137], v[180:183], v[126:129]
	v_mfma_f32_16x16x32_bf16 v[122:125], v[138:141], v[176:179], v[122:125]
	v_mfma_f32_16x16x32_bf16 v[122:125], v[142:145], v[180:183], v[122:125]
	v_mfma_f32_16x16x32_bf16 v[118:121], v[154:157], v[176:179], v[118:121]
	v_mfma_f32_16x16x32_bf16 v[118:121], v[164:167], v[180:183], v[118:121]
	v_mfma_f32_16x16x32_bf16 v[114:117], v[168:171], v[176:179], v[114:117]
	v_mfma_f32_16x16x32_bf16 v[114:117], v[172:175], v[180:183], v[114:117]
	v_mfma_f32_16x16x32_bf16 v[98:101], v[168:171], v[184:187], v[98:101]
	v_mfma_f32_16x16x32_bf16 v[98:101], v[172:175], v[188:191], v[98:101]
	v_mfma_f32_16x16x32_bf16 v[102:105], v[154:157], v[184:187], v[102:105]
	v_mfma_f32_16x16x32_bf16 v[102:105], v[164:167], v[188:191], v[102:105]
	v_mfma_f32_16x16x32_bf16 v[106:109], v[138:141], v[184:187], v[106:109]
	v_mfma_f32_16x16x32_bf16 v[106:109], v[142:145], v[188:191], v[106:109]
	v_mfma_f32_16x16x32_bf16 v[110:113], v[130:133], v[184:187], v[110:113]
	v_mfma_f32_16x16x32_bf16 v[110:113], v[134:137], v[188:191], v[110:113]
	v_mfma_f32_16x16x32_bf16 v[94:97], v[130:133], v[192:195], v[94:97]
	v_mfma_f32_16x16x32_bf16 v[94:97], v[134:137], v[196:199], v[94:97]
	v_mfma_f32_16x16x32_bf16 v[90:93], v[138:141], v[192:195], v[90:93]
	v_mfma_f32_16x16x32_bf16 v[90:93], v[142:145], v[196:199], v[90:93]
	v_mfma_f32_16x16x32_bf16 v[86:89], v[154:157], v[192:195], v[86:89]
	v_mfma_f32_16x16x32_bf16 v[86:89], v[164:167], v[196:199], v[86:89]
	v_mfma_f32_16x16x32_bf16 v[82:85], v[168:171], v[192:195], v[82:85]
	v_mfma_f32_16x16x32_bf16 v[82:85], v[172:175], v[196:199], v[82:85]
	v_mfma_f32_16x16x32_bf16 v[66:69], v[168:171], v[200:203], v[66:69]
	v_mfma_f32_16x16x32_bf16 v[66:69], v[172:175], v[204:207], v[66:69]
	v_mfma_f32_16x16x32_bf16 v[70:73], v[154:157], v[200:203], v[70:73]
	v_mfma_f32_16x16x32_bf16 v[70:73], v[164:167], v[204:207], v[70:73]
	v_mfma_f32_16x16x32_bf16 v[74:77], v[138:141], v[200:203], v[74:77]
	v_mfma_f32_16x16x32_bf16 v[74:77], v[142:145], v[204:207], v[74:77]
	v_mfma_f32_16x16x32_bf16 v[78:81], v[130:133], v[200:203], v[78:81]
	v_mfma_f32_16x16x32_bf16 v[78:81], v[134:137], v[204:207], v[78:81]
	s_setprio 0
	s_barrier
	s_mov_b32 m0, s74
	s_or_b32 s94, s93, 0x80
	ds_read_b128 v[176:179], v163 offset:49152
	ds_read_b128 v[180:183], v163 offset:50176
	ds_read_b128 v[184:187], v163 offset:51200
	ds_read_b128 v[188:191], v163 offset:52224
	ds_read_b128 v[192:195], v163 offset:53248
	ds_read_b128 v[196:199], v163 offset:54272
	ds_read_b128 v[200:203], v163 offset:55296
	ds_read_b128 v[204:207], v163 offset:56320
	buffer_load_dwordx4 v160, s[4:7], s94 offen lds
	s_add_i32 s94, s93, 0x10080
	s_mov_b32 m0, s75
	s_add_i32 s91, s91, 0x10080
	buffer_load_dwordx4 v160, s[4:7], s94 offen lds
	s_add_i32 s94, s93, 0x20080
	s_mov_b32 m0, s78
	s_add_i32 s93, s93, 0x30080
	buffer_load_dwordx4 v160, s[4:7], s94 offen lds
	s_mov_b32 m0, s79
	s_nop 0
	buffer_load_dwordx4 v160, s[4:7], s93 offen lds
	s_mov_b32 m0, s76
	s_nop 0
	buffer_load_dwordx4 v161, s[12:15], s92 offen lds
	s_mov_b32 m0, s77
	s_nop 0
	buffer_load_dwordx4 v161, s[12:15], s91 offen lds
	s_waitcnt vmcnt(8)
	s_waitcnt lgkmcnt(0)
	s_setprio 1
	s_barrier
	v_mfma_f32_16x16x32_bf16 v[62:65], v[130:133], v[176:179], v[62:65]
	v_mfma_f32_16x16x32_bf16 v[62:65], v[134:137], v[180:183], v[62:65]
	v_mfma_f32_16x16x32_bf16 v[58:61], v[138:141], v[176:179], v[58:61]
	v_mfma_f32_16x16x32_bf16 v[58:61], v[142:145], v[180:183], v[58:61]
	v_mfma_f32_16x16x32_bf16 v[54:57], v[154:157], v[176:179], v[54:57]
	v_mfma_f32_16x16x32_bf16 v[54:57], v[164:167], v[180:183], v[54:57]
	v_mfma_f32_16x16x32_bf16 v[50:53], v[168:171], v[176:179], v[50:53]
	v_mfma_f32_16x16x32_bf16 v[50:53], v[172:175], v[180:183], v[50:53]
	v_mfma_f32_16x16x32_bf16 v[34:37], v[168:171], v[184:187], v[34:37]
	v_mfma_f32_16x16x32_bf16 v[34:37], v[172:175], v[188:191], v[34:37]
	v_mfma_f32_16x16x32_bf16 v[38:41], v[154:157], v[184:187], v[38:41]
	v_mfma_f32_16x16x32_bf16 v[38:41], v[164:167], v[188:191], v[38:41]
	v_mfma_f32_16x16x32_bf16 v[42:45], v[138:141], v[184:187], v[42:45]
	v_mfma_f32_16x16x32_bf16 v[42:45], v[142:145], v[188:191], v[42:45]
	v_mfma_f32_16x16x32_bf16 v[46:49], v[130:133], v[184:187], v[46:49]
	v_mfma_f32_16x16x32_bf16 v[46:49], v[134:137], v[188:191], v[46:49]
	v_mfma_f32_16x16x32_bf16 v[30:33], v[130:133], v[192:195], v[30:33]
	v_mfma_f32_16x16x32_bf16 v[30:33], v[134:137], v[196:199], v[30:33]
	v_mfma_f32_16x16x32_bf16 v[26:29], v[138:141], v[192:195], v[26:29]
	v_mfma_f32_16x16x32_bf16 v[26:29], v[142:145], v[196:199], v[26:29]
	v_mfma_f32_16x16x32_bf16 v[22:25], v[154:157], v[192:195], v[22:25]
	v_mfma_f32_16x16x32_bf16 v[22:25], v[164:167], v[196:199], v[22:25]
	v_mfma_f32_16x16x32_bf16 v[18:21], v[168:171], v[192:195], v[18:21]
	v_mfma_f32_16x16x32_bf16 v[18:21], v[172:175], v[196:199], v[18:21]
	v_mfma_f32_16x16x32_bf16 v[2:5], v[168:171], v[200:203], v[2:5]
	v_mfma_f32_16x16x32_bf16 v[2:5], v[172:175], v[204:207], v[2:5]
	v_mfma_f32_16x16x32_bf16 v[6:9], v[154:157], v[200:203], v[6:9]
	v_mfma_f32_16x16x32_bf16 v[6:9], v[164:167], v[204:207], v[6:9]
	v_mfma_f32_16x16x32_bf16 v[10:13], v[138:141], v[200:203], v[10:13]
	v_mfma_f32_16x16x32_bf16 v[10:13], v[142:145], v[204:207], v[10:13]
	v_mfma_f32_16x16x32_bf16 v[14:17], v[130:133], v[200:203], v[14:17]
	v_mfma_f32_16x16x32_bf16 v[14:17], v[134:137], v[204:207], v[14:17]
	s_setprio 0
	s_barrier
	s_add_i32 s89, s89, 2
	s_cmp_ge_i32 s89, s63
	s_mov_b32 s6, s90
	s_cbranch_scc0 .LBB0_1020
	s_and_b64 vcc, exec, s[54:55]
	s_cbranch_vccz .LBB0_1023

.LBB0_1035:
	ds_read_b128 v[140:143], v134
	ds_read_b128 v[148:151], v134 offset:1024
	ds_read_b128 v[152:155], v134 offset:2048
	ds_read_b128 v[156:159], v134 offset:3072
	ds_read_b128 v[160:163], v135
	ds_read_b128 v[164:167], v135 offset:1024
	ds_read_b128 v[168:171], v135 offset:2048
	ds_read_b128 v[172:175], v135 offset:3072
	s_add_i32 s73, s70, 0xfffb8080
	s_cmp_eq_u32 s53, s72
	s_cselect_b32 s73, s68, s73
	s_cselect_b32 s75, s69, s71
	s_add_i32 s74, s73, 0x80
	s_add_i32 s76, s70, 0xfffe8000
	s_mov_b32 m0, s54
	ds_read_b128 v[176:179], v136
	ds_read_b128 v[180:183], v136 offset:1024
	ds_read_b128 v[184:187], v136 offset:2048
	ds_read_b128 v[188:191], v136 offset:3072
	ds_read_b128 v[192:195], v136 offset:4096
	ds_read_b128 v[196:199], v136 offset:5120
	ds_read_b128 v[200:203], v136 offset:6144
	ds_read_b128 v[204:207], v136 offset:7168
	buffer_load_dwordx4 v132, s[12:15], s76 offen lds
	s_mov_b32 m0, s55
	s_nop 0
	buffer_load_dwordx4 v132, s[12:15], s70 offen lds
	s_waitcnt vmcnt(8)
	s_waitcnt lgkmcnt(0)
	s_setprio 1
	s_barrier
	v_mfma_f32_16x16x32_bf16 v[126:129], v[140:143], v[176:179], v[126:129]
	v_mfma_f32_16x16x32_bf16 v[126:129], v[148:151], v[180:183], v[126:129]
	v_mfma_f32_16x16x32_bf16 v[122:125], v[152:155], v[176:179], v[122:125]
	v_mfma_f32_16x16x32_bf16 v[122:125], v[156:159], v[180:183], v[122:125]
	v_mfma_f32_16x16x32_bf16 v[118:121], v[160:163], v[176:179], v[118:121]
	v_mfma_f32_16x16x32_bf16 v[118:121], v[164:167], v[180:183], v[118:121]
	v_mfma_f32_16x16x32_bf16 v[114:117], v[168:171], v[176:179], v[114:117]
	v_mfma_f32_16x16x32_bf16 v[114:117], v[172:175], v[180:183], v[114:117]
	v_mfma_f32_16x16x32_bf16 v[98:101], v[168:171], v[184:187], v[98:101]
	v_mfma_f32_16x16x32_bf16 v[98:101], v[172:175], v[188:191], v[98:101]
	v_mfma_f32_16x16x32_bf16 v[102:105], v[160:163], v[184:187], v[102:105]
	v_mfma_f32_16x16x32_bf16 v[102:105], v[164:167], v[188:191], v[102:105]
	v_mfma_f32_16x16x32_bf16 v[106:109], v[152:155], v[184:187], v[106:109]
	v_mfma_f32_16x16x32_bf16 v[106:109], v[156:159], v[188:191], v[106:109]
	v_mfma_f32_16x16x32_bf16 v[110:113], v[140:143], v[184:187], v[110:113]
	v_mfma_f32_16x16x32_bf16 v[110:113], v[148:151], v[188:191], v[110:113]
	v_mfma_f32_16x16x32_bf16 v[94:97], v[140:143], v[192:195], v[94:97]
	v_mfma_f32_16x16x32_bf16 v[94:97], v[148:151], v[196:199], v[94:97]
	v_mfma_f32_16x16x32_bf16 v[90:93], v[152:155], v[192:195], v[90:93]
	v_mfma_f32_16x16x32_bf16 v[90:93], v[156:159], v[196:199], v[90:93]
	v_mfma_f32_16x16x32_bf16 v[86:89], v[160:163], v[192:195], v[86:89]
	v_mfma_f32_16x16x32_bf16 v[86:89], v[164:167], v[196:199], v[86:89]
	v_mfma_f32_16x16x32_bf16 v[82:85], v[168:171], v[192:195], v[82:85]
	v_mfma_f32_16x16x32_bf16 v[82:85], v[172:175], v[196:199], v[82:85]
	v_mfma_f32_16x16x32_bf16 v[66:69], v[168:171], v[200:203], v[66:69]
	v_mfma_f32_16x16x32_bf16 v[66:69], v[172:175], v[204:207], v[66:69]
	v_mfma_f32_16x16x32_bf16 v[70:73], v[160:163], v[200:203], v[70:73]
	v_mfma_f32_16x16x32_bf16 v[70:73], v[164:167], v[204:207], v[70:73]
	v_mfma_f32_16x16x32_bf16 v[74:77], v[152:155], v[200:203], v[74:77]
	v_mfma_f32_16x16x32_bf16 v[74:77], v[156:159], v[204:207], v[74:77]
	v_mfma_f32_16x16x32_bf16 v[78:81], v[140:143], v[200:203], v[78:81]
	v_mfma_f32_16x16x32_bf16 v[78:81], v[148:151], v[204:207], v[78:81]
	s_setprio 0
	s_barrier
	s_mov_b32 m0, s30
	ds_read_b128 v[176:179], v136 offset:16384
	ds_read_b128 v[180:183], v136 offset:17408
	ds_read_b128 v[184:187], v136 offset:18432
	ds_read_b128 v[188:191], v136 offset:19456
	ds_read_b128 v[192:195], v136 offset:20480
	ds_read_b128 v[196:199], v136 offset:21504
	ds_read_b128 v[200:203], v136 offset:22528
	ds_read_b128 v[204:207], v136 offset:23552
	buffer_load_dwordx4 v133, s[16:19], s75 offen lds
	s_add_i32 s76, s75, 0x200000
	s_mov_b32 m0, s31
	s_nop 0
	buffer_load_dwordx4 v133, s[16:19], s76 offen lds
	s_add_i32 s76, s75, 0x400000
	s_mov_b32 m0, s35
	s_nop 0
	buffer_load_dwordx4 v133, s[16:19], s76 offen lds
	s_add_i32 s76, s75, 0x600000
	s_mov_b32 m0, s42
	s_nop 0
	buffer_load_dwordx4 v133, s[16:19], s76 offen lds
	s_mov_b32 m0, s27
	s_add_i32 s76, s73, 0x18000
	buffer_load_dwordx4 v132, s[12:15], s73 offen lds
	s_mov_b32 m0, s43
	s_nop 0
	buffer_load_dwordx4 v132, s[12:15], s76 offen lds
	s_waitcnt vmcnt(8)
	s_waitcnt lgkmcnt(0)
	s_setprio 1
	s_barrier
	v_mfma_f32_16x16x32_bf16 v[62:65], v[140:143], v[176:179], v[62:65]
	v_mfma_f32_16x16x32_bf16 v[62:65], v[148:151], v[180:183], v[62:65]
	v_mfma_f32_16x16x32_bf16 v[58:61], v[152:155], v[176:179], v[58:61]
	v_mfma_f32_16x16x32_bf16 v[58:61], v[156:159], v[180:183], v[58:61]
	v_mfma_f32_16x16x32_bf16 v[54:57], v[160:163], v[176:179], v[54:57]
	v_mfma_f32_16x16x32_bf16 v[54:57], v[164:167], v[180:183], v[54:57]
	v_mfma_f32_16x16x32_bf16 v[50:53], v[168:171], v[176:179], v[50:53]
	v_mfma_f32_16x16x32_bf16 v[50:53], v[172:175], v[180:183], v[50:53]
	v_mfma_f32_16x16x32_bf16 v[34:37], v[168:171], v[184:187], v[34:37]
	v_mfma_f32_16x16x32_bf16 v[34:37], v[172:175], v[188:191], v[34:37]
	v_mfma_f32_16x16x32_bf16 v[38:41], v[160:163], v[184:187], v[38:41]
	v_mfma_f32_16x16x32_bf16 v[38:41], v[164:167], v[188:191], v[38:41]
	v_mfma_f32_16x16x32_bf16 v[42:45], v[152:155], v[184:187], v[42:45]
	v_mfma_f32_16x16x32_bf16 v[42:45], v[156:159], v[188:191], v[42:45]
	v_mfma_f32_16x16x32_bf16 v[46:49], v[140:143], v[184:187], v[46:49]
	v_mfma_f32_16x16x32_bf16 v[46:49], v[148:151], v[188:191], v[46:49]
	v_mfma_f32_16x16x32_bf16 v[30:33], v[140:143], v[192:195], v[30:33]
	v_mfma_f32_16x16x32_bf16 v[30:33], v[148:151], v[196:199], v[30:33]
	v_mfma_f32_16x16x32_bf16 v[26:29], v[152:155], v[192:195], v[26:29]
	v_mfma_f32_16x16x32_bf16 v[26:29], v[156:159], v[196:199], v[26:29]
	v_mfma_f32_16x16x32_bf16 v[22:25], v[160:163], v[192:195], v[22:25]
	v_mfma_f32_16x16x32_bf16 v[22:25], v[164:167], v[196:199], v[22:25]
	v_mfma_f32_16x16x32_bf16 v[18:21], v[168:171], v[192:195], v[18:21]
	v_mfma_f32_16x16x32_bf16 v[18:21], v[172:175], v[196:199], v[18:21]
	v_mfma_f32_16x16x32_bf16 v[2:5], v[168:171], v[200:203], v[2:5]
	v_mfma_f32_16x16x32_bf16 v[2:5], v[172:175], v[204:207], v[2:5]
	v_mfma_f32_16x16x32_bf16 v[6:9], v[160:163], v[200:203], v[6:9]
	v_mfma_f32_16x16x32_bf16 v[6:9], v[164:167], v[204:207], v[6:9]
	v_mfma_f32_16x16x32_bf16 v[10:13], v[152:155], v[200:203], v[10:13]
	v_mfma_f32_16x16x32_bf16 v[10:13], v[156:159], v[204:207], v[10:13]
	v_mfma_f32_16x16x32_bf16 v[14:17], v[140:143], v[200:203], v[14:17]
	v_mfma_f32_16x16x32_bf16 v[14:17], v[148:151], v[204:207], v[14:17]
	s_setprio 0
	s_barrier
	ds_read_b128 v[140:143], v137
	ds_read_b128 v[148:151], v137 offset:1024
	ds_read_b128 v[152:155], v137 offset:2048
	ds_read_b128 v[156:159], v137 offset:3072
	ds_read_b128 v[160:163], v138
	ds_read_b128 v[164:167], v138 offset:1024
	ds_read_b128 v[168:171], v138 offset:2048
	ds_read_b128 v[172:175], v138 offset:3072
	s_mov_b32 m0, s44
	s_add_i32 s76, s73, 0x30000
	ds_read_b128 v[176:179], v136 offset:32768
	ds_read_b128 v[180:183], v136 offset:33792
	ds_read_b128 v[184:187], v136 offset:34816
	ds_read_b128 v[188:191], v136 offset:35840
	ds_read_b128 v[192:195], v136 offset:36864
	ds_read_b128 v[196:199], v136 offset:37888
	ds_read_b128 v[200:203], v136 offset:38912
	ds_read_b128 v[204:207], v136 offset:39936
	buffer_load_dwordx4 v132, s[12:15], s76 offen lds
	s_add_i32 s76, s73, 0x48000
	s_mov_b32 m0, s45
	s_nop 0
	buffer_load_dwordx4 v132, s[12:15], s76 offen lds
	s_waitcnt vmcnt(8)
	s_waitcnt lgkmcnt(0)
	s_setprio 1
	s_barrier
	v_mfma_f32_16x16x32_bf16 v[126:129], v[140:143], v[176:179], v[126:129]
	v_mfma_f32_16x16x32_bf16 v[126:129], v[148:151], v[180:183], v[126:129]
	v_mfma_f32_16x16x32_bf16 v[122:125], v[152:155], v[176:179], v[122:125]
	v_mfma_f32_16x16x32_bf16 v[122:125], v[156:159], v[180:183], v[122:125]
	v_mfma_f32_16x16x32_bf16 v[118:121], v[160:163], v[176:179], v[118:121]
	v_mfma_f32_16x16x32_bf16 v[118:121], v[164:167], v[180:183], v[118:121]
	v_mfma_f32_16x16x32_bf16 v[114:117], v[168:171], v[176:179], v[114:117]
	v_mfma_f32_16x16x32_bf16 v[114:117], v[172:175], v[180:183], v[114:117]
	v_mfma_f32_16x16x32_bf16 v[98:101], v[168:171], v[184:187], v[98:101]
	v_mfma_f32_16x16x32_bf16 v[98:101], v[172:175], v[188:191], v[98:101]
	v_mfma_f32_16x16x32_bf16 v[102:105], v[160:163], v[184:187], v[102:105]
	v_mfma_f32_16x16x32_bf16 v[102:105], v[164:167], v[188:191], v[102:105]
	v_mfma_f32_16x16x32_bf16 v[106:109], v[152:155], v[184:187], v[106:109]
	v_mfma_f32_16x16x32_bf16 v[106:109], v[156:159], v[188:191], v[106:109]
	v_mfma_f32_16x16x32_bf16 v[110:113], v[140:143], v[184:187], v[110:113]
	v_mfma_f32_16x16x32_bf16 v[110:113], v[148:151], v[188:191], v[110:113]
	v_mfma_f32_16x16x32_bf16 v[94:97], v[140:143], v[192:195], v[94:97]
	v_mfma_f32_16x16x32_bf16 v[94:97], v[148:151], v[196:199], v[94:97]
	v_mfma_f32_16x16x32_bf16 v[90:93], v[152:155], v[192:195], v[90:93]
	v_mfma_f32_16x16x32_bf16 v[90:93], v[156:159], v[196:199], v[90:93]
	v_mfma_f32_16x16x32_bf16 v[86:89], v[160:163], v[192:195], v[86:89]
	v_mfma_f32_16x16x32_bf16 v[86:89], v[164:167], v[196:199], v[86:89]
	v_mfma_f32_16x16x32_bf16 v[82:85], v[168:171], v[192:195], v[82:85]
	v_mfma_f32_16x16x32_bf16 v[82:85], v[172:175], v[196:199], v[82:85]
	v_mfma_f32_16x16x32_bf16 v[66:69], v[168:171], v[200:203], v[66:69]
	v_mfma_f32_16x16x32_bf16 v[66:69], v[172:175], v[204:207], v[66:69]
	v_mfma_f32_16x16x32_bf16 v[70:73], v[160:163], v[200:203], v[70:73]
	v_mfma_f32_16x16x32_bf16 v[70:73], v[164:167], v[204:207], v[70:73]
	v_mfma_f32_16x16x32_bf16 v[74:77], v[152:155], v[200:203], v[74:77]
	v_mfma_f32_16x16x32_bf16 v[74:77], v[156:159], v[204:207], v[74:77]
	v_mfma_f32_16x16x32_bf16 v[78:81], v[140:143], v[200:203], v[78:81]
	v_mfma_f32_16x16x32_bf16 v[78:81], v[148:151], v[204:207], v[78:81]
	s_setprio 0
	s_barrier
	s_mov_b32 m0, s46
	s_add_i32 s76, s75, 0x80
	ds_read_b128 v[176:179], v136 offset:49152
	ds_read_b128 v[180:183], v136 offset:50176
	ds_read_b128 v[184:187], v136 offset:51200
	ds_read_b128 v[188:191], v136 offset:52224
	ds_read_b128 v[192:195], v136 offset:53248
	ds_read_b128 v[196:199], v136 offset:54272
	ds_read_b128 v[200:203], v136 offset:55296
	ds_read_b128 v[204:207], v136 offset:56320
	buffer_load_dwordx4 v133, s[16:19], s76 offen lds
	s_add_i32 s76, s75, 0x200080
	s_mov_b32 m0, s47
	s_add_i32 s73, s73, 0x18080
	buffer_load_dwordx4 v133, s[16:19], s76 offen lds
	s_add_i32 s76, s75, 0x400080
	s_mov_b32 m0, s50
	s_add_i32 s75, s75, 0x600080
	buffer_load_dwordx4 v133, s[16:19], s76 offen lds
	s_mov_b32 m0, s51
	s_nop 0
	buffer_load_dwordx4 v133, s[16:19], s75 offen lds
	s_mov_b32 m0, s48
	s_nop 0
	buffer_load_dwordx4 v132, s[12:15], s74 offen lds
	s_mov_b32 m0, s49
	s_nop 0
	buffer_load_dwordx4 v132, s[12:15], s73 offen lds
	s_waitcnt vmcnt(8)
	s_waitcnt lgkmcnt(0)
	s_setprio 1
	s_barrier
	v_mfma_f32_16x16x32_bf16 v[62:65], v[140:143], v[176:179], v[62:65]
	v_mfma_f32_16x16x32_bf16 v[62:65], v[148:151], v[180:183], v[62:65]
	v_mfma_f32_16x16x32_bf16 v[58:61], v[152:155], v[176:179], v[58:61]
	v_mfma_f32_16x16x32_bf16 v[58:61], v[156:159], v[180:183], v[58:61]
	v_mfma_f32_16x16x32_bf16 v[54:57], v[160:163], v[176:179], v[54:57]
	v_mfma_f32_16x16x32_bf16 v[54:57], v[164:167], v[180:183], v[54:57]
	v_mfma_f32_16x16x32_bf16 v[50:53], v[168:171], v[176:179], v[50:53]
	v_mfma_f32_16x16x32_bf16 v[50:53], v[172:175], v[180:183], v[50:53]
	v_mfma_f32_16x16x32_bf16 v[34:37], v[168:171], v[184:187], v[34:37]
	v_mfma_f32_16x16x32_bf16 v[34:37], v[172:175], v[188:191], v[34:37]
	v_mfma_f32_16x16x32_bf16 v[38:41], v[160:163], v[184:187], v[38:41]
	v_mfma_f32_16x16x32_bf16 v[38:41], v[164:167], v[188:191], v[38:41]
	v_mfma_f32_16x16x32_bf16 v[42:45], v[152:155], v[184:187], v[42:45]
	v_mfma_f32_16x16x32_bf16 v[42:45], v[156:159], v[188:191], v[42:45]
	v_mfma_f32_16x16x32_bf16 v[46:49], v[140:143], v[184:187], v[46:49]
	v_mfma_f32_16x16x32_bf16 v[46:49], v[148:151], v[188:191], v[46:49]
	v_mfma_f32_16x16x32_bf16 v[30:33], v[140:143], v[192:195], v[30:33]
	v_mfma_f32_16x16x32_bf16 v[30:33], v[148:151], v[196:199], v[30:33]
	v_mfma_f32_16x16x32_bf16 v[26:29], v[152:155], v[192:195], v[26:29]
	v_mfma_f32_16x16x32_bf16 v[26:29], v[156:159], v[196:199], v[26:29]
	v_mfma_f32_16x16x32_bf16 v[22:25], v[160:163], v[192:195], v[22:25]
	v_mfma_f32_16x16x32_bf16 v[22:25], v[164:167], v[196:199], v[22:25]
	v_mfma_f32_16x16x32_bf16 v[18:21], v[168:171], v[192:195], v[18:21]
	v_mfma_f32_16x16x32_bf16 v[18:21], v[172:175], v[196:199], v[18:21]
	v_mfma_f32_16x16x32_bf16 v[2:5], v[168:171], v[200:203], v[2:5]
	v_mfma_f32_16x16x32_bf16 v[2:5], v[172:175], v[204:207], v[2:5]
	v_mfma_f32_16x16x32_bf16 v[6:9], v[160:163], v[200:203], v[6:9]
	v_mfma_f32_16x16x32_bf16 v[6:9], v[164:167], v[204:207], v[6:9]
	v_mfma_f32_16x16x32_bf16 v[10:13], v[152:155], v[200:203], v[10:13]
	v_mfma_f32_16x16x32_bf16 v[10:13], v[156:159], v[204:207], v[10:13]
	v_mfma_f32_16x16x32_bf16 v[14:17], v[140:143], v[200:203], v[14:17]
	v_mfma_f32_16x16x32_bf16 v[14:17], v[148:151], v[204:207], v[14:17]
	s_setprio 0
	s_barrier
	s_add_i32 s72, s72, 2
	s_addk_i32 s70, 0x100
	s_addk_i32 s71, 0x100
	s_cmp_ge_i32 s72, s21
	s_cbranch_scc0 .LBB0_1035

.LBB0_1050:
	ds_read_b128 v[132:135], v142
	ds_read_b128 v[136:139], v142 offset:1024
	ds_read_b128 v[148:151], v142 offset:2048
	ds_read_b128 v[152:155], v142 offset:3072
	ds_read_b128 v[156:159], v143
	ds_read_b128 v[160:163], v143 offset:1024
	ds_read_b128 v[164:167], v143 offset:2048
	ds_read_b128 v[168:171], v143 offset:3072
	s_add_i32 s18, s61, 0xfff40080
	s_cmp_eq_u32 s54, s62
	s_cselect_b32 s64, s35, s18
	s_add_i32 s63, s64, 0x80
	s_add_i32 s18, s61, 0xfffc0000
	s_mov_b32 m0, s55
	ds_read_b128 v[172:175], v144
	ds_read_b128 v[176:179], v144 offset:1024
	ds_read_b128 v[180:183], v144 offset:2048
	ds_read_b128 v[184:187], v144 offset:3072
	ds_read_b128 v[188:191], v144 offset:4096
	ds_read_b128 v[192:195], v144 offset:5120
	ds_read_b128 v[196:199], v144 offset:6144
	ds_read_b128 v[200:203], v144 offset:7168
	buffer_load_dwordx4 v140, s[12:15], s18 offen lds
	s_mov_b32 m0, s56
	s_nop 0
	buffer_load_dwordx4 v140, s[12:15], s61 offen lds
	s_waitcnt vmcnt(8)
	s_waitcnt lgkmcnt(0)
	s_setprio 1
	s_barrier
	v_mfma_f32_16x16x32_bf16 v[126:129], v[132:135], v[172:175], v[126:129]
	v_mfma_f32_16x16x32_bf16 v[126:129], v[136:139], v[176:179], v[126:129]
	v_mfma_f32_16x16x32_bf16 v[122:125], v[148:151], v[172:175], v[122:125]
	v_mfma_f32_16x16x32_bf16 v[122:125], v[152:155], v[176:179], v[122:125]
	v_mfma_f32_16x16x32_bf16 v[118:121], v[156:159], v[172:175], v[118:121]
	v_mfma_f32_16x16x32_bf16 v[118:121], v[160:163], v[176:179], v[118:121]
	v_mfma_f32_16x16x32_bf16 v[114:117], v[164:167], v[172:175], v[114:117]
	v_mfma_f32_16x16x32_bf16 v[114:117], v[168:171], v[176:179], v[114:117]
	v_mfma_f32_16x16x32_bf16 v[98:101], v[164:167], v[180:183], v[98:101]
	v_mfma_f32_16x16x32_bf16 v[98:101], v[168:171], v[184:187], v[98:101]
	v_mfma_f32_16x16x32_bf16 v[102:105], v[156:159], v[180:183], v[102:105]
	v_mfma_f32_16x16x32_bf16 v[102:105], v[160:163], v[184:187], v[102:105]
	v_mfma_f32_16x16x32_bf16 v[106:109], v[148:151], v[180:183], v[106:109]
	v_mfma_f32_16x16x32_bf16 v[106:109], v[152:155], v[184:187], v[106:109]
	v_mfma_f32_16x16x32_bf16 v[110:113], v[132:135], v[180:183], v[110:113]
	v_mfma_f32_16x16x32_bf16 v[110:113], v[136:139], v[184:187], v[110:113]
	v_mfma_f32_16x16x32_bf16 v[94:97], v[132:135], v[188:191], v[94:97]
	v_mfma_f32_16x16x32_bf16 v[94:97], v[136:139], v[192:195], v[94:97]
	v_mfma_f32_16x16x32_bf16 v[90:93], v[148:151], v[188:191], v[90:93]
	v_mfma_f32_16x16x32_bf16 v[90:93], v[152:155], v[192:195], v[90:93]
	v_mfma_f32_16x16x32_bf16 v[86:89], v[156:159], v[188:191], v[86:89]
	v_mfma_f32_16x16x32_bf16 v[86:89], v[160:163], v[192:195], v[86:89]
	v_mfma_f32_16x16x32_bf16 v[82:85], v[164:167], v[188:191], v[82:85]
	v_mfma_f32_16x16x32_bf16 v[82:85], v[168:171], v[192:195], v[82:85]
	v_mfma_f32_16x16x32_bf16 v[66:69], v[164:167], v[196:199], v[66:69]
	v_mfma_f32_16x16x32_bf16 v[66:69], v[168:171], v[200:203], v[66:69]
	v_mfma_f32_16x16x32_bf16 v[70:73], v[156:159], v[196:199], v[70:73]
	v_mfma_f32_16x16x32_bf16 v[70:73], v[160:163], v[200:203], v[70:73]
	v_mfma_f32_16x16x32_bf16 v[74:77], v[148:151], v[196:199], v[74:77]
	v_mfma_f32_16x16x32_bf16 v[74:77], v[152:155], v[200:203], v[74:77]
	v_mfma_f32_16x16x32_bf16 v[78:81], v[132:135], v[196:199], v[78:81]
	v_mfma_f32_16x16x32_bf16 v[78:81], v[136:139], v[200:203], v[78:81]
	s_setprio 0
	s_barrier
	s_mov_b32 m0, s25
	s_mov_b32 s18, s14
	s_mov_b32 s19, s15
	ds_read_b128 v[172:175], v144 offset:16384
	ds_read_b128 v[176:179], v144 offset:17408
	ds_read_b128 v[180:183], v144 offset:18432
	ds_read_b128 v[184:187], v144 offset:19456
	ds_read_b128 v[188:191], v144 offset:20480
	ds_read_b128 v[192:195], v144 offset:21504
	ds_read_b128 v[196:199], v144 offset:22528
	ds_read_b128 v[200:203], v144 offset:23552
	buffer_load_dwordx4 v141, s[16:19], s64 offen lds
	s_add_i32 s65, s64, 0x40000
	s_mov_b32 m0, s27
	s_add_i32 s66, s64, 0x80000
	buffer_load_dwordx4 v141, s[16:19], s65 offen lds
	s_mov_b32 m0, s30
	s_add_i32 s67, s64, 0xc0000
	buffer_load_dwordx4 v141, s[16:19], s66 offen lds
	s_mov_b32 m0, s31
	s_nop 0
	buffer_load_dwordx4 v141, s[16:19], s67 offen lds
	s_mov_b32 m0, s21
	s_nop 0
	buffer_load_dwordx4 v140, s[12:15], s64 offen lds
	s_mov_b32 m0, s38
	s_nop 0
	buffer_load_dwordx4 v140, s[12:15], s65 offen lds
	s_waitcnt vmcnt(8)
	s_waitcnt lgkmcnt(0)
	s_setprio 1
	s_barrier
	v_mfma_f32_16x16x32_bf16 v[62:65], v[132:135], v[172:175], v[62:65]
	v_mfma_f32_16x16x32_bf16 v[62:65], v[136:139], v[176:179], v[62:65]
	v_mfma_f32_16x16x32_bf16 v[58:61], v[148:151], v[172:175], v[58:61]
	v_mfma_f32_16x16x32_bf16 v[58:61], v[152:155], v[176:179], v[58:61]
	v_mfma_f32_16x16x32_bf16 v[54:57], v[156:159], v[172:175], v[54:57]
	v_mfma_f32_16x16x32_bf16 v[54:57], v[160:163], v[176:179], v[54:57]
	v_mfma_f32_16x16x32_bf16 v[50:53], v[164:167], v[172:175], v[50:53]
	v_mfma_f32_16x16x32_bf16 v[50:53], v[168:171], v[176:179], v[50:53]
	v_mfma_f32_16x16x32_bf16 v[34:37], v[164:167], v[180:183], v[34:37]
	v_mfma_f32_16x16x32_bf16 v[34:37], v[168:171], v[184:187], v[34:37]
	v_mfma_f32_16x16x32_bf16 v[38:41], v[156:159], v[180:183], v[38:41]
	v_mfma_f32_16x16x32_bf16 v[38:41], v[160:163], v[184:187], v[38:41]
	v_mfma_f32_16x16x32_bf16 v[42:45], v[148:151], v[180:183], v[42:45]
	v_mfma_f32_16x16x32_bf16 v[42:45], v[152:155], v[184:187], v[42:45]
	v_mfma_f32_16x16x32_bf16 v[46:49], v[132:135], v[180:183], v[46:49]
	v_mfma_f32_16x16x32_bf16 v[46:49], v[136:139], v[184:187], v[46:49]
	v_mfma_f32_16x16x32_bf16 v[30:33], v[132:135], v[188:191], v[30:33]
	v_mfma_f32_16x16x32_bf16 v[30:33], v[136:139], v[192:195], v[30:33]
	v_mfma_f32_16x16x32_bf16 v[26:29], v[148:151], v[188:191], v[26:29]
	v_mfma_f32_16x16x32_bf16 v[26:29], v[152:155], v[192:195], v[26:29]
	v_mfma_f32_16x16x32_bf16 v[22:25], v[156:159], v[188:191], v[22:25]
	v_mfma_f32_16x16x32_bf16 v[22:25], v[160:163], v[192:195], v[22:25]
	v_mfma_f32_16x16x32_bf16 v[18:21], v[164:167], v[188:191], v[18:21]
	v_mfma_f32_16x16x32_bf16 v[18:21], v[168:171], v[192:195], v[18:21]
	v_mfma_f32_16x16x32_bf16 v[2:5], v[164:167], v[196:199], v[2:5]
	v_mfma_f32_16x16x32_bf16 v[2:5], v[168:171], v[200:203], v[2:5]
	v_mfma_f32_16x16x32_bf16 v[6:9], v[156:159], v[196:199], v[6:9]
	v_mfma_f32_16x16x32_bf16 v[6:9], v[160:163], v[200:203], v[6:9]
	v_mfma_f32_16x16x32_bf16 v[10:13], v[148:151], v[196:199], v[10:13]
	v_mfma_f32_16x16x32_bf16 v[10:13], v[152:155], v[200:203], v[10:13]
	v_mfma_f32_16x16x32_bf16 v[14:17], v[132:135], v[196:199], v[14:17]
	v_mfma_f32_16x16x32_bf16 v[14:17], v[136:139], v[200:203], v[14:17]
	s_setprio 0
	s_barrier
	ds_read_b128 v[132:135], v145
	ds_read_b128 v[136:139], v145 offset:1024
	ds_read_b128 v[148:151], v145 offset:2048
	ds_read_b128 v[152:155], v145 offset:3072
	ds_read_b128 v[156:159], v147
	ds_read_b128 v[160:163], v147 offset:1024
	ds_read_b128 v[164:167], v147 offset:2048
	ds_read_b128 v[168:171], v147 offset:3072
	s_mov_b32 m0, s39
	ds_read_b128 v[172:175], v144 offset:32768
	ds_read_b128 v[176:179], v144 offset:33792
	ds_read_b128 v[180:183], v144 offset:34816
	ds_read_b128 v[184:187], v144 offset:35840
	ds_read_b128 v[188:191], v144 offset:36864
	ds_read_b128 v[192:195], v144 offset:37888
	ds_read_b128 v[196:199], v144 offset:38912
	ds_read_b128 v[200:203], v144 offset:39936
	buffer_load_dwordx4 v140, s[12:15], s66 offen lds
	s_mov_b32 m0, s40
	s_nop 0
	buffer_load_dwordx4 v140, s[12:15], s67 offen lds
	s_waitcnt vmcnt(8)
	s_waitcnt lgkmcnt(0)
	s_setprio 1
	s_barrier
	v_mfma_f32_16x16x32_bf16 v[126:129], v[132:135], v[172:175], v[126:129]
	v_mfma_f32_16x16x32_bf16 v[126:129], v[136:139], v[176:179], v[126:129]
	v_mfma_f32_16x16x32_bf16 v[122:125], v[148:151], v[172:175], v[122:125]
	v_mfma_f32_16x16x32_bf16 v[122:125], v[152:155], v[176:179], v[122:125]
	v_mfma_f32_16x16x32_bf16 v[118:121], v[156:159], v[172:175], v[118:121]
	v_mfma_f32_16x16x32_bf16 v[118:121], v[160:163], v[176:179], v[118:121]
	v_mfma_f32_16x16x32_bf16 v[114:117], v[164:167], v[172:175], v[114:117]
	v_mfma_f32_16x16x32_bf16 v[114:117], v[168:171], v[176:179], v[114:117]
	v_mfma_f32_16x16x32_bf16 v[98:101], v[164:167], v[180:183], v[98:101]
	v_mfma_f32_16x16x32_bf16 v[98:101], v[168:171], v[184:187], v[98:101]
	v_mfma_f32_16x16x32_bf16 v[102:105], v[156:159], v[180:183], v[102:105]
	v_mfma_f32_16x16x32_bf16 v[102:105], v[160:163], v[184:187], v[102:105]
	v_mfma_f32_16x16x32_bf16 v[106:109], v[148:151], v[180:183], v[106:109]
	v_mfma_f32_16x16x32_bf16 v[106:109], v[152:155], v[184:187], v[106:109]
	v_mfma_f32_16x16x32_bf16 v[110:113], v[132:135], v[180:183], v[110:113]
	v_mfma_f32_16x16x32_bf16 v[110:113], v[136:139], v[184:187], v[110:113]
	v_mfma_f32_16x16x32_bf16 v[94:97], v[132:135], v[188:191], v[94:97]
	v_mfma_f32_16x16x32_bf16 v[94:97], v[136:139], v[192:195], v[94:97]
	v_mfma_f32_16x16x32_bf16 v[90:93], v[148:151], v[188:191], v[90:93]
	v_mfma_f32_16x16x32_bf16 v[90:93], v[152:155], v[192:195], v[90:93]
	v_mfma_f32_16x16x32_bf16 v[86:89], v[156:159], v[188:191], v[86:89]
	v_mfma_f32_16x16x32_bf16 v[86:89], v[160:163], v[192:195], v[86:89]
	v_mfma_f32_16x16x32_bf16 v[82:85], v[164:167], v[188:191], v[82:85]
	v_mfma_f32_16x16x32_bf16 v[82:85], v[168:171], v[192:195], v[82:85]
	v_mfma_f32_16x16x32_bf16 v[66:69], v[164:167], v[196:199], v[66:69]
	v_mfma_f32_16x16x32_bf16 v[66:69], v[168:171], v[200:203], v[66:69]
	v_mfma_f32_16x16x32_bf16 v[70:73], v[156:159], v[196:199], v[70:73]
	v_mfma_f32_16x16x32_bf16 v[70:73], v[160:163], v[200:203], v[70:73]
	v_mfma_f32_16x16x32_bf16 v[74:77], v[148:151], v[196:199], v[74:77]
	v_mfma_f32_16x16x32_bf16 v[74:77], v[152:155], v[200:203], v[74:77]
	v_mfma_f32_16x16x32_bf16 v[78:81], v[132:135], v[196:199], v[78:81]
	v_mfma_f32_16x16x32_bf16 v[78:81], v[136:139], v[200:203], v[78:81]
	s_setprio 0
	s_barrier
	s_mov_b32 m0, s48
	ds_read_b128 v[172:175], v144 offset:49152
	ds_read_b128 v[176:179], v144 offset:50176
	ds_read_b128 v[180:183], v144 offset:51200
	ds_read_b128 v[184:187], v144 offset:52224
	ds_read_b128 v[188:191], v144 offset:53248
	ds_read_b128 v[192:195], v144 offset:54272
	ds_read_b128 v[196:199], v144 offset:55296
	ds_read_b128 v[200:203], v144 offset:56320
	buffer_load_dwordx4 v141, s[16:19], s63 offen lds
	s_add_i32 s65, s64, 0x40080
	s_mov_b32 m0, s49
	s_add_i32 s66, s64, 0x80080
	buffer_load_dwordx4 v141, s[16:19], s65 offen lds
	s_mov_b32 m0, s52
	s_add_i32 s64, s64, 0xc0080
	buffer_load_dwordx4 v141, s[16:19], s66 offen lds
	s_mov_b32 m0, s53
	s_nop 0
	buffer_load_dwordx4 v141, s[16:19], s64 offen lds
	s_mov_b32 m0, s50
	s_nop 0
	buffer_load_dwordx4 v140, s[12:15], s63 offen lds
	s_mov_b32 m0, s51
	s_nop 0
	buffer_load_dwordx4 v140, s[12:15], s65 offen lds
	s_waitcnt vmcnt(8)
	s_waitcnt lgkmcnt(0)
	s_setprio 1
	s_barrier
	v_mfma_f32_16x16x32_bf16 v[62:65], v[132:135], v[172:175], v[62:65]
	v_mfma_f32_16x16x32_bf16 v[62:65], v[136:139], v[176:179], v[62:65]
	v_mfma_f32_16x16x32_bf16 v[58:61], v[148:151], v[172:175], v[58:61]
	v_mfma_f32_16x16x32_bf16 v[58:61], v[152:155], v[176:179], v[58:61]
	v_mfma_f32_16x16x32_bf16 v[54:57], v[156:159], v[172:175], v[54:57]
	v_mfma_f32_16x16x32_bf16 v[54:57], v[160:163], v[176:179], v[54:57]
	v_mfma_f32_16x16x32_bf16 v[50:53], v[164:167], v[172:175], v[50:53]
	v_mfma_f32_16x16x32_bf16 v[50:53], v[168:171], v[176:179], v[50:53]
	v_mfma_f32_16x16x32_bf16 v[34:37], v[164:167], v[180:183], v[34:37]
	v_mfma_f32_16x16x32_bf16 v[34:37], v[168:171], v[184:187], v[34:37]
	v_mfma_f32_16x16x32_bf16 v[38:41], v[156:159], v[180:183], v[38:41]
	v_mfma_f32_16x16x32_bf16 v[38:41], v[160:163], v[184:187], v[38:41]
	v_mfma_f32_16x16x32_bf16 v[42:45], v[148:151], v[180:183], v[42:45]
	v_mfma_f32_16x16x32_bf16 v[42:45], v[152:155], v[184:187], v[42:45]
	v_mfma_f32_16x16x32_bf16 v[46:49], v[132:135], v[180:183], v[46:49]
	v_mfma_f32_16x16x32_bf16 v[46:49], v[136:139], v[184:187], v[46:49]
	v_mfma_f32_16x16x32_bf16 v[30:33], v[132:135], v[188:191], v[30:33]
	v_mfma_f32_16x16x32_bf16 v[30:33], v[136:139], v[192:195], v[30:33]
	v_mfma_f32_16x16x32_bf16 v[26:29], v[148:151], v[188:191], v[26:29]
	v_mfma_f32_16x16x32_bf16 v[26:29], v[152:155], v[192:195], v[26:29]
	v_mfma_f32_16x16x32_bf16 v[22:25], v[156:159], v[188:191], v[22:25]
	v_mfma_f32_16x16x32_bf16 v[22:25], v[160:163], v[192:195], v[22:25]
	v_mfma_f32_16x16x32_bf16 v[18:21], v[164:167], v[188:191], v[18:21]
	v_mfma_f32_16x16x32_bf16 v[18:21], v[168:171], v[192:195], v[18:21]
	v_mfma_f32_16x16x32_bf16 v[2:5], v[164:167], v[196:199], v[2:5]
	v_mfma_f32_16x16x32_bf16 v[2:5], v[168:171], v[200:203], v[2:5]
	v_mfma_f32_16x16x32_bf16 v[6:9], v[156:159], v[196:199], v[6:9]
	v_mfma_f32_16x16x32_bf16 v[6:9], v[160:163], v[200:203], v[6:9]
	v_mfma_f32_16x16x32_bf16 v[10:13], v[148:151], v[196:199], v[10:13]
	v_mfma_f32_16x16x32_bf16 v[10:13], v[152:155], v[200:203], v[10:13]
	v_mfma_f32_16x16x32_bf16 v[14:17], v[132:135], v[196:199], v[14:17]
	v_mfma_f32_16x16x32_bf16 v[14:17], v[136:139], v[200:203], v[14:17]
	s_setprio 0
	s_barrier
	s_add_i32 s62, s62, 2
	s_addk_i32 s61, 0x100
	s_cmp_ge_i32 s62, s3
	s_cbranch_scc0 .LBB0_1050

.LBB0_1181:
	v_add_u32_e32 v2, 0x10000, v232
	ds_read_b128 v[134:137], v2
	ds_read_b128 v[138:141], v2 offset:1024
	ds_read_b128 v[142:145], v2 offset:2048
	ds_read_b128 v[146:149], v2 offset:3072
	v_add_u32_e32 v2, 0x14000, v232
	ds_read_b128 v[150:153], v2
	ds_read_b128 v[154:157], v2 offset:1024
	ds_read_b128 v[158:161], v2 offset:2048
	ds_read_b128 v[162:165], v2 offset:3072
	s_add_i32 s50, s47, s90
	s_and_b64 s[18:19], exec, s[18:19]
	s_cselect_b32 s51, s88, s50
	s_add_i32 s50, s92, 0x80
	s_or_b32 s52, s51, 0x80
	s_add_i32 s18, s89, s93
	s_add_i32 s94, s94, 0x1bfffc80
	s_cmp_lt_u32 s91, 8
	s_cselect_b32 s18, s18, s94
	s_mov_b32 m0, s74
	s_add_i32 s19, s18, 0x80000
	ds_read_b128 v[166:169], v233
	ds_read_b128 v[170:173], v233 offset:1024
	ds_read_b128 v[174:177], v233 offset:2048
	ds_read_b128 v[178:181], v233 offset:3072
	ds_read_b128 v[182:185], v233 offset:4096
	ds_read_b128 v[186:189], v233 offset:5120
	ds_read_b128 v[190:193], v233 offset:6144
	ds_read_b128 v[194:197], v233 offset:7168
	buffer_load_dwordx4 v230, s[12:15], s19 offen lds
	s_add_i32 s18, s18, 0xc0000
	s_mov_b32 m0, s75
	s_nop 0
	buffer_load_dwordx4 v230, s[12:15], s18 offen lds
	s_waitcnt vmcnt(8)
	s_waitcnt lgkmcnt(0)
	s_setprio 1
	s_barrier
	v_mfma_f32_16x16x32_bf16 v[130:133], v[134:137], v[166:169], v[130:133]
	v_mfma_f32_16x16x32_bf16 v[130:133], v[138:141], v[170:173], v[130:133]
	v_mfma_f32_16x16x32_bf16 v[126:129], v[142:145], v[166:169], v[126:129]
	v_mfma_f32_16x16x32_bf16 v[126:129], v[146:149], v[170:173], v[126:129]
	v_mfma_f32_16x16x32_bf16 v[122:125], v[150:153], v[166:169], v[122:125]
	v_mfma_f32_16x16x32_bf16 v[122:125], v[154:157], v[170:173], v[122:125]
	v_mfma_f32_16x16x32_bf16 v[118:121], v[158:161], v[166:169], v[118:121]
	v_mfma_f32_16x16x32_bf16 v[118:121], v[162:165], v[170:173], v[118:121]
	v_mfma_f32_16x16x32_bf16 v[102:105], v[158:161], v[174:177], v[102:105]
	v_mfma_f32_16x16x32_bf16 v[102:105], v[162:165], v[178:181], v[102:105]
	v_mfma_f32_16x16x32_bf16 v[106:109], v[150:153], v[174:177], v[106:109]
	v_mfma_f32_16x16x32_bf16 v[106:109], v[154:157], v[178:181], v[106:109]
	v_mfma_f32_16x16x32_bf16 v[110:113], v[142:145], v[174:177], v[110:113]
	v_mfma_f32_16x16x32_bf16 v[110:113], v[146:149], v[178:181], v[110:113]
	v_mfma_f32_16x16x32_bf16 v[114:117], v[134:137], v[174:177], v[114:117]
	v_mfma_f32_16x16x32_bf16 v[114:117], v[138:141], v[178:181], v[114:117]
	v_mfma_f32_16x16x32_bf16 v[98:101], v[134:137], v[182:185], v[98:101]
	v_mfma_f32_16x16x32_bf16 v[98:101], v[138:141], v[186:189], v[98:101]
	v_mfma_f32_16x16x32_bf16 v[94:97], v[142:145], v[182:185], v[94:97]
	v_mfma_f32_16x16x32_bf16 v[94:97], v[146:149], v[186:189], v[94:97]
	v_mfma_f32_16x16x32_bf16 v[90:93], v[150:153], v[182:185], v[90:93]
	v_mfma_f32_16x16x32_bf16 v[90:93], v[154:157], v[186:189], v[90:93]
	v_mfma_f32_16x16x32_bf16 v[86:89], v[158:161], v[182:185], v[86:89]
	v_mfma_f32_16x16x32_bf16 v[86:89], v[162:165], v[186:189], v[86:89]
	v_mfma_f32_16x16x32_bf16 v[70:73], v[158:161], v[190:193], v[70:73]
	v_mfma_f32_16x16x32_bf16 v[70:73], v[162:165], v[194:197], v[70:73]
	v_mfma_f32_16x16x32_bf16 v[74:77], v[150:153], v[190:193], v[74:77]
	v_mfma_f32_16x16x32_bf16 v[74:77], v[154:157], v[194:197], v[74:77]
	v_mfma_f32_16x16x32_bf16 v[78:81], v[142:145], v[190:193], v[78:81]
	v_mfma_f32_16x16x32_bf16 v[78:81], v[146:149], v[194:197], v[78:81]
	v_mfma_f32_16x16x32_bf16 v[82:85], v[134:137], v[190:193], v[82:85]
	v_mfma_f32_16x16x32_bf16 v[82:85], v[138:141], v[194:197], v[82:85]
	s_setprio 0
	s_barrier
	s_mov_b32 m0, s27
	s_mov_b32 s18, s14
	s_mov_b32 s19, s15
	ds_read_b128 v[166:169], v233 offset:16384
	ds_read_b128 v[170:173], v233 offset:17408
	ds_read_b128 v[174:177], v233 offset:18432
	ds_read_b128 v[178:181], v233 offset:19456
	ds_read_b128 v[182:185], v233 offset:20480
	ds_read_b128 v[186:189], v233 offset:21504
	ds_read_b128 v[190:193], v233 offset:22528
	ds_read_b128 v[194:197], v233 offset:23552
	buffer_load_dwordx4 v231, s[16:19], s51 offen lds
	s_add_i32 s53, s51, 0x18000
	s_mov_b32 m0, s30
	s_nop 0
	buffer_load_dwordx4 v231, s[16:19], s53 offen lds
	s_add_i32 s53, s51, 0x30000
	s_mov_b32 m0, s31
	s_nop 0
	buffer_load_dwordx4 v231, s[16:19], s53 offen lds
	s_add_i32 s53, s51, 0x48000
	s_mov_b32 m0, s54
	s_nop 0
	buffer_load_dwordx4 v231, s[16:19], s53 offen lds
	s_mov_b32 m0, s25
	s_add_i32 s53, s92, 0x40000
	buffer_load_dwordx4 v230, s[12:15], s92 offen lds
	s_mov_b32 m0, s55
	s_nop 0
	buffer_load_dwordx4 v230, s[12:15], s53 offen lds
	s_waitcnt vmcnt(8)
	s_waitcnt lgkmcnt(0)
	s_setprio 1
	s_barrier
	v_mfma_f32_16x16x32_bf16 v[66:69], v[134:137], v[166:169], v[66:69]
	v_mfma_f32_16x16x32_bf16 v[62:65], v[142:145], v[166:169], v[62:65]
	v_mfma_f32_16x16x32_bf16 v[50:53], v[134:137], v[174:177], v[50:53]
	v_mfma_f32_16x16x32_bf16 v[46:49], v[142:145], v[174:177], v[46:49]
	v_mfma_f32_16x16x32_bf16 v[34:37], v[134:137], v[182:185], v[34:37]
	v_mfma_f32_16x16x32_bf16 v[30:33], v[142:145], v[182:185], v[30:33]
	v_mfma_f32_16x16x32_bf16 v[18:21], v[134:137], v[190:193], v[18:21]
	v_mfma_f32_16x16x32_bf16 v[14:17], v[142:145], v[190:193], v[14:17]
	v_mfma_f32_16x16x32_bf16 v[58:61], v[150:153], v[166:169], v[58:61]
	v_mfma_f32_16x16x32_bf16 v[54:57], v[158:161], v[166:169], v[54:57]
	v_mfma_f32_16x16x32_bf16 v[42:45], v[150:153], v[174:177], v[42:45]
	v_mfma_f32_16x16x32_bf16 v[38:41], v[158:161], v[174:177], v[38:41]
	v_mfma_f32_16x16x32_bf16 v[26:29], v[150:153], v[182:185], v[26:29]
	v_mfma_f32_16x16x32_bf16 v[22:25], v[158:161], v[182:185], v[22:25]
	v_mfma_f32_16x16x32_bf16 v[10:13], v[150:153], v[190:193], v[10:13]
	v_mfma_f32_16x16x32_bf16 v[4:7], v[158:161], v[190:193], v[6:9]
	v_mfma_f32_16x16x32_bf16 v[66:69], v[138:141], v[170:173], v[66:69]
	v_mfma_f32_16x16x32_bf16 v[62:65], v[146:149], v[170:173], v[62:65]
	v_mfma_f32_16x16x32_bf16 v[50:53], v[138:141], v[178:181], v[50:53]
	v_mfma_f32_16x16x32_bf16 v[46:49], v[146:149], v[178:181], v[46:49]
	v_mfma_f32_16x16x32_bf16 v[34:37], v[138:141], v[186:189], v[34:37]
	v_mfma_f32_16x16x32_bf16 v[30:33], v[146:149], v[186:189], v[30:33]
	v_mfma_f32_16x16x32_bf16 v[18:21], v[138:141], v[194:197], v[18:21]
	v_mfma_f32_16x16x32_bf16 v[14:17], v[146:149], v[194:197], v[14:17]
	v_mfma_f32_16x16x32_bf16 v[58:61], v[154:157], v[170:173], v[58:61]
	v_mfma_f32_16x16x32_bf16 v[54:57], v[162:165], v[170:173], v[54:57]
	v_mfma_f32_16x16x32_bf16 v[42:45], v[154:157], v[178:181], v[42:45]
	v_mfma_f32_16x16x32_bf16 v[38:41], v[162:165], v[178:181], v[38:41]
	v_mfma_f32_16x16x32_bf16 v[26:29], v[154:157], v[186:189], v[26:29]
	v_mfma_f32_16x16x32_bf16 v[22:25], v[162:165], v[186:189], v[22:25]
	v_mfma_f32_16x16x32_bf16 v[10:13], v[154:157], v[194:197], v[10:13]
	v_mfma_f32_16x16x32_bf16 v[4:7], v[162:165], v[194:197], v[4:7]
	s_setprio 0
	s_barrier
	v_add_u32_e32 v2, 0x18000, v232
	ds_read_b128 v[134:137], v2
	ds_read_b128 v[138:141], v2 offset:1024
	ds_read_b128 v[142:145], v2 offset:2048
	ds_read_b128 v[146:149], v2 offset:3072
	v_add_u32_e32 v2, 0x1c000, v232
	ds_read_b128 v[150:153], v2
	ds_read_b128 v[154:157], v2 offset:1024
	ds_read_b128 v[158:161], v2 offset:2048
	ds_read_b128 v[162:165], v2 offset:3072
	s_mov_b32 m0, s56
	s_add_i32 s53, s92, 0x80000
	ds_read_b128 v[166:169], v233 offset:32768
	ds_read_b128 v[170:173], v233 offset:33792
	ds_read_b128 v[174:177], v233 offset:34816
	ds_read_b128 v[178:181], v233 offset:35840
	ds_read_b128 v[182:185], v233 offset:36864
	ds_read_b128 v[186:189], v233 offset:37888
	ds_read_b128 v[190:193], v233 offset:38912
	ds_read_b128 v[194:197], v233 offset:39936
	buffer_load_dwordx4 v230, s[12:15], s53 offen lds
	s_add_i32 s53, s92, 0xc0000
	s_mov_b32 m0, s57
	s_nop 0
	buffer_load_dwordx4 v230, s[12:15], s53 offen lds
	s_waitcnt vmcnt(8)
	s_waitcnt lgkmcnt(0)
	s_setprio 1
	s_barrier
	v_mfma_f32_16x16x32_bf16 v[130:133], v[134:137], v[166:169], v[130:133]
	v_mfma_f32_16x16x32_bf16 v[130:133], v[138:141], v[170:173], v[130:133]
	v_mfma_f32_16x16x32_bf16 v[126:129], v[142:145], v[166:169], v[126:129]
	v_mfma_f32_16x16x32_bf16 v[126:129], v[146:149], v[170:173], v[126:129]
	v_mfma_f32_16x16x32_bf16 v[122:125], v[150:153], v[166:169], v[122:125]
	v_mfma_f32_16x16x32_bf16 v[122:125], v[154:157], v[170:173], v[122:125]
	v_mfma_f32_16x16x32_bf16 v[118:121], v[158:161], v[166:169], v[118:121]
	v_mfma_f32_16x16x32_bf16 v[118:121], v[162:165], v[170:173], v[118:121]
	v_mfma_f32_16x16x32_bf16 v[102:105], v[158:161], v[174:177], v[102:105]
	v_mfma_f32_16x16x32_bf16 v[102:105], v[162:165], v[178:181], v[102:105]
	v_mfma_f32_16x16x32_bf16 v[106:109], v[150:153], v[174:177], v[106:109]
	v_mfma_f32_16x16x32_bf16 v[106:109], v[154:157], v[178:181], v[106:109]
	v_mfma_f32_16x16x32_bf16 v[110:113], v[142:145], v[174:177], v[110:113]
	v_mfma_f32_16x16x32_bf16 v[110:113], v[146:149], v[178:181], v[110:113]
	v_mfma_f32_16x16x32_bf16 v[114:117], v[134:137], v[174:177], v[114:117]
	v_mfma_f32_16x16x32_bf16 v[114:117], v[138:141], v[178:181], v[114:117]
	v_mfma_f32_16x16x32_bf16 v[98:101], v[134:137], v[182:185], v[98:101]
	v_mfma_f32_16x16x32_bf16 v[98:101], v[138:141], v[186:189], v[98:101]
	v_mfma_f32_16x16x32_bf16 v[94:97], v[142:145], v[182:185], v[94:97]
	v_mfma_f32_16x16x32_bf16 v[94:97], v[146:149], v[186:189], v[94:97]
	v_mfma_f32_16x16x32_bf16 v[90:93], v[150:153], v[182:185], v[90:93]
	v_mfma_f32_16x16x32_bf16 v[90:93], v[154:157], v[186:189], v[90:93]
	v_mfma_f32_16x16x32_bf16 v[86:89], v[158:161], v[182:185], v[86:89]
	v_mfma_f32_16x16x32_bf16 v[86:89], v[162:165], v[186:189], v[86:89]
	v_mfma_f32_16x16x32_bf16 v[70:73], v[158:161], v[190:193], v[70:73]
	v_mfma_f32_16x16x32_bf16 v[70:73], v[162:165], v[194:197], v[70:73]
	v_mfma_f32_16x16x32_bf16 v[74:77], v[150:153], v[190:193], v[74:77]
	v_mfma_f32_16x16x32_bf16 v[74:77], v[154:157], v[194:197], v[74:77]
	v_mfma_f32_16x16x32_bf16 v[78:81], v[142:145], v[190:193], v[78:81]
	v_mfma_f32_16x16x32_bf16 v[78:81], v[146:149], v[194:197], v[78:81]
	v_mfma_f32_16x16x32_bf16 v[82:85], v[134:137], v[190:193], v[82:85]
	v_mfma_f32_16x16x32_bf16 v[82:85], v[138:141], v[194:197], v[82:85]
	s_setprio 0
	s_barrier
	s_mov_b32 m0, s64
	ds_read_b128 v[166:169], v233 offset:49152
	ds_read_b128 v[170:173], v233 offset:50176
	ds_read_b128 v[174:177], v233 offset:51200
	ds_read_b128 v[178:181], v233 offset:52224
	ds_read_b128 v[182:185], v233 offset:53248
	ds_read_b128 v[186:189], v233 offset:54272
	ds_read_b128 v[190:193], v233 offset:55296
	ds_read_b128 v[194:197], v233 offset:56320
	buffer_load_dwordx4 v231, s[16:19], s52 offen lds
	s_add_i32 s52, s51, 0x18080
	s_mov_b32 m0, s65
	s_nop 0
	buffer_load_dwordx4 v231, s[16:19], s52 offen lds
	s_add_i32 s52, s51, 0x30080
	s_mov_b32 m0, s68
	s_add_i32 s51, s51, 0x48080
	buffer_load_dwordx4 v231, s[16:19], s52 offen lds
	s_mov_b32 m0, s69
	s_nop 0
	buffer_load_dwordx4 v231, s[16:19], s51 offen lds
	s_mov_b32 m0, s66
	s_add_i32 s18, s92, 0x40080
	buffer_load_dwordx4 v230, s[12:15], s50 offen lds
	s_mov_b32 m0, s67
	s_nop 0
	buffer_load_dwordx4 v230, s[12:15], s18 offen lds
	s_waitcnt vmcnt(8)
	s_waitcnt lgkmcnt(0)
	s_setprio 1
	s_barrier
	v_mfma_f32_16x16x32_bf16 v[66:69], v[134:137], v[166:169], v[66:69]
	v_mfma_f32_16x16x32_bf16 v[62:65], v[142:145], v[166:169], v[62:65]
	v_mfma_f32_16x16x32_bf16 v[50:53], v[134:137], v[174:177], v[50:53]
	v_mfma_f32_16x16x32_bf16 v[46:49], v[142:145], v[174:177], v[46:49]
	v_mfma_f32_16x16x32_bf16 v[34:37], v[134:137], v[182:185], v[34:37]
	v_mfma_f32_16x16x32_bf16 v[30:33], v[142:145], v[182:185], v[30:33]
	v_mfma_f32_16x16x32_bf16 v[18:21], v[134:137], v[190:193], v[18:21]
	v_mfma_f32_16x16x32_bf16 v[14:17], v[142:145], v[190:193], v[14:17]
	v_mfma_f32_16x16x32_bf16 v[58:61], v[150:153], v[166:169], v[58:61]
	v_mfma_f32_16x16x32_bf16 v[54:57], v[158:161], v[166:169], v[54:57]
	v_mfma_f32_16x16x32_bf16 v[42:45], v[150:153], v[174:177], v[42:45]
	v_mfma_f32_16x16x32_bf16 v[38:41], v[158:161], v[174:177], v[38:41]
	v_mfma_f32_16x16x32_bf16 v[26:29], v[150:153], v[182:185], v[26:29]
	v_mfma_f32_16x16x32_bf16 v[22:25], v[158:161], v[182:185], v[22:25]
	v_mfma_f32_16x16x32_bf16 v[8:11], v[150:153], v[190:193], v[10:13]
	v_mfma_f32_16x16x32_bf16 v[4:7], v[158:161], v[190:193], v[4:7]
	v_mfma_f32_16x16x32_bf16 v[66:69], v[138:141], v[170:173], v[66:69]
	v_mfma_f32_16x16x32_bf16 v[62:65], v[146:149], v[170:173], v[62:65]
	v_mfma_f32_16x16x32_bf16 v[50:53], v[138:141], v[178:181], v[50:53]
	v_mfma_f32_16x16x32_bf16 v[46:49], v[146:149], v[178:181], v[46:49]
	v_mfma_f32_16x16x32_bf16 v[34:37], v[138:141], v[186:189], v[34:37]
	v_mfma_f32_16x16x32_bf16 v[30:33], v[146:149], v[186:189], v[30:33]
	v_mfma_f32_16x16x32_bf16 v[18:21], v[138:141], v[194:197], v[18:21]
	v_mfma_f32_16x16x32_bf16 v[14:17], v[146:149], v[194:197], v[14:17]
	v_mfma_f32_16x16x32_bf16 v[58:61], v[154:157], v[170:173], v[58:61]
	v_mfma_f32_16x16x32_bf16 v[54:57], v[162:165], v[170:173], v[54:57]
	v_mfma_f32_16x16x32_bf16 v[42:45], v[154:157], v[178:181], v[42:45]
	v_mfma_f32_16x16x32_bf16 v[38:41], v[162:165], v[178:181], v[38:41]
	v_mfma_f32_16x16x32_bf16 v[26:29], v[154:157], v[186:189], v[26:29]
	v_mfma_f32_16x16x32_bf16 v[22:25], v[162:165], v[186:189], v[22:25]
	v_mfma_f32_16x16x32_bf16 v[10:13], v[154:157], v[194:197], v[8:11]
	v_mfma_f32_16x16x32_bf16 v[6:9], v[162:165], v[194:197], v[4:7]
	s_setprio 0
	s_barrier
	s_add_i32 s91, s91, 2
	s_addk_i32 s90, 0x100
	s_cmp_ge_i32 s91, s3
	s_cbranch_scc1 .LBB0_1193

.LBB0_1290:
	ds_read_b128 v[106:109], v224
	ds_read_b128 v[118:121], v224 offset:1024
	ds_read_b128 v[130:133], v224 offset:2048
	ds_read_b128 v[138:141], v224 offset:3072
	ds_read_b128 v[146:149], v225
	ds_read_b128 v[150:153], v225 offset:1024
	ds_read_b128 v[154:157], v225 offset:2048
	ds_read_b128 v[158:161], v225 offset:3072
	s_add_i32 s18, s72, 0xffe80080
	s_cmp_eq_u32 s56, s74
	s_cselect_b32 s75, s6, s18
	s_cselect_b32 s77, s7, s73
	s_or_b32 s76, s75, 0x80
	s_add_i32 s18, s72, 0xfff80000
	s_mov_b32 m0, s57
	ds_read_b128 v[162:165], v226
	ds_read_b128 v[166:169], v226 offset:1024
	ds_read_b128 v[170:173], v226 offset:2048
	ds_read_b128 v[174:177], v226 offset:3072
	ds_read_b128 v[178:181], v226 offset:4096
	ds_read_b128 v[182:185], v226 offset:5120
	ds_read_b128 v[190:193], v226 offset:6144
	ds_read_b128 v[194:197], v226 offset:7168
	buffer_load_dwordx4 v222, s[12:15], s18 offen lds
	s_mov_b32 m0, s60
	s_nop 0
	buffer_load_dwordx4 v222, s[12:15], s72 offen lds
	s_waitcnt vmcnt(8)
	s_waitcnt lgkmcnt(0)
	s_setprio 1
	s_barrier
	v_mfma_f32_16x16x32_bf16 v[142:145], v[106:109], v[162:165], v[142:145]
	v_mfma_f32_16x16x32_bf16 v[142:145], v[118:121], v[166:169], v[142:145]
	v_mfma_f32_16x16x32_bf16 v[134:137], v[130:133], v[162:165], v[134:137]
	v_mfma_f32_16x16x32_bf16 v[134:137], v[138:141], v[166:169], v[134:137]
	v_mfma_f32_16x16x32_bf16 v[126:129], v[146:149], v[162:165], v[126:129]
	v_mfma_f32_16x16x32_bf16 v[126:129], v[150:153], v[166:169], v[126:129]
	v_mfma_f32_16x16x32_bf16 v[122:125], v[154:157], v[162:165], v[122:125]
	v_mfma_f32_16x16x32_bf16 v[122:125], v[158:161], v[166:169], v[122:125]
	v_mfma_f32_16x16x32_bf16 v[98:101], v[154:157], v[170:173], v[98:101]
	v_mfma_f32_16x16x32_bf16 v[98:101], v[158:161], v[174:177], v[98:101]
	v_mfma_f32_16x16x32_bf16 v[102:105], v[146:149], v[170:173], v[102:105]
	v_mfma_f32_16x16x32_bf16 v[102:105], v[150:153], v[174:177], v[102:105]
	v_mfma_f32_16x16x32_bf16 v[110:113], v[130:133], v[170:173], v[110:113]
	v_mfma_f32_16x16x32_bf16 v[110:113], v[138:141], v[174:177], v[110:113]
	v_mfma_f32_16x16x32_bf16 v[114:117], v[106:109], v[170:173], v[114:117]
	v_mfma_f32_16x16x32_bf16 v[114:117], v[118:121], v[174:177], v[114:117]
	v_mfma_f32_16x16x32_bf16 v[94:97], v[106:109], v[178:181], v[94:97]
	v_mfma_f32_16x16x32_bf16 v[94:97], v[118:121], v[182:185], v[94:97]
	v_mfma_f32_16x16x32_bf16 v[90:93], v[130:133], v[178:181], v[90:93]
	v_mfma_f32_16x16x32_bf16 v[90:93], v[138:141], v[182:185], v[90:93]
	v_mfma_f32_16x16x32_bf16 v[86:89], v[146:149], v[178:181], v[86:89]
	v_mfma_f32_16x16x32_bf16 v[86:89], v[150:153], v[182:185], v[86:89]
	v_mfma_f32_16x16x32_bf16 v[82:85], v[154:157], v[178:181], v[82:85]
	v_mfma_f32_16x16x32_bf16 v[82:85], v[158:161], v[182:185], v[82:85]
	v_mfma_f32_16x16x32_bf16 v[66:69], v[154:157], v[190:193], v[66:69]
	v_mfma_f32_16x16x32_bf16 v[66:69], v[158:161], v[194:197], v[66:69]
	v_mfma_f32_16x16x32_bf16 v[70:73], v[146:149], v[190:193], v[70:73]
	v_mfma_f32_16x16x32_bf16 v[70:73], v[150:153], v[194:197], v[70:73]
	v_mfma_f32_16x16x32_bf16 v[74:77], v[130:133], v[190:193], v[74:77]
	v_mfma_f32_16x16x32_bf16 v[74:77], v[138:141], v[194:197], v[74:77]
	v_mfma_f32_16x16x32_bf16 v[78:81], v[106:109], v[190:193], v[78:81]
	v_mfma_f32_16x16x32_bf16 v[78:81], v[118:121], v[194:197], v[78:81]
	s_setprio 0
	s_barrier
	s_mov_b32 m0, s27
	s_mov_b32 s18, s14
	s_mov_b32 s19, s15
	ds_read_b128 v[162:165], v226 offset:16384
	ds_read_b128 v[166:169], v226 offset:17408
	ds_read_b128 v[170:173], v226 offset:18432
	ds_read_b128 v[174:177], v226 offset:19456
	ds_read_b128 v[178:181], v226 offset:20480
	ds_read_b128 v[182:185], v226 offset:21504
	ds_read_b128 v[190:193], v226 offset:22528
	ds_read_b128 v[194:197], v226 offset:23552
	buffer_load_dwordx4 v223, s[16:19], s77 offen lds
	s_add_i32 s78, s77, 0x80000
	s_mov_b32 m0, s30
	s_nop 0
	buffer_load_dwordx4 v223, s[16:19], s78 offen lds
	s_add_i32 s78, s77, 0x100000
	s_mov_b32 m0, s31
	s_nop 0
	buffer_load_dwordx4 v223, s[16:19], s78 offen lds
	s_add_i32 s78, s77, 0x180000
	s_mov_b32 m0, s41
	s_nop 0
	buffer_load_dwordx4 v223, s[16:19], s78 offen lds
	s_mov_b32 m0, s25
	s_add_i32 s78, s75, 0x80000
	buffer_load_dwordx4 v222, s[12:15], s75 offen lds
	s_mov_b32 m0, s42
	s_nop 0
	buffer_load_dwordx4 v222, s[12:15], s78 offen lds
	s_waitcnt vmcnt(8)
	s_waitcnt lgkmcnt(0)
	s_setprio 1
	s_barrier
	v_mfma_f32_16x16x32_bf16 v[62:65], v[106:109], v[162:165], v[62:65]
	v_mfma_f32_16x16x32_bf16 v[62:65], v[118:121], v[166:169], v[62:65]
	v_mfma_f32_16x16x32_bf16 v[58:61], v[130:133], v[162:165], v[58:61]
	v_mfma_f32_16x16x32_bf16 v[58:61], v[138:141], v[166:169], v[58:61]
	v_mfma_f32_16x16x32_bf16 v[54:57], v[146:149], v[162:165], v[54:57]
	v_mfma_f32_16x16x32_bf16 v[54:57], v[150:153], v[166:169], v[54:57]
	v_mfma_f32_16x16x32_bf16 v[50:53], v[154:157], v[162:165], v[50:53]
	v_mfma_f32_16x16x32_bf16 v[50:53], v[158:161], v[166:169], v[50:53]
	v_mfma_f32_16x16x32_bf16 v[34:37], v[154:157], v[170:173], v[34:37]
	v_mfma_f32_16x16x32_bf16 v[34:37], v[158:161], v[174:177], v[34:37]
	v_mfma_f32_16x16x32_bf16 v[38:41], v[146:149], v[170:173], v[38:41]
	v_mfma_f32_16x16x32_bf16 v[38:41], v[150:153], v[174:177], v[38:41]
	v_mfma_f32_16x16x32_bf16 v[42:45], v[130:133], v[170:173], v[42:45]
	v_mfma_f32_16x16x32_bf16 v[42:45], v[138:141], v[174:177], v[42:45]
	v_mfma_f32_16x16x32_bf16 v[46:49], v[106:109], v[170:173], v[46:49]
	v_mfma_f32_16x16x32_bf16 v[46:49], v[118:121], v[174:177], v[46:49]
	v_mfma_f32_16x16x32_bf16 v[30:33], v[106:109], v[178:181], v[30:33]
	v_mfma_f32_16x16x32_bf16 v[30:33], v[118:121], v[182:185], v[30:33]
	v_mfma_f32_16x16x32_bf16 v[26:29], v[130:133], v[178:181], v[26:29]
	v_mfma_f32_16x16x32_bf16 v[26:29], v[138:141], v[182:185], v[26:29]
	v_mfma_f32_16x16x32_bf16 v[22:25], v[146:149], v[178:181], v[22:25]
	v_mfma_f32_16x16x32_bf16 v[22:25], v[150:153], v[182:185], v[22:25]
	v_mfma_f32_16x16x32_bf16 v[18:21], v[154:157], v[178:181], v[18:21]
	v_mfma_f32_16x16x32_bf16 v[18:21], v[158:161], v[182:185], v[18:21]
	v_mfma_f32_16x16x32_bf16 v[2:5], v[154:157], v[190:193], v[2:5]
	v_mfma_f32_16x16x32_bf16 v[2:5], v[158:161], v[194:197], v[2:5]
	v_mfma_f32_16x16x32_bf16 v[6:9], v[146:149], v[190:193], v[6:9]
	v_mfma_f32_16x16x32_bf16 v[6:9], v[150:153], v[194:197], v[6:9]
	v_mfma_f32_16x16x32_bf16 v[10:13], v[130:133], v[190:193], v[10:13]
	v_mfma_f32_16x16x32_bf16 v[10:13], v[138:141], v[194:197], v[10:13]
	v_mfma_f32_16x16x32_bf16 v[14:17], v[106:109], v[190:193], v[14:17]
	v_mfma_f32_16x16x32_bf16 v[14:17], v[118:121], v[194:197], v[14:17]
	s_setprio 0
	s_barrier
	ds_read_b128 v[106:109], v227
	ds_read_b128 v[118:121], v227 offset:1024
	ds_read_b128 v[130:133], v227 offset:2048
	ds_read_b128 v[138:141], v227 offset:3072
	ds_read_b128 v[146:149], v228
	ds_read_b128 v[150:153], v228 offset:1024
	ds_read_b128 v[154:157], v228 offset:2048
	ds_read_b128 v[158:161], v228 offset:3072
	s_mov_b32 m0, s43
	s_add_i32 s78, s75, 0x100000
	ds_read_b128 v[162:165], v226 offset:32768
	ds_read_b128 v[166:169], v226 offset:33792
	ds_read_b128 v[170:173], v226 offset:34816
	ds_read_b128 v[174:177], v226 offset:35840
	ds_read_b128 v[178:181], v226 offset:36864
	ds_read_b128 v[182:185], v226 offset:37888
	ds_read_b128 v[190:193], v226 offset:38912
	ds_read_b128 v[194:197], v226 offset:39936
	buffer_load_dwordx4 v222, s[12:15], s78 offen lds
	s_add_i32 s78, s75, 0x180000
	s_mov_b32 m0, s44
	s_nop 0
	buffer_load_dwordx4 v222, s[12:15], s78 offen lds
	s_waitcnt vmcnt(8)
	s_waitcnt lgkmcnt(0)
	s_setprio 1
	s_barrier
	v_mfma_f32_16x16x32_bf16 v[142:145], v[106:109], v[162:165], v[142:145]
	v_mfma_f32_16x16x32_bf16 v[142:145], v[118:121], v[166:169], v[142:145]
	v_mfma_f32_16x16x32_bf16 v[134:137], v[130:133], v[162:165], v[134:137]
	v_mfma_f32_16x16x32_bf16 v[134:137], v[138:141], v[166:169], v[134:137]
	v_mfma_f32_16x16x32_bf16 v[126:129], v[146:149], v[162:165], v[126:129]
	v_mfma_f32_16x16x32_bf16 v[126:129], v[150:153], v[166:169], v[126:129]
	v_mfma_f32_16x16x32_bf16 v[122:125], v[154:157], v[162:165], v[122:125]
	v_mfma_f32_16x16x32_bf16 v[122:125], v[158:161], v[166:169], v[122:125]
	v_mfma_f32_16x16x32_bf16 v[98:101], v[154:157], v[170:173], v[98:101]
	v_mfma_f32_16x16x32_bf16 v[98:101], v[158:161], v[174:177], v[98:101]
	v_mfma_f32_16x16x32_bf16 v[102:105], v[146:149], v[170:173], v[102:105]
	v_mfma_f32_16x16x32_bf16 v[102:105], v[150:153], v[174:177], v[102:105]
	v_mfma_f32_16x16x32_bf16 v[110:113], v[130:133], v[170:173], v[110:113]
	v_mfma_f32_16x16x32_bf16 v[110:113], v[138:141], v[174:177], v[110:113]
	v_mfma_f32_16x16x32_bf16 v[114:117], v[106:109], v[170:173], v[114:117]
	v_mfma_f32_16x16x32_bf16 v[114:117], v[118:121], v[174:177], v[114:117]
	v_mfma_f32_16x16x32_bf16 v[94:97], v[106:109], v[178:181], v[94:97]
	v_mfma_f32_16x16x32_bf16 v[94:97], v[118:121], v[182:185], v[94:97]
	v_mfma_f32_16x16x32_bf16 v[90:93], v[130:133], v[178:181], v[90:93]
	v_mfma_f32_16x16x32_bf16 v[90:93], v[138:141], v[182:185], v[90:93]
	v_mfma_f32_16x16x32_bf16 v[86:89], v[146:149], v[178:181], v[86:89]
	v_mfma_f32_16x16x32_bf16 v[86:89], v[150:153], v[182:185], v[86:89]
	v_mfma_f32_16x16x32_bf16 v[82:85], v[154:157], v[178:181], v[82:85]
	v_mfma_f32_16x16x32_bf16 v[82:85], v[158:161], v[182:185], v[82:85]
	v_mfma_f32_16x16x32_bf16 v[66:69], v[154:157], v[190:193], v[66:69]
	v_mfma_f32_16x16x32_bf16 v[66:69], v[158:161], v[194:197], v[66:69]
	v_mfma_f32_16x16x32_bf16 v[70:73], v[146:149], v[190:193], v[70:73]
	v_mfma_f32_16x16x32_bf16 v[70:73], v[150:153], v[194:197], v[70:73]
	v_mfma_f32_16x16x32_bf16 v[74:77], v[130:133], v[190:193], v[74:77]
	v_mfma_f32_16x16x32_bf16 v[74:77], v[138:141], v[194:197], v[74:77]
	v_mfma_f32_16x16x32_bf16 v[78:81], v[106:109], v[190:193], v[78:81]
	v_mfma_f32_16x16x32_bf16 v[78:81], v[118:121], v[194:197], v[78:81]
	s_setprio 0
	s_barrier
	s_mov_b32 m0, s48
	s_or_b32 s78, s77, 0x80
	ds_read_b128 v[162:165], v226 offset:49152
	ds_read_b128 v[166:169], v226 offset:50176
	ds_read_b128 v[170:173], v226 offset:51200
	ds_read_b128 v[174:177], v226 offset:52224
	ds_read_b128 v[178:181], v226 offset:53248
	ds_read_b128 v[182:185], v226 offset:54272
	ds_read_b128 v[190:193], v226 offset:55296
	ds_read_b128 v[194:197], v226 offset:56320
	buffer_load_dwordx4 v223, s[16:19], s78 offen lds
	s_add_i32 s78, s77, 0x80080
	s_mov_b32 m0, s49
	s_add_i32 s75, s75, 0x80080
	buffer_load_dwordx4 v223, s[16:19], s78 offen lds
	s_add_i32 s78, s77, 0x100080
	s_mov_b32 m0, s52
	s_add_i32 s77, s77, 0x180080
	buffer_load_dwordx4 v223, s[16:19], s78 offen lds
	s_mov_b32 m0, s53
	s_nop 0
	buffer_load_dwordx4 v223, s[16:19], s77 offen lds
	s_mov_b32 m0, s50
	s_nop 0
	buffer_load_dwordx4 v222, s[12:15], s76 offen lds
	s_mov_b32 m0, s51
	s_nop 0
	buffer_load_dwordx4 v222, s[12:15], s75 offen lds
	s_waitcnt vmcnt(8)
	s_waitcnt lgkmcnt(0)
	s_setprio 1
	s_barrier
	v_mfma_f32_16x16x32_bf16 v[62:65], v[106:109], v[162:165], v[62:65]
	v_mfma_f32_16x16x32_bf16 v[62:65], v[118:121], v[166:169], v[62:65]
	v_mfma_f32_16x16x32_bf16 v[58:61], v[130:133], v[162:165], v[58:61]
	v_mfma_f32_16x16x32_bf16 v[58:61], v[138:141], v[166:169], v[58:61]
	v_mfma_f32_16x16x32_bf16 v[54:57], v[146:149], v[162:165], v[54:57]
	v_mfma_f32_16x16x32_bf16 v[54:57], v[150:153], v[166:169], v[54:57]
	v_mfma_f32_16x16x32_bf16 v[50:53], v[154:157], v[162:165], v[50:53]
	v_mfma_f32_16x16x32_bf16 v[50:53], v[158:161], v[166:169], v[50:53]
	v_mfma_f32_16x16x32_bf16 v[34:37], v[154:157], v[170:173], v[34:37]
	v_mfma_f32_16x16x32_bf16 v[34:37], v[158:161], v[174:177], v[34:37]
	v_mfma_f32_16x16x32_bf16 v[38:41], v[146:149], v[170:173], v[38:41]
	v_mfma_f32_16x16x32_bf16 v[38:41], v[150:153], v[174:177], v[38:41]
	v_mfma_f32_16x16x32_bf16 v[42:45], v[130:133], v[170:173], v[42:45]
	v_mfma_f32_16x16x32_bf16 v[42:45], v[138:141], v[174:177], v[42:45]
	v_mfma_f32_16x16x32_bf16 v[46:49], v[106:109], v[170:173], v[46:49]
	v_mfma_f32_16x16x32_bf16 v[46:49], v[118:121], v[174:177], v[46:49]
	v_mfma_f32_16x16x32_bf16 v[30:33], v[106:109], v[178:181], v[30:33]
	v_mfma_f32_16x16x32_bf16 v[30:33], v[118:121], v[182:185], v[30:33]
	v_mfma_f32_16x16x32_bf16 v[26:29], v[130:133], v[178:181], v[26:29]
	v_mfma_f32_16x16x32_bf16 v[26:29], v[138:141], v[182:185], v[26:29]
	v_mfma_f32_16x16x32_bf16 v[22:25], v[146:149], v[178:181], v[22:25]
	v_mfma_f32_16x16x32_bf16 v[22:25], v[150:153], v[182:185], v[22:25]
	v_mfma_f32_16x16x32_bf16 v[18:21], v[154:157], v[178:181], v[18:21]
	v_mfma_f32_16x16x32_bf16 v[18:21], v[158:161], v[182:185], v[18:21]
	v_mfma_f32_16x16x32_bf16 v[2:5], v[154:157], v[190:193], v[2:5]
	v_mfma_f32_16x16x32_bf16 v[2:5], v[158:161], v[194:197], v[2:5]
	v_mfma_f32_16x16x32_bf16 v[6:9], v[146:149], v[190:193], v[6:9]
	v_mfma_f32_16x16x32_bf16 v[6:9], v[150:153], v[194:197], v[6:9]
	v_mfma_f32_16x16x32_bf16 v[10:13], v[130:133], v[190:193], v[10:13]
	v_mfma_f32_16x16x32_bf16 v[10:13], v[138:141], v[194:197], v[10:13]
	v_mfma_f32_16x16x32_bf16 v[14:17], v[106:109], v[190:193], v[14:17]
	v_mfma_f32_16x16x32_bf16 v[14:17], v[118:121], v[194:197], v[14:17]
	s_setprio 0
	s_barrier
	s_add_i32 s74, s74, 2
	s_addk_i32 s72, 0x100
	s_addk_i32 s73, 0x100
	s_cmp_ge_i32 s74, s3
	s_cbranch_scc0 .LBB0_1290
	s_and_b64 vcc, exec, s[38:39]
	s_cbranch_vccz .LBB0_1293

.LBB0_1382:
	ds_read_b128 v[144:147], v138
	ds_read_b128 v[148:151], v138 offset:1024
	ds_read_b128 v[152:155], v138 offset:2048
	ds_read_b128 v[156:159], v138 offset:3072
	ds_read_b128 v[160:163], v139
	ds_read_b128 v[164:167], v139 offset:1024
	ds_read_b128 v[168:171], v139 offset:2048
	ds_read_b128 v[172:175], v139 offset:3072
	s_add_i32 s14, s74, 0xffe80080
	s_cmp_eq_u32 s61, s76
	s_cselect_b32 s77, s72, s14
	s_cselect_b32 s79, s73, s75
	s_or_b32 s78, s77, 0x80
	s_add_i32 s14, s74, 0xfff80000
	s_mov_b32 m0, s62
	ds_read_b128 v[176:179], v140
	ds_read_b128 v[180:183], v140 offset:1024
	ds_read_b128 v[184:187], v140 offset:2048
	ds_read_b128 v[188:191], v140 offset:3072
	ds_read_b128 v[192:195], v140 offset:4096
	ds_read_b128 v[196:199], v140 offset:5120
	ds_read_b128 v[200:203], v140 offset:6144
	ds_read_b128 v[204:207], v140 offset:7168
	buffer_load_dwordx4 v136, s[16:19], s14 offen lds
	s_mov_b32 m0, s63
	s_nop 0
	buffer_load_dwordx4 v136, s[16:19], s74 offen lds
	s_waitcnt vmcnt(8)
	s_waitcnt lgkmcnt(0)
	s_setprio 1
	s_barrier
	v_mfma_f32_16x16x32_bf16 v[118:121], v[144:147], v[176:179], v[118:121]
	v_mfma_f32_16x16x32_bf16 v[118:121], v[148:151], v[180:183], v[118:121]
	v_mfma_f32_16x16x32_bf16 v[114:117], v[152:155], v[176:179], v[114:117]
	v_mfma_f32_16x16x32_bf16 v[114:117], v[156:159], v[180:183], v[114:117]
	v_mfma_f32_16x16x32_bf16 v[126:129], v[160:163], v[176:179], v[126:129]
	v_mfma_f32_16x16x32_bf16 v[126:129], v[164:167], v[180:183], v[126:129]
	v_mfma_f32_16x16x32_bf16 v[122:125], v[168:171], v[176:179], v[122:125]
	v_mfma_f32_16x16x32_bf16 v[122:125], v[172:175], v[180:183], v[122:125]
	v_mfma_f32_16x16x32_bf16 v[98:101], v[168:171], v[184:187], v[98:101]
	v_mfma_f32_16x16x32_bf16 v[98:101], v[172:175], v[188:191], v[98:101]
	v_mfma_f32_16x16x32_bf16 v[106:109], v[160:163], v[184:187], v[106:109]
	v_mfma_f32_16x16x32_bf16 v[106:109], v[164:167], v[188:191], v[106:109]
	v_mfma_f32_16x16x32_bf16 v[102:105], v[152:155], v[184:187], v[102:105]
	v_mfma_f32_16x16x32_bf16 v[102:105], v[156:159], v[188:191], v[102:105]
	v_mfma_f32_16x16x32_bf16 v[110:113], v[144:147], v[184:187], v[110:113]
	v_mfma_f32_16x16x32_bf16 v[110:113], v[148:151], v[188:191], v[110:113]
	v_mfma_f32_16x16x32_bf16 v[94:97], v[144:147], v[192:195], v[94:97]
	v_mfma_f32_16x16x32_bf16 v[94:97], v[148:151], v[196:199], v[94:97]
	v_mfma_f32_16x16x32_bf16 v[86:89], v[152:155], v[192:195], v[86:89]
	v_mfma_f32_16x16x32_bf16 v[86:89], v[156:159], v[196:199], v[86:89]
	v_mfma_f32_16x16x32_bf16 v[90:93], v[160:163], v[192:195], v[90:93]
	v_mfma_f32_16x16x32_bf16 v[90:93], v[164:167], v[196:199], v[90:93]
	v_mfma_f32_16x16x32_bf16 v[82:85], v[168:171], v[192:195], v[82:85]
	v_mfma_f32_16x16x32_bf16 v[82:85], v[172:175], v[196:199], v[82:85]
	v_mfma_f32_16x16x32_bf16 v[70:73], v[168:171], v[200:203], v[70:73]
	v_mfma_f32_16x16x32_bf16 v[70:73], v[172:175], v[204:207], v[70:73]
	v_mfma_f32_16x16x32_bf16 v[74:77], v[160:163], v[200:203], v[74:77]
	v_mfma_f32_16x16x32_bf16 v[74:77], v[164:167], v[204:207], v[74:77]
	v_mfma_f32_16x16x32_bf16 v[66:69], v[152:155], v[200:203], v[66:69]
	v_mfma_f32_16x16x32_bf16 v[66:69], v[156:159], v[204:207], v[66:69]
	v_mfma_f32_16x16x32_bf16 v[78:81], v[144:147], v[200:203], v[78:81]
	v_mfma_f32_16x16x32_bf16 v[78:81], v[148:151], v[204:207], v[78:81]
	s_setprio 0
	s_barrier
	s_mov_b32 m0, s45
	s_mov_b32 s14, s18
	s_mov_b32 s15, s19
	ds_read_b128 v[176:179], v140 offset:16384
	ds_read_b128 v[180:183], v140 offset:17408
	ds_read_b128 v[184:187], v140 offset:18432
	ds_read_b128 v[188:191], v140 offset:19456
	ds_read_b128 v[192:195], v140 offset:20480
	ds_read_b128 v[196:199], v140 offset:21504
	ds_read_b128 v[200:203], v140 offset:22528
	ds_read_b128 v[204:207], v140 offset:23552
	buffer_load_dwordx4 v137, s[12:15], s79 offen lds
	s_add_i32 s80, s79, 0x80000
	s_mov_b32 m0, s46
	s_nop 0
	buffer_load_dwordx4 v137, s[12:15], s80 offen lds
	s_add_i32 s80, s79, 0x100000
	s_mov_b32 m0, s47
	s_nop 0
	buffer_load_dwordx4 v137, s[12:15], s80 offen lds
	s_add_i32 s80, s79, 0x180000
	s_mov_b32 m0, s48
	s_nop 0
	buffer_load_dwordx4 v137, s[12:15], s80 offen lds
	s_mov_b32 m0, s44
	s_add_i32 s80, s77, 0x80000
	buffer_load_dwordx4 v136, s[16:19], s77 offen lds
	s_mov_b32 m0, s49
	s_nop 0
	buffer_load_dwordx4 v136, s[16:19], s80 offen lds
	s_waitcnt vmcnt(8)
	s_waitcnt lgkmcnt(0)
	s_setprio 1
	s_barrier
	v_mfma_f32_16x16x32_bf16 v[62:65], v[144:147], v[176:179], v[62:65]
	v_mfma_f32_16x16x32_bf16 v[62:65], v[148:151], v[180:183], v[62:65]
	v_mfma_f32_16x16x32_bf16 v[54:57], v[152:155], v[176:179], v[54:57]
	v_mfma_f32_16x16x32_bf16 v[54:57], v[156:159], v[180:183], v[54:57]
	v_mfma_f32_16x16x32_bf16 v[58:61], v[160:163], v[176:179], v[58:61]
	v_mfma_f32_16x16x32_bf16 v[58:61], v[164:167], v[180:183], v[58:61]
	v_mfma_f32_16x16x32_bf16 v[50:53], v[168:171], v[176:179], v[50:53]
	v_mfma_f32_16x16x32_bf16 v[50:53], v[172:175], v[180:183], v[50:53]
	v_mfma_f32_16x16x32_bf16 v[34:37], v[168:171], v[184:187], v[34:37]
	v_mfma_f32_16x16x32_bf16 v[34:37], v[172:175], v[188:191], v[34:37]
	v_mfma_f32_16x16x32_bf16 v[42:45], v[160:163], v[184:187], v[42:45]
	v_mfma_f32_16x16x32_bf16 v[42:45], v[164:167], v[188:191], v[42:45]
	v_mfma_f32_16x16x32_bf16 v[38:41], v[152:155], v[184:187], v[38:41]
	v_mfma_f32_16x16x32_bf16 v[38:41], v[156:159], v[188:191], v[38:41]
	v_mfma_f32_16x16x32_bf16 v[46:49], v[144:147], v[184:187], v[46:49]
	v_mfma_f32_16x16x32_bf16 v[46:49], v[148:151], v[188:191], v[46:49]
	v_mfma_f32_16x16x32_bf16 v[30:33], v[144:147], v[192:195], v[30:33]
	v_mfma_f32_16x16x32_bf16 v[30:33], v[148:151], v[196:199], v[30:33]
	v_mfma_f32_16x16x32_bf16 v[22:25], v[152:155], v[192:195], v[22:25]
	v_mfma_f32_16x16x32_bf16 v[22:25], v[156:159], v[196:199], v[22:25]
	v_mfma_f32_16x16x32_bf16 v[26:29], v[160:163], v[192:195], v[26:29]
	v_mfma_f32_16x16x32_bf16 v[26:29], v[164:167], v[196:199], v[26:29]
	v_mfma_f32_16x16x32_bf16 v[18:21], v[168:171], v[192:195], v[18:21]
	v_mfma_f32_16x16x32_bf16 v[18:21], v[172:175], v[196:199], v[18:21]
	v_mfma_f32_16x16x32_bf16 v[2:5], v[168:171], v[200:203], v[2:5]
	v_mfma_f32_16x16x32_bf16 v[2:5], v[172:175], v[204:207], v[2:5]
	v_mfma_f32_16x16x32_bf16 v[10:13], v[160:163], v[200:203], v[10:13]
	v_mfma_f32_16x16x32_bf16 v[10:13], v[164:167], v[204:207], v[10:13]
	v_mfma_f32_16x16x32_bf16 v[6:9], v[152:155], v[200:203], v[6:9]
	v_mfma_f32_16x16x32_bf16 v[6:9], v[156:159], v[204:207], v[6:9]
	v_mfma_f32_16x16x32_bf16 v[14:17], v[144:147], v[200:203], v[14:17]
	v_mfma_f32_16x16x32_bf16 v[14:17], v[148:151], v[204:207], v[14:17]
	s_setprio 0
	s_barrier
	ds_read_b128 v[144:147], v141
	ds_read_b128 v[148:151], v141 offset:1024
	ds_read_b128 v[152:155], v141 offset:2048
	ds_read_b128 v[156:159], v141 offset:3072
	ds_read_b128 v[160:163], v142
	ds_read_b128 v[164:167], v142 offset:1024
	ds_read_b128 v[168:171], v142 offset:2048
	ds_read_b128 v[172:175], v142 offset:3072
	s_mov_b32 m0, s50
	s_add_i32 s80, s77, 0x100000
	ds_read_b128 v[176:179], v140 offset:32768
	ds_read_b128 v[180:183], v140 offset:33792
	ds_read_b128 v[184:187], v140 offset:34816
	ds_read_b128 v[188:191], v140 offset:35840
	ds_read_b128 v[192:195], v140 offset:36864
	ds_read_b128 v[196:199], v140 offset:37888
	ds_read_b128 v[200:203], v140 offset:38912
	ds_read_b128 v[204:207], v140 offset:39936
	buffer_load_dwordx4 v136, s[16:19], s80 offen lds
	s_add_i32 s80, s77, 0x180000
	s_mov_b32 m0, s51
	s_nop 0
	buffer_load_dwordx4 v136, s[16:19], s80 offen lds
	s_waitcnt vmcnt(8)
	s_waitcnt lgkmcnt(0)
	s_setprio 1
	s_barrier
	v_mfma_f32_16x16x32_bf16 v[118:121], v[144:147], v[176:179], v[118:121]
	v_mfma_f32_16x16x32_bf16 v[118:121], v[148:151], v[180:183], v[118:121]
	v_mfma_f32_16x16x32_bf16 v[114:117], v[152:155], v[176:179], v[114:117]
	v_mfma_f32_16x16x32_bf16 v[114:117], v[156:159], v[180:183], v[114:117]
	v_mfma_f32_16x16x32_bf16 v[126:129], v[160:163], v[176:179], v[126:129]
	v_mfma_f32_16x16x32_bf16 v[126:129], v[164:167], v[180:183], v[126:129]
	v_mfma_f32_16x16x32_bf16 v[122:125], v[168:171], v[176:179], v[122:125]
	v_mfma_f32_16x16x32_bf16 v[122:125], v[172:175], v[180:183], v[122:125]
	v_mfma_f32_16x16x32_bf16 v[98:101], v[168:171], v[184:187], v[98:101]
	v_mfma_f32_16x16x32_bf16 v[98:101], v[172:175], v[188:191], v[98:101]
	v_mfma_f32_16x16x32_bf16 v[106:109], v[160:163], v[184:187], v[106:109]
	v_mfma_f32_16x16x32_bf16 v[106:109], v[164:167], v[188:191], v[106:109]
	v_mfma_f32_16x16x32_bf16 v[102:105], v[152:155], v[184:187], v[102:105]
	v_mfma_f32_16x16x32_bf16 v[102:105], v[156:159], v[188:191], v[102:105]
	v_mfma_f32_16x16x32_bf16 v[110:113], v[144:147], v[184:187], v[110:113]
	v_mfma_f32_16x16x32_bf16 v[110:113], v[148:151], v[188:191], v[110:113]
	v_mfma_f32_16x16x32_bf16 v[94:97], v[144:147], v[192:195], v[94:97]
	v_mfma_f32_16x16x32_bf16 v[94:97], v[148:151], v[196:199], v[94:97]
	v_mfma_f32_16x16x32_bf16 v[86:89], v[152:155], v[192:195], v[86:89]
	v_mfma_f32_16x16x32_bf16 v[86:89], v[156:159], v[196:199], v[86:89]
	v_mfma_f32_16x16x32_bf16 v[90:93], v[160:163], v[192:195], v[90:93]
	v_mfma_f32_16x16x32_bf16 v[90:93], v[164:167], v[196:199], v[90:93]
	v_mfma_f32_16x16x32_bf16 v[82:85], v[168:171], v[192:195], v[82:85]
	v_mfma_f32_16x16x32_bf16 v[82:85], v[172:175], v[196:199], v[82:85]
	v_mfma_f32_16x16x32_bf16 v[70:73], v[168:171], v[200:203], v[70:73]
	v_mfma_f32_16x16x32_bf16 v[70:73], v[172:175], v[204:207], v[70:73]
	v_mfma_f32_16x16x32_bf16 v[74:77], v[160:163], v[200:203], v[74:77]
	v_mfma_f32_16x16x32_bf16 v[74:77], v[164:167], v[204:207], v[74:77]
	v_mfma_f32_16x16x32_bf16 v[66:69], v[152:155], v[200:203], v[66:69]
	v_mfma_f32_16x16x32_bf16 v[66:69], v[156:159], v[204:207], v[66:69]
	v_mfma_f32_16x16x32_bf16 v[78:81], v[144:147], v[200:203], v[78:81]
	v_mfma_f32_16x16x32_bf16 v[78:81], v[148:151], v[204:207], v[78:81]
	s_setprio 0
	s_barrier
	s_mov_b32 m0, s53
	s_or_b32 s80, s79, 0x80
	ds_read_b128 v[176:179], v140 offset:49152
	ds_read_b128 v[180:183], v140 offset:50176
	ds_read_b128 v[184:187], v140 offset:51200
	ds_read_b128 v[188:191], v140 offset:52224
	ds_read_b128 v[192:195], v140 offset:53248
	ds_read_b128 v[196:199], v140 offset:54272
	ds_read_b128 v[200:203], v140 offset:55296
	ds_read_b128 v[204:207], v140 offset:56320
	buffer_load_dwordx4 v137, s[12:15], s80 offen lds
	s_add_i32 s80, s79, 0x80080
	s_mov_b32 m0, s54
	s_add_i32 s77, s77, 0x80080
	buffer_load_dwordx4 v137, s[12:15], s80 offen lds
	s_add_i32 s80, s79, 0x100080
	s_mov_b32 m0, s57
	s_add_i32 s79, s79, 0x180080
	buffer_load_dwordx4 v137, s[12:15], s80 offen lds
	s_mov_b32 m0, s58
	s_nop 0
	buffer_load_dwordx4 v137, s[12:15], s79 offen lds
	s_mov_b32 m0, s55
	s_nop 0
	buffer_load_dwordx4 v136, s[16:19], s78 offen lds
	s_mov_b32 m0, s56
	s_nop 0
	buffer_load_dwordx4 v136, s[16:19], s77 offen lds
	s_waitcnt vmcnt(8)
	s_waitcnt lgkmcnt(0)
	s_setprio 1
	s_barrier
	v_mfma_f32_16x16x32_bf16 v[62:65], v[144:147], v[176:179], v[62:65]
	v_mfma_f32_16x16x32_bf16 v[62:65], v[148:151], v[180:183], v[62:65]
	v_mfma_f32_16x16x32_bf16 v[54:57], v[152:155], v[176:179], v[54:57]
	v_mfma_f32_16x16x32_bf16 v[54:57], v[156:159], v[180:183], v[54:57]
	v_mfma_f32_16x16x32_bf16 v[58:61], v[160:163], v[176:179], v[58:61]
	v_mfma_f32_16x16x32_bf16 v[58:61], v[164:167], v[180:183], v[58:61]
	v_mfma_f32_16x16x32_bf16 v[50:53], v[168:171], v[176:179], v[50:53]
	v_mfma_f32_16x16x32_bf16 v[50:53], v[172:175], v[180:183], v[50:53]
	v_mfma_f32_16x16x32_bf16 v[34:37], v[168:171], v[184:187], v[34:37]
	v_mfma_f32_16x16x32_bf16 v[34:37], v[172:175], v[188:191], v[34:37]
	v_mfma_f32_16x16x32_bf16 v[42:45], v[160:163], v[184:187], v[42:45]
	v_mfma_f32_16x16x32_bf16 v[42:45], v[164:167], v[188:191], v[42:45]
	v_mfma_f32_16x16x32_bf16 v[38:41], v[152:155], v[184:187], v[38:41]
	v_mfma_f32_16x16x32_bf16 v[38:41], v[156:159], v[188:191], v[38:41]
	v_mfma_f32_16x16x32_bf16 v[46:49], v[144:147], v[184:187], v[46:49]
	v_mfma_f32_16x16x32_bf16 v[46:49], v[148:151], v[188:191], v[46:49]
	v_mfma_f32_16x16x32_bf16 v[30:33], v[144:147], v[192:195], v[30:33]
	v_mfma_f32_16x16x32_bf16 v[30:33], v[148:151], v[196:199], v[30:33]
	v_mfma_f32_16x16x32_bf16 v[22:25], v[152:155], v[192:195], v[22:25]
	v_mfma_f32_16x16x32_bf16 v[22:25], v[156:159], v[196:199], v[22:25]
	v_mfma_f32_16x16x32_bf16 v[26:29], v[160:163], v[192:195], v[26:29]
	v_mfma_f32_16x16x32_bf16 v[26:29], v[164:167], v[196:199], v[26:29]
	v_mfma_f32_16x16x32_bf16 v[18:21], v[168:171], v[192:195], v[18:21]
	v_mfma_f32_16x16x32_bf16 v[18:21], v[172:175], v[196:199], v[18:21]
	v_mfma_f32_16x16x32_bf16 v[2:5], v[168:171], v[200:203], v[2:5]
	v_mfma_f32_16x16x32_bf16 v[2:5], v[172:175], v[204:207], v[2:5]
	v_mfma_f32_16x16x32_bf16 v[10:13], v[160:163], v[200:203], v[10:13]
	v_mfma_f32_16x16x32_bf16 v[10:13], v[164:167], v[204:207], v[10:13]
	v_mfma_f32_16x16x32_bf16 v[6:9], v[152:155], v[200:203], v[6:9]
	v_mfma_f32_16x16x32_bf16 v[6:9], v[156:159], v[204:207], v[6:9]
	v_mfma_f32_16x16x32_bf16 v[14:17], v[144:147], v[200:203], v[14:17]
	v_mfma_f32_16x16x32_bf16 v[14:17], v[148:151], v[204:207], v[14:17]
	s_setprio 0
	s_barrier
	s_add_i32 s76, s76, 2
	s_addk_i32 s74, 0x100
	s_addk_i32 s75, 0x100
	s_cmp_ge_i32 s76, s27
	s_cbranch_scc0 .LBB0_1382
	s_and_b64 vcc, exec, s[42:43]
	s_cbranch_vccz .LBB0_1385

.LBB0_1402:
	ds_read_b128 v[146:149], v138
	ds_read_b128 v[150:153], v138 offset:1024
	ds_read_b128 v[154:157], v138 offset:2048
	ds_read_b128 v[158:161], v138 offset:3072
	ds_read_b128 v[162:165], v139
	ds_read_b128 v[166:169], v139 offset:1024
	ds_read_b128 v[170:173], v139 offset:2048
	ds_read_b128 v[174:177], v139 offset:3072
	s_add_i32 s22, s75, 0xffe80080
	s_cmp_eq_u32 s62, s77
	s_cselect_b32 s78, s73, s22
	s_cselect_b32 s80, s74, s76
	s_or_b32 s79, s78, 0x80
	s_add_i32 s22, s75, 0xfff80000
	s_mov_b32 m0, s63
	ds_read_b128 v[178:181], v140
	ds_read_b128 v[182:185], v140 offset:1024
	ds_read_b128 v[186:189], v140 offset:2048
	ds_read_b128 v[190:193], v140 offset:3072
	ds_read_b128 v[194:197], v140 offset:4096
	ds_read_b128 v[198:201], v140 offset:5120
	ds_read_b128 v[202:205], v140 offset:6144
	ds_read_b128 v[206:209], v140 offset:7168
	buffer_load_dwordx4 v136, s[16:19], s22 offen lds
	s_mov_b32 m0, s64
	s_nop 0
	buffer_load_dwordx4 v136, s[16:19], s75 offen lds
	s_waitcnt vmcnt(8)
	s_waitcnt lgkmcnt(0)
	s_setprio 1
	s_barrier
	v_mfma_f32_16x16x32_bf16 v[118:121], v[146:149], v[178:181], v[118:121]
	v_mfma_f32_16x16x32_bf16 v[118:121], v[150:153], v[182:185], v[118:121]
	v_mfma_f32_16x16x32_bf16 v[114:117], v[154:157], v[178:181], v[114:117]
	v_mfma_f32_16x16x32_bf16 v[114:117], v[158:161], v[182:185], v[114:117]
	v_mfma_f32_16x16x32_bf16 v[126:129], v[162:165], v[178:181], v[126:129]
	v_mfma_f32_16x16x32_bf16 v[126:129], v[166:169], v[182:185], v[126:129]
	v_mfma_f32_16x16x32_bf16 v[122:125], v[170:173], v[178:181], v[122:125]
	v_mfma_f32_16x16x32_bf16 v[122:125], v[174:177], v[182:185], v[122:125]
	v_mfma_f32_16x16x32_bf16 v[98:101], v[170:173], v[186:189], v[98:101]
	v_mfma_f32_16x16x32_bf16 v[98:101], v[174:177], v[190:193], v[98:101]
	v_mfma_f32_16x16x32_bf16 v[106:109], v[162:165], v[186:189], v[106:109]
	v_mfma_f32_16x16x32_bf16 v[106:109], v[166:169], v[190:193], v[106:109]
	v_mfma_f32_16x16x32_bf16 v[102:105], v[154:157], v[186:189], v[102:105]
	v_mfma_f32_16x16x32_bf16 v[102:105], v[158:161], v[190:193], v[102:105]
	v_mfma_f32_16x16x32_bf16 v[110:113], v[146:149], v[186:189], v[110:113]
	v_mfma_f32_16x16x32_bf16 v[110:113], v[150:153], v[190:193], v[110:113]
	v_mfma_f32_16x16x32_bf16 v[94:97], v[146:149], v[194:197], v[94:97]
	v_mfma_f32_16x16x32_bf16 v[94:97], v[150:153], v[198:201], v[94:97]
	v_mfma_f32_16x16x32_bf16 v[86:89], v[154:157], v[194:197], v[86:89]
	v_mfma_f32_16x16x32_bf16 v[86:89], v[158:161], v[198:201], v[86:89]
	v_mfma_f32_16x16x32_bf16 v[90:93], v[162:165], v[194:197], v[90:93]
	v_mfma_f32_16x16x32_bf16 v[90:93], v[166:169], v[198:201], v[90:93]
	v_mfma_f32_16x16x32_bf16 v[82:85], v[170:173], v[194:197], v[82:85]
	v_mfma_f32_16x16x32_bf16 v[82:85], v[174:177], v[198:201], v[82:85]
	v_mfma_f32_16x16x32_bf16 v[70:73], v[170:173], v[202:205], v[70:73]
	v_mfma_f32_16x16x32_bf16 v[70:73], v[174:177], v[206:209], v[70:73]
	v_mfma_f32_16x16x32_bf16 v[74:77], v[162:165], v[202:205], v[74:77]
	v_mfma_f32_16x16x32_bf16 v[74:77], v[166:169], v[206:209], v[74:77]
	v_mfma_f32_16x16x32_bf16 v[66:69], v[154:157], v[202:205], v[66:69]
	v_mfma_f32_16x16x32_bf16 v[66:69], v[158:161], v[206:209], v[66:69]
	v_mfma_f32_16x16x32_bf16 v[78:81], v[146:149], v[202:205], v[78:81]
	v_mfma_f32_16x16x32_bf16 v[78:81], v[150:153], v[206:209], v[78:81]
	s_setprio 0
	s_barrier
	s_mov_b32 m0, s31
	s_mov_b32 s22, s18
	s_mov_b32 s23, s19
	ds_read_b128 v[178:181], v140 offset:16384
	ds_read_b128 v[182:185], v140 offset:17408
	ds_read_b128 v[186:189], v140 offset:18432
	ds_read_b128 v[190:193], v140 offset:19456
	ds_read_b128 v[194:197], v140 offset:20480
	ds_read_b128 v[198:201], v140 offset:21504
	ds_read_b128 v[202:205], v140 offset:22528
	ds_read_b128 v[206:209], v140 offset:23552
	buffer_load_dwordx4 v137, s[20:23], s80 offen lds
	s_add_i32 s81, s80, 0x80000
	s_mov_b32 m0, s48
	s_nop 0
	buffer_load_dwordx4 v137, s[20:23], s81 offen lds
	s_add_i32 s81, s80, 0x100000
	s_mov_b32 m0, s49
	s_nop 0
	buffer_load_dwordx4 v137, s[20:23], s81 offen lds
	s_add_i32 s81, s80, 0x180000
	s_mov_b32 m0, s50
	s_nop 0
	buffer_load_dwordx4 v137, s[20:23], s81 offen lds
	s_mov_b32 m0, s30
	s_add_i32 s81, s78, 0x80000
	buffer_load_dwordx4 v136, s[16:19], s78 offen lds
	s_mov_b32 m0, s51
	s_nop 0
	buffer_load_dwordx4 v136, s[16:19], s81 offen lds
	s_waitcnt vmcnt(8)
	s_waitcnt lgkmcnt(0)
	s_setprio 1
	s_barrier
	v_mfma_f32_16x16x32_bf16 v[62:65], v[146:149], v[178:181], v[62:65]
	v_mfma_f32_16x16x32_bf16 v[62:65], v[150:153], v[182:185], v[62:65]
	v_mfma_f32_16x16x32_bf16 v[54:57], v[154:157], v[178:181], v[54:57]
	v_mfma_f32_16x16x32_bf16 v[54:57], v[158:161], v[182:185], v[54:57]
	v_mfma_f32_16x16x32_bf16 v[58:61], v[162:165], v[178:181], v[58:61]
	v_mfma_f32_16x16x32_bf16 v[58:61], v[166:169], v[182:185], v[58:61]
	v_mfma_f32_16x16x32_bf16 v[50:53], v[170:173], v[178:181], v[50:53]
	v_mfma_f32_16x16x32_bf16 v[50:53], v[174:177], v[182:185], v[50:53]
	v_mfma_f32_16x16x32_bf16 v[34:37], v[170:173], v[186:189], v[34:37]
	v_mfma_f32_16x16x32_bf16 v[34:37], v[174:177], v[190:193], v[34:37]
	v_mfma_f32_16x16x32_bf16 v[42:45], v[162:165], v[186:189], v[42:45]
	v_mfma_f32_16x16x32_bf16 v[42:45], v[166:169], v[190:193], v[42:45]
	v_mfma_f32_16x16x32_bf16 v[38:41], v[154:157], v[186:189], v[38:41]
	v_mfma_f32_16x16x32_bf16 v[38:41], v[158:161], v[190:193], v[38:41]
	v_mfma_f32_16x16x32_bf16 v[46:49], v[146:149], v[186:189], v[46:49]
	v_mfma_f32_16x16x32_bf16 v[46:49], v[150:153], v[190:193], v[46:49]
	v_mfma_f32_16x16x32_bf16 v[30:33], v[146:149], v[194:197], v[30:33]
	v_mfma_f32_16x16x32_bf16 v[30:33], v[150:153], v[198:201], v[30:33]
	v_mfma_f32_16x16x32_bf16 v[22:25], v[154:157], v[194:197], v[22:25]
	v_mfma_f32_16x16x32_bf16 v[22:25], v[158:161], v[198:201], v[22:25]
	v_mfma_f32_16x16x32_bf16 v[26:29], v[162:165], v[194:197], v[26:29]
	v_mfma_f32_16x16x32_bf16 v[26:29], v[166:169], v[198:201], v[26:29]
	v_mfma_f32_16x16x32_bf16 v[18:21], v[170:173], v[194:197], v[18:21]
	v_mfma_f32_16x16x32_bf16 v[18:21], v[174:177], v[198:201], v[18:21]
	v_mfma_f32_16x16x32_bf16 v[2:5], v[170:173], v[202:205], v[2:5]
	v_mfma_f32_16x16x32_bf16 v[2:5], v[174:177], v[206:209], v[2:5]
	v_mfma_f32_16x16x32_bf16 v[10:13], v[162:165], v[202:205], v[10:13]
	v_mfma_f32_16x16x32_bf16 v[10:13], v[166:169], v[206:209], v[10:13]
	v_mfma_f32_16x16x32_bf16 v[6:9], v[154:157], v[202:205], v[6:9]
	v_mfma_f32_16x16x32_bf16 v[6:9], v[158:161], v[206:209], v[6:9]
	v_mfma_f32_16x16x32_bf16 v[14:17], v[146:149], v[202:205], v[14:17]
	v_mfma_f32_16x16x32_bf16 v[14:17], v[150:153], v[206:209], v[14:17]
	s_setprio 0
	s_barrier
	ds_read_b128 v[146:149], v141
	ds_read_b128 v[150:153], v141 offset:1024
	ds_read_b128 v[154:157], v141 offset:2048
	ds_read_b128 v[158:161], v141 offset:3072
	ds_read_b128 v[162:165], v142
	ds_read_b128 v[166:169], v142 offset:1024
	ds_read_b128 v[170:173], v142 offset:2048
	ds_read_b128 v[174:177], v142 offset:3072
	s_mov_b32 m0, s52
	s_add_i32 s81, s78, 0x100000
	ds_read_b128 v[178:181], v140 offset:32768
	ds_read_b128 v[182:185], v140 offset:33792
	ds_read_b128 v[186:189], v140 offset:34816
	ds_read_b128 v[190:193], v140 offset:35840
	ds_read_b128 v[194:197], v140 offset:36864
	ds_read_b128 v[198:201], v140 offset:37888
	ds_read_b128 v[202:205], v140 offset:38912
	ds_read_b128 v[206:209], v140 offset:39936
	buffer_load_dwordx4 v136, s[16:19], s81 offen lds
	s_add_i32 s81, s78, 0x180000
	s_mov_b32 m0, s53
	s_nop 0
	buffer_load_dwordx4 v136, s[16:19], s81 offen lds
	s_waitcnt vmcnt(8)
	s_waitcnt lgkmcnt(0)
	s_setprio 1
	s_barrier
	v_mfma_f32_16x16x32_bf16 v[118:121], v[146:149], v[178:181], v[118:121]
	v_mfma_f32_16x16x32_bf16 v[118:121], v[150:153], v[182:185], v[118:121]
	v_mfma_f32_16x16x32_bf16 v[114:117], v[154:157], v[178:181], v[114:117]
	v_mfma_f32_16x16x32_bf16 v[114:117], v[158:161], v[182:185], v[114:117]
	v_mfma_f32_16x16x32_bf16 v[126:129], v[162:165], v[178:181], v[126:129]
	v_mfma_f32_16x16x32_bf16 v[126:129], v[166:169], v[182:185], v[126:129]
	v_mfma_f32_16x16x32_bf16 v[122:125], v[170:173], v[178:181], v[122:125]
	v_mfma_f32_16x16x32_bf16 v[122:125], v[174:177], v[182:185], v[122:125]
	v_mfma_f32_16x16x32_bf16 v[98:101], v[170:173], v[186:189], v[98:101]
	v_mfma_f32_16x16x32_bf16 v[98:101], v[174:177], v[190:193], v[98:101]
	v_mfma_f32_16x16x32_bf16 v[106:109], v[162:165], v[186:189], v[106:109]
	v_mfma_f32_16x16x32_bf16 v[106:109], v[166:169], v[190:193], v[106:109]
	v_mfma_f32_16x16x32_bf16 v[102:105], v[154:157], v[186:189], v[102:105]
	v_mfma_f32_16x16x32_bf16 v[102:105], v[158:161], v[190:193], v[102:105]
	v_mfma_f32_16x16x32_bf16 v[110:113], v[146:149], v[186:189], v[110:113]
	v_mfma_f32_16x16x32_bf16 v[110:113], v[150:153], v[190:193], v[110:113]
	v_mfma_f32_16x16x32_bf16 v[94:97], v[146:149], v[194:197], v[94:97]
	v_mfma_f32_16x16x32_bf16 v[94:97], v[150:153], v[198:201], v[94:97]
	v_mfma_f32_16x16x32_bf16 v[86:89], v[154:157], v[194:197], v[86:89]
	v_mfma_f32_16x16x32_bf16 v[86:89], v[158:161], v[198:201], v[86:89]
	v_mfma_f32_16x16x32_bf16 v[90:93], v[162:165], v[194:197], v[90:93]
	v_mfma_f32_16x16x32_bf16 v[90:93], v[166:169], v[198:201], v[90:93]
	v_mfma_f32_16x16x32_bf16 v[82:85], v[170:173], v[194:197], v[82:85]
	v_mfma_f32_16x16x32_bf16 v[82:85], v[174:177], v[198:201], v[82:85]
	v_mfma_f32_16x16x32_bf16 v[70:73], v[170:173], v[202:205], v[70:73]
	v_mfma_f32_16x16x32_bf16 v[70:73], v[174:177], v[206:209], v[70:73]
	v_mfma_f32_16x16x32_bf16 v[74:77], v[162:165], v[202:205], v[74:77]
	v_mfma_f32_16x16x32_bf16 v[74:77], v[166:169], v[206:209], v[74:77]
	v_mfma_f32_16x16x32_bf16 v[66:69], v[154:157], v[202:205], v[66:69]
	v_mfma_f32_16x16x32_bf16 v[66:69], v[158:161], v[206:209], v[66:69]
	v_mfma_f32_16x16x32_bf16 v[78:81], v[146:149], v[202:205], v[78:81]
	v_mfma_f32_16x16x32_bf16 v[78:81], v[150:153], v[206:209], v[78:81]
	s_setprio 0
	s_barrier
	s_mov_b32 m0, s54
	s_or_b32 s81, s80, 0x80
	ds_read_b128 v[178:181], v140 offset:49152
	ds_read_b128 v[182:185], v140 offset:50176
	ds_read_b128 v[186:189], v140 offset:51200
	ds_read_b128 v[190:193], v140 offset:52224
	ds_read_b128 v[194:197], v140 offset:53248
	ds_read_b128 v[198:201], v140 offset:54272
	ds_read_b128 v[202:205], v140 offset:55296
	ds_read_b128 v[206:209], v140 offset:56320
	buffer_load_dwordx4 v137, s[20:23], s81 offen lds
	s_add_i32 s81, s80, 0x80080
	s_mov_b32 m0, s55
	s_add_i32 s78, s78, 0x80080
	buffer_load_dwordx4 v137, s[20:23], s81 offen lds
	s_add_i32 s81, s80, 0x100080
	s_mov_b32 m0, s58
	s_add_i32 s80, s80, 0x180080
	buffer_load_dwordx4 v137, s[20:23], s81 offen lds
	s_mov_b32 m0, s59
	s_nop 0
	buffer_load_dwordx4 v137, s[20:23], s80 offen lds
	s_mov_b32 m0, s56
	s_nop 0
	buffer_load_dwordx4 v136, s[16:19], s79 offen lds
	s_mov_b32 m0, s57
	s_nop 0
	buffer_load_dwordx4 v136, s[16:19], s78 offen lds
	s_waitcnt vmcnt(8)
	s_waitcnt lgkmcnt(0)
	s_setprio 1
	s_barrier
	v_mfma_f32_16x16x32_bf16 v[62:65], v[146:149], v[178:181], v[62:65]
	v_mfma_f32_16x16x32_bf16 v[62:65], v[150:153], v[182:185], v[62:65]
	v_mfma_f32_16x16x32_bf16 v[54:57], v[154:157], v[178:181], v[54:57]
	v_mfma_f32_16x16x32_bf16 v[54:57], v[158:161], v[182:185], v[54:57]
	v_mfma_f32_16x16x32_bf16 v[58:61], v[162:165], v[178:181], v[58:61]
	v_mfma_f32_16x16x32_bf16 v[58:61], v[166:169], v[182:185], v[58:61]
	v_mfma_f32_16x16x32_bf16 v[50:53], v[170:173], v[178:181], v[50:53]
	v_mfma_f32_16x16x32_bf16 v[50:53], v[174:177], v[182:185], v[50:53]
	v_mfma_f32_16x16x32_bf16 v[34:37], v[170:173], v[186:189], v[34:37]
	v_mfma_f32_16x16x32_bf16 v[34:37], v[174:177], v[190:193], v[34:37]
	v_mfma_f32_16x16x32_bf16 v[42:45], v[162:165], v[186:189], v[42:45]
	v_mfma_f32_16x16x32_bf16 v[42:45], v[166:169], v[190:193], v[42:45]
	v_mfma_f32_16x16x32_bf16 v[38:41], v[154:157], v[186:189], v[38:41]
	v_mfma_f32_16x16x32_bf16 v[38:41], v[158:161], v[190:193], v[38:41]
	v_mfma_f32_16x16x32_bf16 v[46:49], v[146:149], v[186:189], v[46:49]
	v_mfma_f32_16x16x32_bf16 v[46:49], v[150:153], v[190:193], v[46:49]
	v_mfma_f32_16x16x32_bf16 v[30:33], v[146:149], v[194:197], v[30:33]
	v_mfma_f32_16x16x32_bf16 v[30:33], v[150:153], v[198:201], v[30:33]
	v_mfma_f32_16x16x32_bf16 v[22:25], v[154:157], v[194:197], v[22:25]
	v_mfma_f32_16x16x32_bf16 v[22:25], v[158:161], v[198:201], v[22:25]
	v_mfma_f32_16x16x32_bf16 v[26:29], v[162:165], v[194:197], v[26:29]
	v_mfma_f32_16x16x32_bf16 v[26:29], v[166:169], v[198:201], v[26:29]
	v_mfma_f32_16x16x32_bf16 v[18:21], v[170:173], v[194:197], v[18:21]
	v_mfma_f32_16x16x32_bf16 v[18:21], v[174:177], v[198:201], v[18:21]
	v_mfma_f32_16x16x32_bf16 v[2:5], v[170:173], v[202:205], v[2:5]
	v_mfma_f32_16x16x32_bf16 v[2:5], v[174:177], v[206:209], v[2:5]
	v_mfma_f32_16x16x32_bf16 v[10:13], v[162:165], v[202:205], v[10:13]
	v_mfma_f32_16x16x32_bf16 v[10:13], v[166:169], v[206:209], v[10:13]
	v_mfma_f32_16x16x32_bf16 v[6:9], v[154:157], v[202:205], v[6:9]
	v_mfma_f32_16x16x32_bf16 v[6:9], v[158:161], v[206:209], v[6:9]
	v_mfma_f32_16x16x32_bf16 v[14:17], v[146:149], v[202:205], v[14:17]
	v_mfma_f32_16x16x32_bf16 v[14:17], v[150:153], v[206:209], v[14:17]
	s_setprio 0
	s_barrier
	s_add_i32 s77, s77, 2
	s_addk_i32 s75, 0x100
	s_addk_i32 s76, 0x100
	s_cmp_ge_i32 s77, s13
	s_cbranch_scc0 .LBB0_1402
	s_and_b64 vcc, exec, s[46:47]
	s_cbranch_vccz .LBB0_1405

.LBB0_1519:
	ds_read_b128 v[134:137], v208
	ds_read_b128 v[138:141], v208 offset:1024
	ds_read_b128 v[142:145], v208 offset:2048
	ds_read_b128 v[146:149], v208 offset:3072
	ds_read_b128 v[150:153], v209
	ds_read_b128 v[154:157], v209 offset:1024
	ds_read_b128 v[158:161], v209 offset:2048
	ds_read_b128 v[162:165], v209 offset:3072
	s_add_i32 s18, s80, 0xffbf8080
	s_cmp_eq_u32 s65, s82
	s_cselect_b32 s83, s6, s18
	s_cselect_b32 s85, s7, s81
	s_or_b32 s84, s83, 0x80
	s_add_i32 s18, s80, 0xffea8000
	s_mov_b32 m0, s66
	ds_read_b128 v[166:169], v210
	ds_read_b128 v[170:173], v210 offset:1024
	ds_read_b128 v[174:177], v210 offset:2048
	ds_read_b128 v[178:181], v210 offset:3072
	ds_read_b128 v[182:185], v210 offset:4096
	ds_read_b128 v[186:189], v210 offset:5120
	ds_read_b128 v[190:193], v210 offset:6144
	ds_read_b128 v[194:197], v210 offset:7168
	buffer_load_dwordx4 v206, s[12:15], s18 offen lds
	s_mov_b32 m0, s69
	s_nop 0
	buffer_load_dwordx4 v206, s[12:15], s80 offen lds
	s_waitcnt vmcnt(8)
	s_waitcnt lgkmcnt(0)
	s_setprio 1
	s_barrier
	v_mfma_f32_16x16x32_bf16 v[126:129], v[134:137], v[166:169], v[126:129]
	v_mfma_f32_16x16x32_bf16 v[126:129], v[138:141], v[170:173], v[126:129]
	v_mfma_f32_16x16x32_bf16 v[122:125], v[142:145], v[166:169], v[122:125]
	v_mfma_f32_16x16x32_bf16 v[122:125], v[146:149], v[170:173], v[122:125]
	v_mfma_f32_16x16x32_bf16 v[110:113], v[150:153], v[166:169], v[110:113]
	v_mfma_f32_16x16x32_bf16 v[110:113], v[154:157], v[170:173], v[110:113]
	v_mfma_f32_16x16x32_bf16 v[102:105], v[158:161], v[166:169], v[102:105]
	v_mfma_f32_16x16x32_bf16 v[102:105], v[162:165], v[170:173], v[102:105]
	v_mfma_f32_16x16x32_bf16 v[86:89], v[158:161], v[174:177], v[86:89]
	v_mfma_f32_16x16x32_bf16 v[86:89], v[162:165], v[178:181], v[86:89]
	v_mfma_f32_16x16x32_bf16 v[94:97], v[150:153], v[174:177], v[94:97]
	v_mfma_f32_16x16x32_bf16 v[94:97], v[154:157], v[178:181], v[94:97]
	v_mfma_f32_16x16x32_bf16 v[114:117], v[142:145], v[174:177], v[114:117]
	v_mfma_f32_16x16x32_bf16 v[114:117], v[146:149], v[178:181], v[114:117]
	v_mfma_f32_16x16x32_bf16 v[118:121], v[134:137], v[174:177], v[118:121]
	v_mfma_f32_16x16x32_bf16 v[118:121], v[138:141], v[178:181], v[118:121]
	v_mfma_f32_16x16x32_bf16 v[106:109], v[134:137], v[182:185], v[106:109]
	v_mfma_f32_16x16x32_bf16 v[106:109], v[138:141], v[186:189], v[106:109]
	v_mfma_f32_16x16x32_bf16 v[98:101], v[142:145], v[182:185], v[98:101]
	v_mfma_f32_16x16x32_bf16 v[98:101], v[146:149], v[186:189], v[98:101]
	v_mfma_f32_16x16x32_bf16 v[78:81], v[150:153], v[182:185], v[78:81]
	v_mfma_f32_16x16x32_bf16 v[78:81], v[154:157], v[186:189], v[78:81]
	v_mfma_f32_16x16x32_bf16 v[74:77], v[158:161], v[182:185], v[74:77]
	v_mfma_f32_16x16x32_bf16 v[74:77], v[162:165], v[186:189], v[74:77]
	v_mfma_f32_16x16x32_bf16 v[66:69], v[158:161], v[190:193], v[66:69]
	v_mfma_f32_16x16x32_bf16 v[66:69], v[162:165], v[194:197], v[66:69]
	v_mfma_f32_16x16x32_bf16 v[70:73], v[150:153], v[190:193], v[70:73]
	v_mfma_f32_16x16x32_bf16 v[70:73], v[154:157], v[194:197], v[70:73]
	v_mfma_f32_16x16x32_bf16 v[82:85], v[142:145], v[190:193], v[82:85]
	v_mfma_f32_16x16x32_bf16 v[82:85], v[146:149], v[194:197], v[82:85]
	v_mfma_f32_16x16x32_bf16 v[90:93], v[134:137], v[190:193], v[90:93]
	v_mfma_f32_16x16x32_bf16 v[90:93], v[138:141], v[194:197], v[90:93]
	s_setprio 0
	s_barrier
	s_mov_b32 m0, s27
	s_mov_b32 s18, s14
	s_mov_b32 s19, s15
	ds_read_b128 v[166:169], v210 offset:16384
	ds_read_b128 v[170:173], v210 offset:17408
	ds_read_b128 v[174:177], v210 offset:18432
	ds_read_b128 v[178:181], v210 offset:19456
	ds_read_b128 v[182:185], v210 offset:20480
	ds_read_b128 v[186:189], v210 offset:21504
	ds_read_b128 v[190:193], v210 offset:22528
	ds_read_b128 v[194:197], v210 offset:23552
	buffer_load_dwordx4 v207, s[16:19], s85 offen lds
	s_add_i32 s86, s85, 0x158000
	s_mov_b32 m0, s30
	s_nop 0
	buffer_load_dwordx4 v207, s[16:19], s86 offen lds
	s_add_i32 s86, s85, 0x2b0000
	s_mov_b32 m0, s31
	s_nop 0
	buffer_load_dwordx4 v207, s[16:19], s86 offen lds
	s_add_i32 s86, s85, 0x408000
	s_mov_b32 m0, s50
	s_nop 0
	buffer_load_dwordx4 v207, s[16:19], s86 offen lds
	s_mov_b32 m0, s25
	s_add_i32 s86, s83, 0x158000
	buffer_load_dwordx4 v206, s[12:15], s83 offen lds
	s_mov_b32 m0, s51
	s_nop 0
	buffer_load_dwordx4 v206, s[12:15], s86 offen lds
	s_waitcnt vmcnt(8)
	s_waitcnt lgkmcnt(0)
	s_setprio 1
	s_barrier
	v_mfma_f32_16x16x32_bf16 v[62:65], v[134:137], v[166:169], v[62:65]
	v_mfma_f32_16x16x32_bf16 v[62:65], v[138:141], v[170:173], v[62:65]
	v_mfma_f32_16x16x32_bf16 v[58:61], v[142:145], v[166:169], v[58:61]
	v_mfma_f32_16x16x32_bf16 v[58:61], v[146:149], v[170:173], v[58:61]
	v_mfma_f32_16x16x32_bf16 v[46:49], v[150:153], v[166:169], v[46:49]
	v_mfma_f32_16x16x32_bf16 v[46:49], v[154:157], v[170:173], v[46:49]
	v_mfma_f32_16x16x32_bf16 v[38:41], v[158:161], v[166:169], v[38:41]
	v_mfma_f32_16x16x32_bf16 v[38:41], v[162:165], v[170:173], v[38:41]
	v_mfma_f32_16x16x32_bf16 v[22:25], v[158:161], v[174:177], v[22:25]
	v_mfma_f32_16x16x32_bf16 v[22:25], v[162:165], v[178:181], v[22:25]
	v_mfma_f32_16x16x32_bf16 v[30:33], v[150:153], v[174:177], v[30:33]
	v_mfma_f32_16x16x32_bf16 v[30:33], v[154:157], v[178:181], v[30:33]
	v_mfma_f32_16x16x32_bf16 v[50:53], v[142:145], v[174:177], v[50:53]
	v_mfma_f32_16x16x32_bf16 v[50:53], v[146:149], v[178:181], v[50:53]
	v_mfma_f32_16x16x32_bf16 v[54:57], v[134:137], v[174:177], v[54:57]
	v_mfma_f32_16x16x32_bf16 v[54:57], v[138:141], v[178:181], v[54:57]
	v_mfma_f32_16x16x32_bf16 v[42:45], v[134:137], v[182:185], v[42:45]
	v_mfma_f32_16x16x32_bf16 v[42:45], v[138:141], v[186:189], v[42:45]
	v_mfma_f32_16x16x32_bf16 v[34:37], v[142:145], v[182:185], v[34:37]
	v_mfma_f32_16x16x32_bf16 v[34:37], v[146:149], v[186:189], v[34:37]
	v_mfma_f32_16x16x32_bf16 v[14:17], v[150:153], v[182:185], v[14:17]
	v_mfma_f32_16x16x32_bf16 v[14:17], v[154:157], v[186:189], v[14:17]
	v_mfma_f32_16x16x32_bf16 v[10:13], v[158:161], v[182:185], v[10:13]
	v_mfma_f32_16x16x32_bf16 v[10:13], v[162:165], v[186:189], v[10:13]
	v_mfma_f32_16x16x32_bf16 v[2:5], v[158:161], v[190:193], v[2:5]
	v_mfma_f32_16x16x32_bf16 v[2:5], v[162:165], v[194:197], v[2:5]
	v_mfma_f32_16x16x32_bf16 v[6:9], v[150:153], v[190:193], v[6:9]
	v_mfma_f32_16x16x32_bf16 v[6:9], v[154:157], v[194:197], v[6:9]
	v_mfma_f32_16x16x32_bf16 v[18:21], v[142:145], v[190:193], v[18:21]
	v_mfma_f32_16x16x32_bf16 v[18:21], v[146:149], v[194:197], v[18:21]
	v_mfma_f32_16x16x32_bf16 v[26:29], v[134:137], v[190:193], v[26:29]
	v_mfma_f32_16x16x32_bf16 v[26:29], v[138:141], v[194:197], v[26:29]
	s_setprio 0
	s_barrier
	ds_read_b128 v[134:137], v211
	ds_read_b128 v[138:141], v211 offset:1024
	ds_read_b128 v[142:145], v211 offset:2048
	ds_read_b128 v[146:149], v211 offset:3072
	ds_read_b128 v[150:153], v212
	ds_read_b128 v[154:157], v212 offset:1024
	ds_read_b128 v[158:161], v212 offset:2048
	ds_read_b128 v[162:165], v212 offset:3072
	s_mov_b32 m0, s52
	s_add_i32 s86, s83, 0x2b0000
	ds_read_b128 v[166:169], v210 offset:32768
	ds_read_b128 v[170:173], v210 offset:33792
	ds_read_b128 v[174:177], v210 offset:34816
	ds_read_b128 v[178:181], v210 offset:35840
	ds_read_b128 v[182:185], v210 offset:36864
	ds_read_b128 v[186:189], v210 offset:37888
	ds_read_b128 v[190:193], v210 offset:38912
	ds_read_b128 v[194:197], v210 offset:39936
	buffer_load_dwordx4 v206, s[12:15], s86 offen lds
	s_add_i32 s86, s83, 0x408000
	s_mov_b32 m0, s53
	s_nop 0
	buffer_load_dwordx4 v206, s[12:15], s86 offen lds
	s_waitcnt vmcnt(8)
	s_waitcnt lgkmcnt(0)
	s_setprio 1
	s_barrier
	v_mfma_f32_16x16x32_bf16 v[126:129], v[134:137], v[166:169], v[126:129]
	v_mfma_f32_16x16x32_bf16 v[126:129], v[138:141], v[170:173], v[126:129]
	v_mfma_f32_16x16x32_bf16 v[122:125], v[142:145], v[166:169], v[122:125]
	v_mfma_f32_16x16x32_bf16 v[122:125], v[146:149], v[170:173], v[122:125]
	v_mfma_f32_16x16x32_bf16 v[110:113], v[150:153], v[166:169], v[110:113]
	v_mfma_f32_16x16x32_bf16 v[110:113], v[154:157], v[170:173], v[110:113]
	v_mfma_f32_16x16x32_bf16 v[102:105], v[158:161], v[166:169], v[102:105]
	v_mfma_f32_16x16x32_bf16 v[102:105], v[162:165], v[170:173], v[102:105]
	v_mfma_f32_16x16x32_bf16 v[86:89], v[158:161], v[174:177], v[86:89]
	v_mfma_f32_16x16x32_bf16 v[86:89], v[162:165], v[178:181], v[86:89]
	v_mfma_f32_16x16x32_bf16 v[94:97], v[150:153], v[174:177], v[94:97]
	v_mfma_f32_16x16x32_bf16 v[94:97], v[154:157], v[178:181], v[94:97]
	v_mfma_f32_16x16x32_bf16 v[114:117], v[142:145], v[174:177], v[114:117]
	v_mfma_f32_16x16x32_bf16 v[114:117], v[146:149], v[178:181], v[114:117]
	v_mfma_f32_16x16x32_bf16 v[118:121], v[134:137], v[174:177], v[118:121]
	v_mfma_f32_16x16x32_bf16 v[118:121], v[138:141], v[178:181], v[118:121]
	v_mfma_f32_16x16x32_bf16 v[106:109], v[134:137], v[182:185], v[106:109]
	v_mfma_f32_16x16x32_bf16 v[106:109], v[138:141], v[186:189], v[106:109]
	v_mfma_f32_16x16x32_bf16 v[98:101], v[142:145], v[182:185], v[98:101]
	v_mfma_f32_16x16x32_bf16 v[98:101], v[146:149], v[186:189], v[98:101]
	v_mfma_f32_16x16x32_bf16 v[78:81], v[150:153], v[182:185], v[78:81]
	v_mfma_f32_16x16x32_bf16 v[78:81], v[154:157], v[186:189], v[78:81]
	v_mfma_f32_16x16x32_bf16 v[74:77], v[158:161], v[182:185], v[74:77]
	v_mfma_f32_16x16x32_bf16 v[74:77], v[162:165], v[186:189], v[74:77]
	v_mfma_f32_16x16x32_bf16 v[66:69], v[158:161], v[190:193], v[66:69]
	v_mfma_f32_16x16x32_bf16 v[66:69], v[162:165], v[194:197], v[66:69]
	v_mfma_f32_16x16x32_bf16 v[70:73], v[150:153], v[190:193], v[70:73]
	v_mfma_f32_16x16x32_bf16 v[70:73], v[154:157], v[194:197], v[70:73]
	v_mfma_f32_16x16x32_bf16 v[82:85], v[142:145], v[190:193], v[82:85]
	v_mfma_f32_16x16x32_bf16 v[82:85], v[146:149], v[194:197], v[82:85]
	v_mfma_f32_16x16x32_bf16 v[90:93], v[134:137], v[190:193], v[90:93]
	v_mfma_f32_16x16x32_bf16 v[90:93], v[138:141], v[194:197], v[90:93]
	s_setprio 0
	s_barrier
	s_mov_b32 m0, s57
	s_or_b32 s86, s85, 0x80
	ds_read_b128 v[166:169], v210 offset:49152
	ds_read_b128 v[170:173], v210 offset:50176
	ds_read_b128 v[174:177], v210 offset:51200
	ds_read_b128 v[178:181], v210 offset:52224
	ds_read_b128 v[182:185], v210 offset:53248
	ds_read_b128 v[186:189], v210 offset:54272
	ds_read_b128 v[190:193], v210 offset:55296
	ds_read_b128 v[194:197], v210 offset:56320
	buffer_load_dwordx4 v207, s[16:19], s86 offen lds
	s_add_i32 s86, s85, 0x158080
	s_mov_b32 m0, s58
	s_add_i32 s83, s83, 0x158080
	buffer_load_dwordx4 v207, s[16:19], s86 offen lds
	s_add_i32 s86, s85, 0x2b0080
	s_mov_b32 m0, s61
	s_add_i32 s85, s85, 0x408080
	buffer_load_dwordx4 v207, s[16:19], s86 offen lds
	s_mov_b32 m0, s62
	s_nop 0
	buffer_load_dwordx4 v207, s[16:19], s85 offen lds
	s_mov_b32 m0, s59
	s_nop 0
	buffer_load_dwordx4 v206, s[12:15], s84 offen lds
	s_mov_b32 m0, s60
	s_nop 0
	buffer_load_dwordx4 v206, s[12:15], s83 offen lds
	s_waitcnt vmcnt(8)
	s_waitcnt lgkmcnt(0)
	s_setprio 1
	s_barrier
	v_mfma_f32_16x16x32_bf16 v[62:65], v[134:137], v[166:169], v[62:65]
	v_mfma_f32_16x16x32_bf16 v[62:65], v[138:141], v[170:173], v[62:65]
	v_mfma_f32_16x16x32_bf16 v[58:61], v[142:145], v[166:169], v[58:61]
	v_mfma_f32_16x16x32_bf16 v[58:61], v[146:149], v[170:173], v[58:61]
	v_mfma_f32_16x16x32_bf16 v[46:49], v[150:153], v[166:169], v[46:49]
	v_mfma_f32_16x16x32_bf16 v[46:49], v[154:157], v[170:173], v[46:49]
	v_mfma_f32_16x16x32_bf16 v[38:41], v[158:161], v[166:169], v[38:41]
	v_mfma_f32_16x16x32_bf16 v[38:41], v[162:165], v[170:173], v[38:41]
	v_mfma_f32_16x16x32_bf16 v[22:25], v[158:161], v[174:177], v[22:25]
	v_mfma_f32_16x16x32_bf16 v[22:25], v[162:165], v[178:181], v[22:25]
	v_mfma_f32_16x16x32_bf16 v[30:33], v[150:153], v[174:177], v[30:33]
	v_mfma_f32_16x16x32_bf16 v[30:33], v[154:157], v[178:181], v[30:33]
	v_mfma_f32_16x16x32_bf16 v[50:53], v[142:145], v[174:177], v[50:53]
	v_mfma_f32_16x16x32_bf16 v[50:53], v[146:149], v[178:181], v[50:53]
	v_mfma_f32_16x16x32_bf16 v[54:57], v[134:137], v[174:177], v[54:57]
	v_mfma_f32_16x16x32_bf16 v[54:57], v[138:141], v[178:181], v[54:57]
	v_mfma_f32_16x16x32_bf16 v[42:45], v[134:137], v[182:185], v[42:45]
	v_mfma_f32_16x16x32_bf16 v[42:45], v[138:141], v[186:189], v[42:45]
	v_mfma_f32_16x16x32_bf16 v[34:37], v[142:145], v[182:185], v[34:37]
	v_mfma_f32_16x16x32_bf16 v[34:37], v[146:149], v[186:189], v[34:37]
	v_mfma_f32_16x16x32_bf16 v[14:17], v[150:153], v[182:185], v[14:17]
	v_mfma_f32_16x16x32_bf16 v[14:17], v[154:157], v[186:189], v[14:17]
	v_mfma_f32_16x16x32_bf16 v[10:13], v[158:161], v[182:185], v[10:13]
	v_mfma_f32_16x16x32_bf16 v[10:13], v[162:165], v[186:189], v[10:13]
	v_mfma_f32_16x16x32_bf16 v[2:5], v[158:161], v[190:193], v[2:5]
	v_mfma_f32_16x16x32_bf16 v[2:5], v[162:165], v[194:197], v[2:5]
	v_mfma_f32_16x16x32_bf16 v[6:9], v[150:153], v[190:193], v[6:9]
	v_mfma_f32_16x16x32_bf16 v[6:9], v[154:157], v[194:197], v[6:9]
	v_mfma_f32_16x16x32_bf16 v[18:21], v[142:145], v[190:193], v[18:21]
	v_mfma_f32_16x16x32_bf16 v[18:21], v[146:149], v[194:197], v[18:21]
	v_mfma_f32_16x16x32_bf16 v[26:29], v[134:137], v[190:193], v[26:29]
	v_mfma_f32_16x16x32_bf16 v[26:29], v[138:141], v[194:197], v[26:29]
	s_setprio 0
	s_barrier
	s_add_i32 s82, s82, 2
	s_addk_i32 s80, 0x100
	s_addk_i32 s81, 0x100
	s_cmp_ge_i32 s82, s3
	s_cbranch_scc0 .LBB0_1519
	v_pk_mul_f32 v[182:183], v[128:129], 0.5 op_sel_hi:[1,0]
	v_pk_mul_f32 v[184:185], v[126:127], 0.5 op_sel_hi:[1,0]
	v_pk_mul_f32 v[186:187], v[124:125], 0.5 op_sel_hi:[1,0]
	v_pk_mul_f32 v[188:189], v[122:123], 0.5 op_sel_hi:[1,0]
	v_pk_mul_f32 v[196:197], v[112:113], 0.5 op_sel_hi:[1,0]
	v_pk_mul_f32 v[194:195], v[110:111], 0.5 op_sel_hi:[1,0]
	v_pk_mul_f32 v[192:193], v[104:105], 0.5 op_sel_hi:[1,0]
	v_pk_mul_f32 v[190:191], v[102:103], 0.5 op_sel_hi:[1,0]
	v_pk_mul_f32 v[180:181], v[120:121], 0.5 op_sel_hi:[1,0]
	v_pk_mul_f32 v[178:179], v[118:119], 0.5 op_sel_hi:[1,0]
	v_pk_mul_f32 v[176:177], v[116:117], 0.5 op_sel_hi:[1,0]
	v_pk_mul_f32 v[174:175], v[114:115], 0.5 op_sel_hi:[1,0]
	v_pk_mul_f32 v[170:171], v[96:97], 0.5 op_sel_hi:[1,0]
	v_pk_mul_f32 v[168:169], v[94:95], 0.5 op_sel_hi:[1,0]
	v_pk_mul_f32 v[166:167], v[88:89], 0.5 op_sel_hi:[1,0]
	v_pk_mul_f32 v[164:165], v[86:87], 0.5 op_sel_hi:[1,0]
	v_pk_mul_f32 v[162:163], v[108:109], 0.5 op_sel_hi:[1,0]
	v_pk_mul_f32 v[160:161], v[106:107], 0.5 op_sel_hi:[1,0]
	v_pk_mul_f32 v[158:159], v[100:101], 0.5 op_sel_hi:[1,0]
	v_pk_mul_f32 v[156:157], v[98:99], 0.5 op_sel_hi:[1,0]
	v_pk_mul_f32 v[154:155], v[80:81], 0.5 op_sel_hi:[1,0]
	v_pk_mul_f32 v[152:153], v[78:79], 0.5 op_sel_hi:[1,0]
	v_pk_mul_f32 v[150:151], v[76:77], 0.5 op_sel_hi:[1,0]
	v_pk_mul_f32 v[148:149], v[74:75], 0.5 op_sel_hi:[1,0]
	v_pk_mul_f32 v[144:145], v[92:93], 0.5 op_sel_hi:[1,0]
	v_pk_mul_f32 v[142:143], v[90:91], 0.5 op_sel_hi:[1,0]
	v_pk_mul_f32 v[140:141], v[84:85], 0.5 op_sel_hi:[1,0]
	v_pk_mul_f32 v[138:139], v[82:83], 0.5 op_sel_hi:[1,0]
	v_pk_mul_f32 v[136:137], v[72:73], 0.5 op_sel_hi:[1,0]
	v_pk_mul_f32 v[134:135], v[70:71], 0.5 op_sel_hi:[1,0]
	v_pk_mul_f32 v[128:129], v[68:69], 0.5 op_sel_hi:[1,0]
	v_pk_mul_f32 v[126:127], v[66:67], 0.5 op_sel_hi:[1,0]
	v_pk_mul_f32 v[122:123], v[64:65], 0.5 op_sel_hi:[1,0]
	v_pk_mul_f32 v[120:121], v[62:63], 0.5 op_sel_hi:[1,0]
	v_pk_mul_f32 v[118:119], v[60:61], 0.5 op_sel_hi:[1,0]
	v_pk_mul_f32 v[116:117], v[58:59], 0.5 op_sel_hi:[1,0]
	v_pk_mul_f32 v[112:113], v[48:49], 0.5 op_sel_hi:[1,0]
	v_pk_mul_f32 v[110:111], v[46:47], 0.5 op_sel_hi:[1,0]
	v_pk_mul_f32 v[108:109], v[40:41], 0.5 op_sel_hi:[1,0]
	v_pk_mul_f32 v[106:107], v[38:39], 0.5 op_sel_hi:[1,0]
	v_pk_mul_f32 v[104:105], v[56:57], 0.5 op_sel_hi:[1,0]
	v_pk_mul_f32 v[102:103], v[54:55], 0.5 op_sel_hi:[1,0]
	v_pk_mul_f32 v[100:101], v[52:53], 0.5 op_sel_hi:[1,0]
	v_pk_mul_f32 v[98:99], v[50:51], 0.5 op_sel_hi:[1,0]
	v_pk_mul_f32 v[96:97], v[32:33], 0.5 op_sel_hi:[1,0]
	v_pk_mul_f32 v[94:95], v[30:31], 0.5 op_sel_hi:[1,0]
	v_pk_mul_f32 v[92:93], v[24:25], 0.5 op_sel_hi:[1,0]
	v_pk_mul_f32 v[90:91], v[22:23], 0.5 op_sel_hi:[1,0]
	v_pk_mul_f32 v[88:89], v[44:45], 0.5 op_sel_hi:[1,0]
	v_pk_mul_f32 v[86:87], v[42:43], 0.5 op_sel_hi:[1,0]
	v_pk_mul_f32 v[84:85], v[36:37], 0.5 op_sel_hi:[1,0]
	v_pk_mul_f32 v[82:83], v[34:35], 0.5 op_sel_hi:[1,0]
	v_pk_mul_f32 v[80:81], v[16:17], 0.5 op_sel_hi:[1,0]
	v_pk_mul_f32 v[78:79], v[14:15], 0.5 op_sel_hi:[1,0]
	v_pk_mul_f32 v[76:77], v[12:13], 0.5 op_sel_hi:[1,0]
	v_pk_mul_f32 v[74:75], v[10:11], 0.5 op_sel_hi:[1,0]
	v_pk_mul_f32 v[72:73], v[28:29], 0.5 op_sel_hi:[1,0]
	v_pk_mul_f32 v[70:71], v[26:27], 0.5 op_sel_hi:[1,0]
	v_pk_mul_f32 v[68:69], v[20:21], 0.5 op_sel_hi:[1,0]
	v_pk_mul_f32 v[66:67], v[18:19], 0.5 op_sel_hi:[1,0]
	v_pk_mul_f32 v[64:65], v[8:9], 0.5 op_sel_hi:[1,0]
	v_pk_mul_f32 v[62:63], v[6:7], 0.5 op_sel_hi:[1,0]
	v_pk_mul_f32 v[60:61], v[4:5], 0.5 op_sel_hi:[1,0]
	v_pk_mul_f32 v[58:59], v[2:3], 0.5 op_sel_hi:[1,0]
	s_and_b64 vcc, exec, s[40:41]
	s_cbranch_vccz .LBB0_1522
